# GEMM K-loops: s_setprio flips moved across the adjacent barriers (prio 1 set before the pre-MFMA barrier, prio 0 after the closing one), the redundant mid-block 0/1 flip and the duplicate post-barrier
# speedup vs baseline: 1.0076x; 1.0076x over previous
; #define PG8_STAGE(bufoff, gbase, voff) do { _Pragma("unroll") for (int _i = 0; _i < 2; ++_i) \
;         __builtin_amdgcn_global_load_lds((const unsigned*)((const char*)(gbase) + (voff)[_i]), (PG8_LAS unsigned*)(lds + (bufoff) + ldsw + _i * 8192), 16, 0, 0); } while (0)
; #define PG8_LDA(dst, b, h) do { _Pragma("unroll") for (int m = 0; m < 4; ++m) _Pragma("unroll") for (int k = 0; k < 2; ++k) dst[m][k] = *(const PG8_LAS bf16x8*)(lds + PG8_SA(b, h) + aoff + m * 2048 + k * 1024); } while (0)
; #define PG8_LDB(dst, b, h) do { _Pragma("unroll") for (int n = 0; n < 2; ++n) _Pragma("unroll") for (int k = 0; k < 2; ++k) dst[n][k] = *(const PG8_LAS bf16x8*)(lds + PG8_SB(b, h) + boff + n * 2048 + k * 1024); } while (0)
; template <class Epi, class Sched, bool ALIGN_EPI = false, bool SP2 = false>
; __device__ __forceinline__ void gemm_phase(PG8_LAS unsigned char* lds, const Gemm g, const Sched& S, const Epi& E, int wv) {
;     ...
;         for (int t = 0; t < nt; t += 2) {
;             const bool last = (t == nt - 2);
;             const char* a1 = cA + (size_t)(t + 1) * kstep;
;             const char* a2 = last ? nA : cA + (size_t)(t + 2) * kstep; const char* b2 = last ? nB : cB + (size_t)(t + 2) * kstep;
;             const char* a3 = a2 + kstep; const char* b3 = b2 + kstep;
;             if (last && has_next) S.a_ready(nxt);
;             if constexpr (SP2) {
;             PG8_LDB(B0, 0, 0); PG8_LDB(B1, 0, 1); PG8_SCHED; PG8_LDA(At, 0, 0); PG8_STAGE(PG8_SA(1, 1), a1 + hstepA, voffA);
;             PG8_WAIT_V(8); PG8_WAIT_L(0); PG8_BAR; PG8_MMA(0, 0, At, B0); PG8_MMA(0, 1, At, B1); PG8_BAR; PG8_SCHED;
;             PG8_LDA(At, 0, 1); PG8_STAGE(PG8_SB(0, 0), b2, voffB); PG8_STAGE(PG8_SB(0, 1), b2 + hstep, voffB); PG8_STAGE(PG8_SA(0, 0), a2, voffA);
;             PG8_WAIT_V(8); PG8_WAIT_L(0); PG8_BAR; PG8_MMA(1, 0, At, B0); PG8_MMA(1, 1, At, B1); PG8_BAR; PG8_SCHED;
;             PG8_LDB(B0, 1, 0); PG8_LDB(B1, 1, 1); PG8_SCHED; PG8_LDA(At, 1, 0); PG8_STAGE(PG8_SA(0, 1), a2 + hstepA, voffA);
;             PG8_WAIT_V(8); PG8_WAIT_L(0); PG8_BAR; PG8_MMA(0, 0, At, B0); PG8_MMA(0, 1, At, B1); PG8_BAR; PG8_SCHED;
;             PG8_LDA(At, 1, 1); PG8_STAGE(PG8_SB(1, 0), b3, voffB); PG8_STAGE(PG8_SB(1, 1), b3 + hstep, voffB); PG8_STAGE(PG8_SA(1, 0), a3, voffA);
;             PG8_WAIT_V(8); PG8_WAIT_L(0); PG8_BAR; PG8_MMA(1, 0, At, B0); PG8_MMA(1, 1, At, B1); PG8_BAR; PG8_SCHED;
.LBB0_214:
	s_add_u32 s4, s0, 0xfffc0080
	s_addc_u32 s5, s1, -1
	s_add_i32 s25, 0, 0x10000
	s_cmp_eq_u32 s24, 12
	s_cselect_b32 s7, s10, s5
	s_cselect_b32 s6, s11, s4
	v_add_u32_e32 v0, s25, v214
	s_cselect_b32 s5, s12, s23
	s_cselect_b32 s4, s21, s22
	s_add_i32 s26, 0, 0x14000
	ds_read_b128 v[66:69], v0
	ds_read_b128 v[70:73], v0 offset:1024
	ds_read_b128 v[74:77], v0 offset:2048
	ds_read_b128 v[82:85], v0 offset:3072
	v_add_u32_e32 v0, s26, v214
	ds_read_b128 v[114:117], v0
	ds_read_b128 v[118:121], v0 offset:1024
	ds_read_b128 v[122:125], v0 offset:2048
	ds_read_b128 v[126:129], v0 offset:3072
	v_lshl_add_u64 v[192:193], s[0:1], 0, v[180:181]
	s_add_i32 m0, s31, 0xc000
	ds_read_b128 v[184:187], v223
	ds_read_b128 v[188:191], v223 offset:1024
	ds_read_b128 v[196:199], v223 offset:2048
	ds_read_b128 v[200:203], v223 offset:3072
	ds_read_b128 v[204:207], v223 offset:4096
	ds_read_b128 v[208:211], v223 offset:5120
	ds_read_b128 v[224:227], v223 offset:6144
	ds_read_b128 v[228:231], v223 offset:7168
	global_load_lds_dwordx4 v[192:193], off
	v_lshl_add_u64 v[192:193], s[0:1], 0, v[182:183]
	s_add_i32 m0, s31, 0xe000
	s_nop 0
	global_load_lds_dwordx4 v[192:193], off
	s_waitcnt vmcnt(8)
	s_waitcnt lgkmcnt(0)
	s_setprio 1
	s_barrier
	v_mfma_f32_16x16x32_bf16 v[142:145], v[66:69], v[184:187], v[142:145]
	v_mfma_f32_16x16x32_bf16 v[138:141], v[74:77], v[184:187], v[138:141]
	v_mfma_f32_16x16x32_bf16 v[94:97], v[66:69], v[196:199], v[94:97]
	v_mfma_f32_16x16x32_bf16 v[90:93], v[74:77], v[196:199], v[90:93]
	v_mfma_f32_16x16x32_bf16 v[158:161], v[66:69], v[204:207], v[158:161]
	v_mfma_f32_16x16x32_bf16 v[154:157], v[74:77], v[204:207], v[154:157]
	v_mfma_f32_16x16x32_bf16 v[110:113], v[66:69], v[224:227], v[110:113]
	v_mfma_f32_16x16x32_bf16 v[106:109], v[74:77], v[224:227], v[106:109]
	v_mfma_f32_16x16x32_bf16 v[142:145], v[70:73], v[188:191], v[142:145]
	v_mfma_f32_16x16x32_bf16 v[138:141], v[82:85], v[188:191], v[138:141]
	v_mfma_f32_16x16x32_bf16 v[94:97], v[70:73], v[200:203], v[94:97]
	v_mfma_f32_16x16x32_bf16 v[90:93], v[82:85], v[200:203], v[90:93]
	v_mfma_f32_16x16x32_bf16 v[158:161], v[70:73], v[208:211], v[158:161]
	v_mfma_f32_16x16x32_bf16 v[154:157], v[82:85], v[208:211], v[154:157]
	v_mfma_f32_16x16x32_bf16 v[110:113], v[70:73], v[228:231], v[110:113]
	v_mfma_f32_16x16x32_bf16 v[106:109], v[82:85], v[228:231], v[106:109]
	v_mfma_f32_16x16x32_bf16 v[134:137], v[114:117], v[184:187], v[134:137]
	v_mfma_f32_16x16x32_bf16 v[130:133], v[122:125], v[184:187], v[130:133]
	v_mfma_f32_16x16x32_bf16 v[86:89], v[114:117], v[196:199], v[86:89]
	v_mfma_f32_16x16x32_bf16 v[78:81], v[122:125], v[196:199], v[78:81]
	v_mfma_f32_16x16x32_bf16 v[150:153], v[114:117], v[204:207], v[150:153]
	v_mfma_f32_16x16x32_bf16 v[146:149], v[122:125], v[204:207], v[146:149]
	v_mfma_f32_16x16x32_bf16 v[102:105], v[114:117], v[224:227], v[102:105]
	v_mfma_f32_16x16x32_bf16 v[98:101], v[122:125], v[224:227], v[98:101]
	v_mfma_f32_16x16x32_bf16 v[134:137], v[118:121], v[188:191], v[134:137]
	v_mfma_f32_16x16x32_bf16 v[130:133], v[126:129], v[188:191], v[130:133]
	v_mfma_f32_16x16x32_bf16 v[86:89], v[118:121], v[200:203], v[86:89]
	v_mfma_f32_16x16x32_bf16 v[78:81], v[126:129], v[200:203], v[78:81]
	v_mfma_f32_16x16x32_bf16 v[150:153], v[118:121], v[208:211], v[150:153]
	v_mfma_f32_16x16x32_bf16 v[146:149], v[126:129], v[208:211], v[146:149]
	v_mfma_f32_16x16x32_bf16 v[102:105], v[118:121], v[228:231], v[102:105]
	v_mfma_f32_16x16x32_bf16 v[98:101], v[126:129], v[228:231], v[98:101]
	s_barrier
	s_setprio 0
	s_add_i32 s25, s25, s30
	v_lshl_add_u64 v[192:193], s[4:5], 0, v[166:167]
	s_mov_b32 m0, s25
	ds_read_b128 v[184:187], v223 offset:16384
	ds_read_b128 v[188:191], v223 offset:17408
	ds_read_b128 v[196:199], v223 offset:18432
	ds_read_b128 v[200:203], v223 offset:19456
	ds_read_b128 v[204:207], v223 offset:20480
	ds_read_b128 v[208:211], v223 offset:21504
	ds_read_b128 v[224:227], v223 offset:22528
	ds_read_b128 v[228:231], v223 offset:23552
	global_load_lds_dwordx4 v[192:193], off
	s_add_i32 m0, s25, 0x2000
	s_add_u32 s38, s4, 0x40000
	v_lshl_add_u64 v[212:213], s[4:5], 0, v[162:163]
	s_addc_u32 s39, s5, 0
	s_add_i32 s25, s26, s30
	global_load_lds_dwordx4 v[212:213], off
	v_lshl_add_u64 v[232:233], s[38:39], 0, v[166:167]
	s_mov_b32 m0, s25
	v_lshl_add_u64 v[234:235], s[6:7], 0, v[164:165]
	global_load_lds_dwordx4 v[232:233], off
	v_lshl_add_u64 v[232:233], s[38:39], 0, v[162:163]
	s_add_i32 m0, s25, 0x2000
	s_nop 0
	global_load_lds_dwordx4 v[232:233], off
	v_lshl_add_u64 v[232:233], s[6:7], 0, v[168:169]
	s_mov_b32 m0, s31
	s_nop 0
	global_load_lds_dwordx4 v[232:233], off
	s_mov_b32 m0, s62
	s_nop 0
	global_load_lds_dwordx4 v[234:235], off
	s_waitcnt vmcnt(8)
	s_waitcnt lgkmcnt(0)
	s_setprio 1
	s_barrier
; #define PG8_STAGE(bufoff, gbase, voff) do { _Pragma("unroll") for (int _i = 0; _i < 2; ++_i) \
;         __builtin_amdgcn_global_load_lds((const unsigned*)((const char*)(gbase) + (voff)[_i]), (PG8_LAS unsigned*)(lds + (bufoff) + ldsw + _i * 8192), 16, 0, 0); } while (0)
; #define PG8_LDA(dst, b, h) do { _Pragma("unroll") for (int m = 0; m < 4; ++m) _Pragma("unroll") for (int k = 0; k < 2; ++k) dst[m][k] = *(const PG8_LAS bf16x8*)(lds + PG8_SA(b, h) + aoff + m * 2048 + k * 1024); } while (0)
; #define PG8_LDB(dst, b, h) do { _Pragma("unroll") for (int n = 0; n < 2; ++n) _Pragma("unroll") for (int k = 0; k < 2; ++k) dst[n][k] = *(const PG8_LAS bf16x8*)(lds + PG8_SB(b, h) + boff + n * 2048 + k * 1024); } while (0)
; #define PG8_MMA(ai, bj, At, Bt) do { __builtin_amdgcn_s_setprio(1); _Pragma("unroll") for (int m = 0; m < 4; ++m) _Pragma("unroll") for (int n = 0; n < 2; ++n) _Pragma("unroll") for (int k = 0; k < 2; ++k) \
;         acc[ai][bj][m][n] = __builtin_amdgcn_mfma_f32_16x16x32_bf16(Bt[n][k], At[m][k], acc[ai][bj][m][n], 0, 0, 0); __builtin_amdgcn_s_setprio(0); } while (0)
; #define PG8_BAR __builtin_amdgcn_s_barrier()
; template <class Epi, class Sched, bool ALIGN_EPI = false, bool SP2 = false>
; __device__ __forceinline__ void gemm_phase(PG8_LAS unsigned char* lds, const Gemm g, const Sched& S, const Epi& E, int wv) {
;     ...
;             PG8_LDB(B0, 0, 0); PG8_LDB(B1, 0, 1); PG8_SCHED; PG8_LDA(At, 0, 0); PG8_STAGE(PG8_SA(1, 1), a1 + hstepA, voffA);
;             PG8_WAIT_V(8); PG8_WAIT_L(0); PG8_BAR; PG8_MMA(0, 0, At, B0); PG8_MMA(0, 1, At, B1); PG8_BAR; PG8_SCHED;
;             PG8_LDA(At, 0, 1); PG8_STAGE(PG8_SB(0, 0), b2, voffB); PG8_STAGE(PG8_SB(0, 1), b2 + hstep, voffB); PG8_STAGE(PG8_SA(0, 0), a2, voffA);
;             PG8_WAIT_V(8); PG8_WAIT_L(0); PG8_BAR; PG8_MMA(1, 0, At, B0); PG8_MMA(1, 1, At, B1); PG8_BAR; PG8_SCHED;
;             PG8_LDB(B0, 1, 0); PG8_LDB(B1, 1, 1); PG8_SCHED; PG8_LDA(At, 1, 0); PG8_STAGE(PG8_SA(0, 1), a2 + hstepA, voffA);
;             PG8_WAIT_V(8); PG8_WAIT_L(0); PG8_BAR; PG8_MMA(0, 0, At, B0); PG8_MMA(0, 1, At, B1); PG8_BAR; PG8_SCHED;
;             PG8_LDA(At, 1, 1); PG8_STAGE(PG8_SB(1, 0), b3, voffB); PG8_STAGE(PG8_SB(1, 1), b3 + hstep, voffB); PG8_STAGE(PG8_SA(1, 0), a3, voffA);
;             PG8_WAIT_V(8); PG8_WAIT_L(0); PG8_BAR; PG8_MMA(1, 0, At, B0); PG8_MMA(1, 1, At, B1); PG8_BAR; PG8_SCHED;
	v_mfma_f32_16x16x32_bf16 v[62:65], v[66:69], v[184:187], v[62:65]
	v_mfma_f32_16x16x32_bf16 v[58:61], v[74:77], v[184:187], v[58:61]
	v_mfma_f32_16x16x32_bf16 v[46:49], v[66:69], v[196:199], v[46:49]
	v_mfma_f32_16x16x32_bf16 v[42:45], v[74:77], v[196:199], v[42:45]
	v_mfma_f32_16x16x32_bf16 v[30:33], v[66:69], v[204:207], v[30:33]
	v_mfma_f32_16x16x32_bf16 v[26:29], v[74:77], v[204:207], v[26:29]
	v_mfma_f32_16x16x32_bf16 v[14:17], v[66:69], v[224:227], v[14:17]
	v_mfma_f32_16x16x32_bf16 v[10:13], v[74:77], v[224:227], v[10:13]
	v_mfma_f32_16x16x32_bf16 v[62:65], v[70:73], v[188:191], v[62:65]
	v_mfma_f32_16x16x32_bf16 v[58:61], v[82:85], v[188:191], v[58:61]
	v_mfma_f32_16x16x32_bf16 v[46:49], v[70:73], v[200:203], v[46:49]
	v_mfma_f32_16x16x32_bf16 v[42:45], v[82:85], v[200:203], v[42:45]
	v_mfma_f32_16x16x32_bf16 v[30:33], v[70:73], v[208:211], v[30:33]
	v_mfma_f32_16x16x32_bf16 v[26:29], v[82:85], v[208:211], v[26:29]
	v_mfma_f32_16x16x32_bf16 v[14:17], v[70:73], v[228:231], v[14:17]
	v_mfma_f32_16x16x32_bf16 v[10:13], v[82:85], v[228:231], v[10:13]
	v_mfma_f32_16x16x32_bf16 v[54:57], v[114:117], v[184:187], v[54:57]
	v_mfma_f32_16x16x32_bf16 v[50:53], v[122:125], v[184:187], v[50:53]
	v_mfma_f32_16x16x32_bf16 v[38:41], v[114:117], v[196:199], v[38:41]
	v_mfma_f32_16x16x32_bf16 v[34:37], v[122:125], v[196:199], v[34:37]
	v_mfma_f32_16x16x32_bf16 v[22:25], v[114:117], v[204:207], v[22:25]
	v_mfma_f32_16x16x32_bf16 v[18:21], v[122:125], v[204:207], v[18:21]
	v_mfma_f32_16x16x32_bf16 v[6:9], v[114:117], v[224:227], v[6:9]
	v_mfma_f32_16x16x32_bf16 v[2:5], v[122:125], v[224:227], v[2:5]
	v_mfma_f32_16x16x32_bf16 v[54:57], v[118:121], v[188:191], v[54:57]
	v_mfma_f32_16x16x32_bf16 v[50:53], v[126:129], v[188:191], v[50:53]
	v_mfma_f32_16x16x32_bf16 v[38:41], v[118:121], v[200:203], v[38:41]
	v_mfma_f32_16x16x32_bf16 v[34:37], v[126:129], v[200:203], v[34:37]
	v_mfma_f32_16x16x32_bf16 v[22:25], v[118:121], v[208:211], v[22:25]
	v_mfma_f32_16x16x32_bf16 v[18:21], v[126:129], v[208:211], v[18:21]
	v_mfma_f32_16x16x32_bf16 v[6:9], v[118:121], v[228:231], v[6:9]
	v_mfma_f32_16x16x32_bf16 v[2:5], v[126:129], v[228:231], v[2:5]
	s_barrier
	s_setprio 0
	s_add_i32 s25, 0, 0x18000
	v_add_u32_e32 v0, s25, v214
	s_add_i32 s26, 0, 0x1c000
	ds_read_b128 v[66:69], v0
	ds_read_b128 v[70:73], v0 offset:1024
	ds_read_b128 v[74:77], v0 offset:2048
	ds_read_b128 v[82:85], v0 offset:3072
	v_add_u32_e32 v0, s26, v214
	ds_read_b128 v[114:117], v0
	ds_read_b128 v[118:121], v0 offset:1024
	ds_read_b128 v[122:125], v0 offset:2048
	ds_read_b128 v[126:129], v0 offset:3072
	s_add_u32 s6, s6, 0x40000
	s_addc_u32 s7, s7, 0
	s_mov_b32 m0, s63
	v_lshl_add_u64 v[236:237], s[6:7], 0, v[168:169]
	ds_read_b128 v[184:187], v223 offset:32768
	ds_read_b128 v[188:191], v223 offset:33792
	ds_read_b128 v[196:199], v223 offset:34816
	ds_read_b128 v[200:203], v223 offset:35840
	ds_read_b128 v[204:207], v223 offset:36864
	ds_read_b128 v[208:211], v223 offset:37888
	ds_read_b128 v[224:227], v223 offset:38912
	ds_read_b128 v[228:231], v223 offset:39936
	global_load_lds_dwordx4 v[236:237], off
	v_lshl_add_u64 v[236:237], s[6:7], 0, v[164:165]
	s_mov_b32 m0, s64
	s_nop 0
	global_load_lds_dwordx4 v[236:237], off
	s_waitcnt vmcnt(8)
	s_waitcnt lgkmcnt(0)
	s_setprio 1
	s_barrier
	v_mfma_f32_16x16x32_bf16 v[142:145], v[66:69], v[184:187], v[142:145]
	v_mfma_f32_16x16x32_bf16 v[138:141], v[74:77], v[184:187], v[138:141]
	v_mfma_f32_16x16x32_bf16 v[94:97], v[66:69], v[196:199], v[94:97]
	v_mfma_f32_16x16x32_bf16 v[90:93], v[74:77], v[196:199], v[90:93]
	v_mfma_f32_16x16x32_bf16 v[158:161], v[66:69], v[204:207], v[158:161]
	v_mfma_f32_16x16x32_bf16 v[154:157], v[74:77], v[204:207], v[154:157]
	v_mfma_f32_16x16x32_bf16 v[110:113], v[66:69], v[224:227], v[110:113]
	v_mfma_f32_16x16x32_bf16 v[106:109], v[74:77], v[224:227], v[106:109]
	v_mfma_f32_16x16x32_bf16 v[142:145], v[70:73], v[188:191], v[142:145]
	v_mfma_f32_16x16x32_bf16 v[138:141], v[82:85], v[188:191], v[138:141]
	v_mfma_f32_16x16x32_bf16 v[94:97], v[70:73], v[200:203], v[94:97]
	v_mfma_f32_16x16x32_bf16 v[90:93], v[82:85], v[200:203], v[90:93]
	v_mfma_f32_16x16x32_bf16 v[158:161], v[70:73], v[208:211], v[158:161]
	v_mfma_f32_16x16x32_bf16 v[154:157], v[82:85], v[208:211], v[154:157]
	v_mfma_f32_16x16x32_bf16 v[110:113], v[70:73], v[228:231], v[110:113]
	v_mfma_f32_16x16x32_bf16 v[106:109], v[82:85], v[228:231], v[106:109]
	v_mfma_f32_16x16x32_bf16 v[134:137], v[114:117], v[184:187], v[134:137]
	v_mfma_f32_16x16x32_bf16 v[130:133], v[122:125], v[184:187], v[130:133]
	v_mfma_f32_16x16x32_bf16 v[86:89], v[114:117], v[196:199], v[86:89]
	v_mfma_f32_16x16x32_bf16 v[78:81], v[122:125], v[196:199], v[78:81]
	v_mfma_f32_16x16x32_bf16 v[150:153], v[114:117], v[204:207], v[150:153]
	v_mfma_f32_16x16x32_bf16 v[146:149], v[122:125], v[204:207], v[146:149]
	v_mfma_f32_16x16x32_bf16 v[102:105], v[114:117], v[224:227], v[102:105]
	v_mfma_f32_16x16x32_bf16 v[98:101], v[122:125], v[224:227], v[98:101]
	v_mfma_f32_16x16x32_bf16 v[134:137], v[118:121], v[188:191], v[134:137]
	v_mfma_f32_16x16x32_bf16 v[130:133], v[126:129], v[188:191], v[130:133]
	v_mfma_f32_16x16x32_bf16 v[86:89], v[118:121], v[200:203], v[86:89]
	v_mfma_f32_16x16x32_bf16 v[78:81], v[126:129], v[200:203], v[78:81]
	v_mfma_f32_16x16x32_bf16 v[150:153], v[118:121], v[208:211], v[150:153]
	v_mfma_f32_16x16x32_bf16 v[146:149], v[126:129], v[208:211], v[146:149]
	v_mfma_f32_16x16x32_bf16 v[102:105], v[118:121], v[228:231], v[102:105]
	v_mfma_f32_16x16x32_bf16 v[98:101], v[126:129], v[228:231], v[98:101]
	s_barrier
; #define PG8_STAGE(bufoff, gbase, voff) do { _Pragma("unroll") for (int _i = 0; _i < 2; ++_i) \
;         __builtin_amdgcn_global_load_lds((const unsigned*)((const char*)(gbase) + (voff)[_i]), (PG8_LAS unsigned*)(lds + (bufoff) + ldsw + _i * 8192), 16, 0, 0); } while (0)
; #define PG8_LDA(dst, b, h) do { _Pragma("unroll") for (int m = 0; m < 4; ++m) _Pragma("unroll") for (int k = 0; k < 2; ++k) dst[m][k] = *(const PG8_LAS bf16x8*)(lds + PG8_SA(b, h) + aoff + m * 2048 + k * 1024); } while (0)
; #define PG8_LDB(dst, b, h) do { _Pragma("unroll") for (int n = 0; n < 2; ++n) _Pragma("unroll") for (int k = 0; k < 2; ++k) dst[n][k] = *(const PG8_LAS bf16x8*)(lds + PG8_SB(b, h) + boff + n * 2048 + k * 1024); } while (0)
; #define PG8_MMA(ai, bj, At, Bt) do { __builtin_amdgcn_s_setprio(1); _Pragma("unroll") for (int m = 0; m < 4; ++m) _Pragma("unroll") for (int n = 0; n < 2; ++n) _Pragma("unroll") for (int k = 0; k < 2; ++k) \
;         acc[ai][bj][m][n] = __builtin_amdgcn_mfma_f32_16x16x32_bf16(Bt[n][k], At[m][k], acc[ai][bj][m][n], 0, 0, 0); __builtin_amdgcn_s_setprio(0); } while (0)
; template <class Epi, class Sched, bool ALIGN_EPI = false, bool SP2 = false>
; __device__ __forceinline__ void gemm_phase(PG8_LAS unsigned char* lds, const Gemm g, const Sched& S, const Epi& E, int wv) {
;     ...
;             PG8_LDB(B0, 0, 0); PG8_LDB(B1, 0, 1); PG8_SCHED; PG8_LDA(At, 0, 0); PG8_STAGE(PG8_SA(1, 1), a1 + hstepA, voffA);
;             PG8_WAIT_V(8); PG8_WAIT_L(0); PG8_BAR; PG8_MMA(0, 0, At, B0); PG8_MMA(0, 1, At, B1); PG8_BAR; PG8_SCHED;
;             PG8_LDA(At, 0, 1); PG8_STAGE(PG8_SB(0, 0), b2, voffB); PG8_STAGE(PG8_SB(0, 1), b2 + hstep, voffB); PG8_STAGE(PG8_SA(0, 0), a2, voffA);
;             PG8_WAIT_V(8); PG8_WAIT_L(0); PG8_BAR; PG8_MMA(1, 0, At, B0); PG8_MMA(1, 1, At, B1); PG8_BAR; PG8_SCHED;
;             PG8_LDB(B0, 1, 0); PG8_LDB(B1, 1, 1); PG8_SCHED; PG8_LDA(At, 1, 0); PG8_STAGE(PG8_SA(0, 1), a2 + hstepA, voffA);
;             PG8_WAIT_V(8); PG8_WAIT_L(0); PG8_BAR; PG8_MMA(0, 0, At, B0); PG8_MMA(0, 1, At, B1); PG8_BAR; PG8_SCHED;
;             PG8_LDA(At, 1, 1); PG8_STAGE(PG8_SB(1, 0), b3, voffB); PG8_STAGE(PG8_SB(1, 1), b3 + hstep, voffB); PG8_STAGE(PG8_SA(1, 0), a3, voffA);
;             PG8_WAIT_V(8); PG8_WAIT_L(0); PG8_BAR; PG8_MMA(1, 0, At, B0); PG8_MMA(1, 1, At, B1); PG8_BAR; PG8_SCHED;
;     ...
;         if constexpr (ALIGN_EPI) { if (wr == 0) PG8_BAR; }
	s_setprio 0
	s_add_i32 s6, s25, s30
	v_lshl_add_u64 v[192:193], v[192:193], 0, s[14:15]
	s_mov_b32 m0, s6
	ds_read_b128 v[184:187], v223 offset:49152
	ds_read_b128 v[188:191], v223 offset:50176
	ds_read_b128 v[196:199], v223 offset:51200
	ds_read_b128 v[200:203], v223 offset:52224
	ds_read_b128 v[204:207], v223 offset:53248
	ds_read_b128 v[208:211], v223 offset:54272
	ds_read_b128 v[224:227], v223 offset:55296
	ds_read_b128 v[228:231], v223 offset:56320
	global_load_lds_dwordx4 v[192:193], off
	s_add_i32 m0, s6, 0x2000
	s_add_u32 s4, s4, 0x40080
	v_lshl_add_u64 v[192:193], v[212:213], 0, s[14:15]
	s_addc_u32 s5, s5, 0
	s_add_i32 s6, s26, s30
	global_load_lds_dwordx4 v[192:193], off
	v_lshl_add_u64 v[192:193], s[4:5], 0, v[166:167]
	s_mov_b32 m0, s6
	s_nop 0
	global_load_lds_dwordx4 v[192:193], off
	v_lshl_add_u64 v[192:193], s[4:5], 0, v[162:163]
	s_add_i32 m0, s6, 0x2000
	s_nop 0
	global_load_lds_dwordx4 v[192:193], off
	v_lshl_add_u64 v[192:193], v[232:233], 0, s[14:15]
	s_mov_b32 m0, s66
	s_nop 0
	global_load_lds_dwordx4 v[192:193], off
	v_lshl_add_u64 v[192:193], v[234:235], 0, s[14:15]
	s_mov_b32 m0, s67
	s_nop 0
	global_load_lds_dwordx4 v[192:193], off
	s_waitcnt vmcnt(8)
	s_waitcnt lgkmcnt(0)
	s_setprio 1
	s_barrier
	v_mfma_f32_16x16x32_bf16 v[62:65], v[66:69], v[184:187], v[62:65]
	v_mfma_f32_16x16x32_bf16 v[58:61], v[74:77], v[184:187], v[58:61]
	v_mfma_f32_16x16x32_bf16 v[46:49], v[66:69], v[196:199], v[46:49]
	v_mfma_f32_16x16x32_bf16 v[42:45], v[74:77], v[196:199], v[42:45]
	v_mfma_f32_16x16x32_bf16 v[30:33], v[66:69], v[204:207], v[30:33]
	v_mfma_f32_16x16x32_bf16 v[26:29], v[74:77], v[204:207], v[26:29]
	v_mfma_f32_16x16x32_bf16 v[14:17], v[66:69], v[224:227], v[14:17]
	v_mfma_f32_16x16x32_bf16 v[10:13], v[74:77], v[224:227], v[10:13]
	v_mfma_f32_16x16x32_bf16 v[62:65], v[70:73], v[188:191], v[62:65]
	v_mfma_f32_16x16x32_bf16 v[58:61], v[82:85], v[188:191], v[58:61]
	v_mfma_f32_16x16x32_bf16 v[46:49], v[70:73], v[200:203], v[46:49]
	v_mfma_f32_16x16x32_bf16 v[42:45], v[82:85], v[200:203], v[42:45]
	v_mfma_f32_16x16x32_bf16 v[30:33], v[70:73], v[208:211], v[30:33]
	v_mfma_f32_16x16x32_bf16 v[26:29], v[82:85], v[208:211], v[26:29]
	v_mfma_f32_16x16x32_bf16 v[14:17], v[70:73], v[228:231], v[14:17]
	v_mfma_f32_16x16x32_bf16 v[10:13], v[82:85], v[228:231], v[10:13]
	v_mfma_f32_16x16x32_bf16 v[54:57], v[114:117], v[184:187], v[54:57]
	v_mfma_f32_16x16x32_bf16 v[50:53], v[122:125], v[184:187], v[50:53]
	v_mfma_f32_16x16x32_bf16 v[38:41], v[114:117], v[196:199], v[38:41]
	v_mfma_f32_16x16x32_bf16 v[34:37], v[122:125], v[196:199], v[34:37]
	v_mfma_f32_16x16x32_bf16 v[22:25], v[114:117], v[204:207], v[22:25]
	v_mfma_f32_16x16x32_bf16 v[18:21], v[122:125], v[204:207], v[18:21]
	v_mfma_f32_16x16x32_bf16 v[6:9], v[114:117], v[224:227], v[6:9]
	v_mfma_f32_16x16x32_bf16 v[2:5], v[122:125], v[224:227], v[2:5]
	v_mfma_f32_16x16x32_bf16 v[54:57], v[118:121], v[188:191], v[54:57]
	v_mfma_f32_16x16x32_bf16 v[50:53], v[126:129], v[188:191], v[50:53]
	v_mfma_f32_16x16x32_bf16 v[38:41], v[118:121], v[200:203], v[38:41]
	v_mfma_f32_16x16x32_bf16 v[34:37], v[126:129], v[200:203], v[34:37]
	v_mfma_f32_16x16x32_bf16 v[22:25], v[118:121], v[208:211], v[22:25]
	v_mfma_f32_16x16x32_bf16 v[18:21], v[126:129], v[208:211], v[18:21]
	v_mfma_f32_16x16x32_bf16 v[6:9], v[118:121], v[228:231], v[6:9]
	v_mfma_f32_16x16x32_bf16 v[2:5], v[126:129], v[228:231], v[2:5]
	s_barrier
	s_setprio 0
	s_add_i32 s24, s24, 2
	s_add_u32 s0, s0, 0x100
	s_addc_u32 s1, s1, 0
	s_add_u32 s22, s22, 0x100
	s_addc_u32 s23, s23, 0
	s_cmp_gt_u32 s24, 13
	s_cbranch_scc0 .LBB0_214
	s_and_b64 vcc, exec, s[52:53]
	s_cbranch_vccz .LBB0_217
	s_barrier

; #define PG8_STAGE(bufoff, gbase, voff) do { _Pragma("unroll") for (int _i = 0; _i < 2; ++_i) \
;         __builtin_amdgcn_global_load_lds((const unsigned*)((const char*)(gbase) + (voff)[_i]), (PG8_LAS unsigned*)(lds + (bufoff) + ldsw + _i * 8192), 16, 0, 0); } while (0)
; #define PG8_LDA(dst, b, h) do { _Pragma("unroll") for (int m = 0; m < 4; ++m) _Pragma("unroll") for (int k = 0; k < 2; ++k) dst[m][k] = *(const PG8_LAS bf16x8*)(lds + PG8_SA(b, h) + aoff + m * 2048 + k * 1024); } while (0)
; #define PG8_LDB(dst, b, h) do { _Pragma("unroll") for (int n = 0; n < 2; ++n) _Pragma("unroll") for (int k = 0; k < 2; ++k) dst[n][k] = *(const PG8_LAS bf16x8*)(lds + PG8_SB(b, h) + boff + n * 2048 + k * 1024); } while (0)
; template <class Epi, class Sched, bool ALIGN_EPI = false, bool SP2 = false>
; __device__ __forceinline__ void gemm_phase(PG8_LAS unsigned char* lds, const Gemm g, const Sched& S, const Epi& E, int wv) {
;     ...
;         for (int t = 0; t < nt; t += 2) {
;             const bool last = (t == nt - 2);
;             const char* a1 = cA + (size_t)(t + 1) * kstep;
;             const char* a2 = last ? nA : cA + (size_t)(t + 2) * kstep; const char* b2 = last ? nB : cB + (size_t)(t + 2) * kstep;
;             const char* a3 = a2 + kstep; const char* b3 = b2 + kstep;
;             if (last && has_next) S.a_ready(nxt);
;             if constexpr (SP2) {
;             PG8_LDB(B0, 0, 0); PG8_LDB(B1, 0, 1); PG8_SCHED; PG8_LDA(At, 0, 0); PG8_STAGE(PG8_SA(1, 1), a1 + hstepA, voffA);
;             PG8_WAIT_V(8); PG8_WAIT_L(0); PG8_BAR; PG8_MMA(0, 0, At, B0); PG8_MMA(0, 1, At, B1); PG8_BAR; PG8_SCHED;
;             PG8_LDA(At, 0, 1); PG8_STAGE(PG8_SB(0, 0), b2, voffB); PG8_STAGE(PG8_SB(0, 1), b2 + hstep, voffB); PG8_STAGE(PG8_SA(0, 0), a2, voffA);
;             PG8_WAIT_V(8); PG8_WAIT_L(0); PG8_BAR; PG8_MMA(1, 0, At, B0); PG8_MMA(1, 1, At, B1); PG8_BAR; PG8_SCHED;
;             PG8_LDB(B0, 1, 0); PG8_LDB(B1, 1, 1); PG8_SCHED; PG8_LDA(At, 1, 0); PG8_STAGE(PG8_SA(0, 1), a2 + hstepA, voffA);
;             PG8_WAIT_V(8); PG8_WAIT_L(0); PG8_BAR; PG8_MMA(0, 0, At, B0); PG8_MMA(0, 1, At, B1); PG8_BAR; PG8_SCHED;
;             PG8_LDA(At, 1, 1); PG8_STAGE(PG8_SB(1, 0), b3, voffB); PG8_STAGE(PG8_SB(1, 1), b3 + hstep, voffB); PG8_STAGE(PG8_SA(1, 0), a3, voffA);
;             PG8_WAIT_V(8); PG8_WAIT_L(0); PG8_BAR; PG8_MMA(1, 0, At, B0); PG8_MMA(1, 1, At, B1); PG8_BAR; PG8_SCHED;
.LBB0_438:
	s_add_u32 s0, s4, 0x100
	s_addc_u32 s1, s5, 0
	s_add_i32 s25, 0, 0x10000
	s_cmp_eq_u32 s26, 2
	s_cselect_b32 s9, s49, s1
	s_cselect_b32 s8, s48, s0
	s_cselect_b32 s7, s51, s24
	s_cselect_b32 s6, s50, s23
	s_add_i32 s38, 0, 0x14000
	v_add_u32_e32 v86, s25, v191
	v_add_u32_e32 v130, s38, v191
	ds_read_b128 v[74:77], v86
	ds_read_b128 v[78:81], v86 offset:1024
	ds_read_b128 v[82:85], v86 offset:2048
	ds_read_b128 v[86:89], v86 offset:3072
	ds_read_b128 v[114:117], v130
	ds_read_b128 v[118:121], v130 offset:1024
	ds_read_b128 v[126:129], v130 offset:2048
	ds_read_b128 v[130:133], v130 offset:3072
	v_lshl_add_u64 v[192:193], s[4:5], 0, v[174:175]
	s_add_i32 m0, s28, 0xc000
	ds_read_b128 v[178:181], v197
	ds_read_b128 v[182:185], v197 offset:1024
	ds_read_b128 v[186:189], v197 offset:2048
	ds_read_b128 v[198:201], v197 offset:3072
	ds_read_b128 v[202:205], v197 offset:4096
	ds_read_b128 v[206:209], v197 offset:5120
	ds_read_b128 v[210:213], v197 offset:6144
	ds_read_b128 v[222:225], v197 offset:7168
	global_load_lds_dwordx4 v[192:193], off
	v_lshl_add_u64 v[192:193], s[4:5], 0, v[176:177]
	s_add_i32 m0, s28, 0xe000
	s_nop 0
	global_load_lds_dwordx4 v[192:193], off
	s_waitcnt vmcnt(8)
	s_waitcnt lgkmcnt(0)
	s_setprio 1
	s_barrier
	v_mfma_f32_16x16x32_bf16 v[150:153], v[74:77], v[178:181], v[150:153]
	v_mfma_f32_16x16x32_bf16 v[146:149], v[82:85], v[178:181], v[146:149]
	v_mfma_f32_16x16x32_bf16 v[102:105], v[74:77], v[186:189], v[102:105]
	v_mfma_f32_16x16x32_bf16 v[98:101], v[82:85], v[186:189], v[98:101]
	v_mfma_f32_16x16x32_bf16 v[158:161], v[74:77], v[202:205], v[158:161]
	v_mfma_f32_16x16x32_bf16 v[154:157], v[82:85], v[202:205], v[154:157]
	v_mfma_f32_16x16x32_bf16 v[110:113], v[74:77], v[210:213], v[110:113]
	v_mfma_f32_16x16x32_bf16 v[106:109], v[82:85], v[210:213], v[106:109]
	v_mfma_f32_16x16x32_bf16 v[150:153], v[78:81], v[182:185], v[150:153]
	v_mfma_f32_16x16x32_bf16 v[146:149], v[86:89], v[182:185], v[146:149]
	v_mfma_f32_16x16x32_bf16 v[102:105], v[78:81], v[198:201], v[102:105]
	v_mfma_f32_16x16x32_bf16 v[98:101], v[86:89], v[198:201], v[98:101]
	v_mfma_f32_16x16x32_bf16 v[158:161], v[78:81], v[206:209], v[158:161]
	v_mfma_f32_16x16x32_bf16 v[154:157], v[86:89], v[206:209], v[154:157]
	v_mfma_f32_16x16x32_bf16 v[110:113], v[78:81], v[222:225], v[110:113]
	v_mfma_f32_16x16x32_bf16 v[106:109], v[86:89], v[222:225], v[106:109]
	v_mfma_f32_16x16x32_bf16 v[142:145], v[114:117], v[178:181], v[142:145]
	v_mfma_f32_16x16x32_bf16 v[138:141], v[126:129], v[178:181], v[138:141]
	v_mfma_f32_16x16x32_bf16 v[94:97], v[114:117], v[186:189], v[94:97]
	v_mfma_f32_16x16x32_bf16 v[90:93], v[126:129], v[186:189], v[90:93]
	v_mfma_f32_16x16x32_bf16 v[134:137], v[114:117], v[202:205], v[134:137]
	v_mfma_f32_16x16x32_bf16 v[122:125], v[126:129], v[202:205], v[122:125]
	v_mfma_f32_16x16x32_bf16 v[70:73], v[114:117], v[210:213], v[70:73]
	v_mfma_f32_16x16x32_bf16 v[66:69], v[126:129], v[210:213], v[66:69]
	v_mfma_f32_16x16x32_bf16 v[142:145], v[118:121], v[182:185], v[142:145]
	v_mfma_f32_16x16x32_bf16 v[138:141], v[130:133], v[182:185], v[138:141]
	v_mfma_f32_16x16x32_bf16 v[94:97], v[118:121], v[198:201], v[94:97]
	v_mfma_f32_16x16x32_bf16 v[90:93], v[130:133], v[198:201], v[90:93]
	v_mfma_f32_16x16x32_bf16 v[134:137], v[118:121], v[206:209], v[134:137]
	v_mfma_f32_16x16x32_bf16 v[122:125], v[130:133], v[206:209], v[122:125]
	v_mfma_f32_16x16x32_bf16 v[70:73], v[118:121], v[222:225], v[70:73]
	v_mfma_f32_16x16x32_bf16 v[66:69], v[130:133], v[222:225], v[66:69]
	s_barrier
	s_setprio 0
	s_add_i32 s4, s25, s17
	v_lshl_add_u64 v[192:193], s[6:7], 0, v[0:1]
	s_mov_b32 m0, s4
	ds_read_b128 v[178:181], v197 offset:16384
	ds_read_b128 v[182:185], v197 offset:17408
	ds_read_b128 v[186:189], v197 offset:18432
	ds_read_b128 v[198:201], v197 offset:19456
	ds_read_b128 v[202:205], v197 offset:20480
	ds_read_b128 v[206:209], v197 offset:21504
	ds_read_b128 v[210:213], v197 offset:22528
	ds_read_b128 v[222:225], v197 offset:23552
	global_load_lds_dwordx4 v[192:193], off
	s_add_i32 m0, s4, 0x2000
	s_add_u32 s4, s6, 0x18000
	v_lshl_add_u64 v[226:227], s[6:7], 0, v[162:163]
	s_addc_u32 s5, s7, 0
	s_add_i32 s25, s38, s17
	global_load_lds_dwordx4 v[226:227], off
	v_lshl_add_u64 v[228:229], s[4:5], 0, v[0:1]
	s_mov_b32 m0, s25
	v_lshl_add_u64 v[230:231], s[8:9], 0, v[164:165]
	global_load_lds_dwordx4 v[228:229], off
	v_lshl_add_u64 v[228:229], s[4:5], 0, v[162:163]
	s_add_i32 m0, s25, 0x2000
	s_nop 0
	global_load_lds_dwordx4 v[228:229], off
	v_lshl_add_u64 v[228:229], s[8:9], 0, v[166:167]
	s_mov_b32 m0, s28
	s_nop 0
	global_load_lds_dwordx4 v[228:229], off
	s_mov_b32 m0, s29
	s_nop 0
	global_load_lds_dwordx4 v[230:231], off
	s_waitcnt vmcnt(8)
	s_waitcnt lgkmcnt(0)
	s_setprio 1
	s_barrier
; #define PG8_STAGE(bufoff, gbase, voff) do { _Pragma("unroll") for (int _i = 0; _i < 2; ++_i) \
;         __builtin_amdgcn_global_load_lds((const unsigned*)((const char*)(gbase) + (voff)[_i]), (PG8_LAS unsigned*)(lds + (bufoff) + ldsw + _i * 8192), 16, 0, 0); } while (0)
; #define PG8_LDA(dst, b, h) do { _Pragma("unroll") for (int m = 0; m < 4; ++m) _Pragma("unroll") for (int k = 0; k < 2; ++k) dst[m][k] = *(const PG8_LAS bf16x8*)(lds + PG8_SA(b, h) + aoff + m * 2048 + k * 1024); } while (0)
; #define PG8_LDB(dst, b, h) do { _Pragma("unroll") for (int n = 0; n < 2; ++n) _Pragma("unroll") for (int k = 0; k < 2; ++k) dst[n][k] = *(const PG8_LAS bf16x8*)(lds + PG8_SB(b, h) + boff + n * 2048 + k * 1024); } while (0)
; #define PG8_MMA(ai, bj, At, Bt) do { __builtin_amdgcn_s_setprio(1); _Pragma("unroll") for (int m = 0; m < 4; ++m) _Pragma("unroll") for (int n = 0; n < 2; ++n) _Pragma("unroll") for (int k = 0; k < 2; ++k) \
;         acc[ai][bj][m][n] = __builtin_amdgcn_mfma_f32_16x16x32_bf16(Bt[n][k], At[m][k], acc[ai][bj][m][n], 0, 0, 0); __builtin_amdgcn_s_setprio(0); } while (0)
; #define PG8_BAR __builtin_amdgcn_s_barrier()
; template <class Epi, class Sched, bool ALIGN_EPI = false, bool SP2 = false>
; __device__ __forceinline__ void gemm_phase(PG8_LAS unsigned char* lds, const Gemm g, const Sched& S, const Epi& E, int wv) {
;     ...
;             PG8_LDB(B0, 0, 0); PG8_LDB(B1, 0, 1); PG8_SCHED; PG8_LDA(At, 0, 0); PG8_STAGE(PG8_SA(1, 1), a1 + hstepA, voffA);
;             PG8_WAIT_V(8); PG8_WAIT_L(0); PG8_BAR; PG8_MMA(0, 0, At, B0); PG8_MMA(0, 1, At, B1); PG8_BAR; PG8_SCHED;
;             PG8_LDA(At, 0, 1); PG8_STAGE(PG8_SB(0, 0), b2, voffB); PG8_STAGE(PG8_SB(0, 1), b2 + hstep, voffB); PG8_STAGE(PG8_SA(0, 0), a2, voffA);
;             PG8_WAIT_V(8); PG8_WAIT_L(0); PG8_BAR; PG8_MMA(1, 0, At, B0); PG8_MMA(1, 1, At, B1); PG8_BAR; PG8_SCHED;
;             PG8_LDB(B0, 1, 0); PG8_LDB(B1, 1, 1); PG8_SCHED; PG8_LDA(At, 1, 0); PG8_STAGE(PG8_SA(0, 1), a2 + hstepA, voffA);
;             PG8_WAIT_V(8); PG8_WAIT_L(0); PG8_BAR; PG8_MMA(0, 0, At, B0); PG8_MMA(0, 1, At, B1); PG8_BAR; PG8_SCHED;
;             PG8_LDA(At, 1, 1); PG8_STAGE(PG8_SB(1, 0), b3, voffB); PG8_STAGE(PG8_SB(1, 1), b3 + hstep, voffB); PG8_STAGE(PG8_SA(1, 0), a3, voffA);
;             PG8_WAIT_V(8); PG8_WAIT_L(0); PG8_BAR; PG8_MMA(1, 0, At, B0); PG8_MMA(1, 1, At, B1); PG8_BAR; PG8_SCHED;
	v_mfma_f32_16x16x32_bf16 v[62:65], v[74:77], v[178:181], v[62:65]
	v_mfma_f32_16x16x32_bf16 v[58:61], v[82:85], v[178:181], v[58:61]
	v_mfma_f32_16x16x32_bf16 v[46:49], v[74:77], v[186:189], v[46:49]
	v_mfma_f32_16x16x32_bf16 v[42:45], v[82:85], v[186:189], v[42:45]
	v_mfma_f32_16x16x32_bf16 v[30:33], v[74:77], v[202:205], v[30:33]
	v_mfma_f32_16x16x32_bf16 v[26:29], v[82:85], v[202:205], v[26:29]
	v_mfma_f32_16x16x32_bf16 v[14:17], v[74:77], v[210:213], v[14:17]
	v_mfma_f32_16x16x32_bf16 v[10:13], v[82:85], v[210:213], v[10:13]
	v_mfma_f32_16x16x32_bf16 v[62:65], v[78:81], v[182:185], v[62:65]
	v_mfma_f32_16x16x32_bf16 v[58:61], v[86:89], v[182:185], v[58:61]
	v_mfma_f32_16x16x32_bf16 v[46:49], v[78:81], v[198:201], v[46:49]
	v_mfma_f32_16x16x32_bf16 v[42:45], v[86:89], v[198:201], v[42:45]
	v_mfma_f32_16x16x32_bf16 v[30:33], v[78:81], v[206:209], v[30:33]
	v_mfma_f32_16x16x32_bf16 v[26:29], v[86:89], v[206:209], v[26:29]
	v_mfma_f32_16x16x32_bf16 v[14:17], v[78:81], v[222:225], v[14:17]
	v_mfma_f32_16x16x32_bf16 v[10:13], v[86:89], v[222:225], v[10:13]
	v_mfma_f32_16x16x32_bf16 v[54:57], v[114:117], v[178:181], v[54:57]
	v_mfma_f32_16x16x32_bf16 v[50:53], v[126:129], v[178:181], v[50:53]
	v_mfma_f32_16x16x32_bf16 v[38:41], v[114:117], v[186:189], v[38:41]
	v_mfma_f32_16x16x32_bf16 v[34:37], v[126:129], v[186:189], v[34:37]
	v_mfma_f32_16x16x32_bf16 v[22:25], v[114:117], v[202:205], v[22:25]
	v_mfma_f32_16x16x32_bf16 v[18:21], v[126:129], v[202:205], v[18:21]
	v_mfma_f32_16x16x32_bf16 v[6:9], v[114:117], v[210:213], v[6:9]
	v_mfma_f32_16x16x32_bf16 v[2:5], v[126:129], v[210:213], v[2:5]
	v_mfma_f32_16x16x32_bf16 v[54:57], v[118:121], v[182:185], v[54:57]
	v_mfma_f32_16x16x32_bf16 v[50:53], v[130:133], v[182:185], v[50:53]
	v_mfma_f32_16x16x32_bf16 v[38:41], v[118:121], v[198:201], v[38:41]
	v_mfma_f32_16x16x32_bf16 v[34:37], v[130:133], v[198:201], v[34:37]
	v_mfma_f32_16x16x32_bf16 v[22:25], v[118:121], v[206:209], v[22:25]
	v_mfma_f32_16x16x32_bf16 v[18:21], v[130:133], v[206:209], v[18:21]
	v_mfma_f32_16x16x32_bf16 v[6:9], v[118:121], v[222:225], v[6:9]
	v_mfma_f32_16x16x32_bf16 v[2:5], v[130:133], v[222:225], v[2:5]
	s_barrier
	s_setprio 0
	s_add_i32 s25, 0, 0x18000
	s_add_i32 s38, 0, 0x1c000
	v_add_u32_e32 v86, s25, v191
	v_add_u32_e32 v130, s38, v191
	ds_read_b128 v[74:77], v86
	ds_read_b128 v[78:81], v86 offset:1024
	ds_read_b128 v[82:85], v86 offset:2048
	ds_read_b128 v[86:89], v86 offset:3072
	ds_read_b128 v[114:117], v130
	ds_read_b128 v[118:121], v130 offset:1024
	ds_read_b128 v[126:129], v130 offset:2048
	ds_read_b128 v[130:133], v130 offset:3072
	s_add_u32 s4, s8, 0x60000
	s_addc_u32 s5, s9, 0
	s_mov_b32 m0, s30
	v_lshl_add_u64 v[232:233], s[4:5], 0, v[166:167]
	ds_read_b128 v[178:181], v197 offset:32768
	ds_read_b128 v[182:185], v197 offset:33792
	ds_read_b128 v[186:189], v197 offset:34816
	ds_read_b128 v[198:201], v197 offset:35840
	ds_read_b128 v[202:205], v197 offset:36864
	ds_read_b128 v[206:209], v197 offset:37888
	ds_read_b128 v[210:213], v197 offset:38912
	ds_read_b128 v[222:225], v197 offset:39936
	global_load_lds_dwordx4 v[232:233], off
	v_lshl_add_u64 v[232:233], s[4:5], 0, v[164:165]
	s_mov_b32 m0, s31
	s_nop 0
	global_load_lds_dwordx4 v[232:233], off
	s_waitcnt vmcnt(8)
	s_waitcnt lgkmcnt(0)
	s_setprio 1
	s_barrier
	v_mfma_f32_16x16x32_bf16 v[150:153], v[74:77], v[178:181], v[150:153]
	v_mfma_f32_16x16x32_bf16 v[146:149], v[82:85], v[178:181], v[146:149]
	v_mfma_f32_16x16x32_bf16 v[102:105], v[74:77], v[186:189], v[102:105]
	v_mfma_f32_16x16x32_bf16 v[98:101], v[82:85], v[186:189], v[98:101]
	v_mfma_f32_16x16x32_bf16 v[158:161], v[74:77], v[202:205], v[158:161]
	v_mfma_f32_16x16x32_bf16 v[154:157], v[82:85], v[202:205], v[154:157]
	v_mfma_f32_16x16x32_bf16 v[110:113], v[74:77], v[210:213], v[110:113]
	v_mfma_f32_16x16x32_bf16 v[106:109], v[82:85], v[210:213], v[106:109]
	v_mfma_f32_16x16x32_bf16 v[150:153], v[78:81], v[182:185], v[150:153]
	v_mfma_f32_16x16x32_bf16 v[146:149], v[86:89], v[182:185], v[146:149]
	v_mfma_f32_16x16x32_bf16 v[102:105], v[78:81], v[198:201], v[102:105]
	v_mfma_f32_16x16x32_bf16 v[98:101], v[86:89], v[198:201], v[98:101]
	v_mfma_f32_16x16x32_bf16 v[158:161], v[78:81], v[206:209], v[158:161]
	v_mfma_f32_16x16x32_bf16 v[154:157], v[86:89], v[206:209], v[154:157]
	v_mfma_f32_16x16x32_bf16 v[110:113], v[78:81], v[222:225], v[110:113]
	v_mfma_f32_16x16x32_bf16 v[106:109], v[86:89], v[222:225], v[106:109]
	v_mfma_f32_16x16x32_bf16 v[142:145], v[114:117], v[178:181], v[142:145]
	v_mfma_f32_16x16x32_bf16 v[138:141], v[126:129], v[178:181], v[138:141]
	v_mfma_f32_16x16x32_bf16 v[94:97], v[114:117], v[186:189], v[94:97]
	v_mfma_f32_16x16x32_bf16 v[90:93], v[126:129], v[186:189], v[90:93]
	v_mfma_f32_16x16x32_bf16 v[134:137], v[114:117], v[202:205], v[134:137]
	v_mfma_f32_16x16x32_bf16 v[122:125], v[126:129], v[202:205], v[122:125]
	v_mfma_f32_16x16x32_bf16 v[70:73], v[114:117], v[210:213], v[70:73]
	v_mfma_f32_16x16x32_bf16 v[66:69], v[126:129], v[210:213], v[66:69]
	v_mfma_f32_16x16x32_bf16 v[142:145], v[118:121], v[182:185], v[142:145]
	v_mfma_f32_16x16x32_bf16 v[138:141], v[130:133], v[182:185], v[138:141]
	v_mfma_f32_16x16x32_bf16 v[94:97], v[118:121], v[198:201], v[94:97]
	v_mfma_f32_16x16x32_bf16 v[90:93], v[130:133], v[198:201], v[90:93]
	v_mfma_f32_16x16x32_bf16 v[134:137], v[118:121], v[206:209], v[134:137]
	v_mfma_f32_16x16x32_bf16 v[122:125], v[130:133], v[206:209], v[122:125]
	v_mfma_f32_16x16x32_bf16 v[70:73], v[118:121], v[222:225], v[70:73]
	v_mfma_f32_16x16x32_bf16 v[66:69], v[130:133], v[222:225], v[66:69]
	s_barrier
; #define PG8_STAGE(bufoff, gbase, voff) do { _Pragma("unroll") for (int _i = 0; _i < 2; ++_i) \
;         __builtin_amdgcn_global_load_lds((const unsigned*)((const char*)(gbase) + (voff)[_i]), (PG8_LAS unsigned*)(lds + (bufoff) + ldsw + _i * 8192), 16, 0, 0); } while (0)
; #define PG8_LDA(dst, b, h) do { _Pragma("unroll") for (int m = 0; m < 4; ++m) _Pragma("unroll") for (int k = 0; k < 2; ++k) dst[m][k] = *(const PG8_LAS bf16x8*)(lds + PG8_SA(b, h) + aoff + m * 2048 + k * 1024); } while (0)
; #define PG8_LDB(dst, b, h) do { _Pragma("unroll") for (int n = 0; n < 2; ++n) _Pragma("unroll") for (int k = 0; k < 2; ++k) dst[n][k] = *(const PG8_LAS bf16x8*)(lds + PG8_SB(b, h) + boff + n * 2048 + k * 1024); } while (0)
; #define PG8_MMA(ai, bj, At, Bt) do { __builtin_amdgcn_s_setprio(1); _Pragma("unroll") for (int m = 0; m < 4; ++m) _Pragma("unroll") for (int n = 0; n < 2; ++n) _Pragma("unroll") for (int k = 0; k < 2; ++k) \
;         acc[ai][bj][m][n] = __builtin_amdgcn_mfma_f32_16x16x32_bf16(Bt[n][k], At[m][k], acc[ai][bj][m][n], 0, 0, 0); __builtin_amdgcn_s_setprio(0); } while (0)
; template <class Epi, class Sched, bool ALIGN_EPI = false, bool SP2 = false>
; __device__ __forceinline__ void gemm_phase(PG8_LAS unsigned char* lds, const Gemm g, const Sched& S, const Epi& E, int wv) {
;     ...
;             PG8_LDB(B0, 0, 0); PG8_LDB(B1, 0, 1); PG8_SCHED; PG8_LDA(At, 0, 0); PG8_STAGE(PG8_SA(1, 1), a1 + hstepA, voffA);
;             PG8_WAIT_V(8); PG8_WAIT_L(0); PG8_BAR; PG8_MMA(0, 0, At, B0); PG8_MMA(0, 1, At, B1); PG8_BAR; PG8_SCHED;
;             PG8_LDA(At, 0, 1); PG8_STAGE(PG8_SB(0, 0), b2, voffB); PG8_STAGE(PG8_SB(0, 1), b2 + hstep, voffB); PG8_STAGE(PG8_SA(0, 0), a2, voffA);
;             PG8_WAIT_V(8); PG8_WAIT_L(0); PG8_BAR; PG8_MMA(1, 0, At, B0); PG8_MMA(1, 1, At, B1); PG8_BAR; PG8_SCHED;
;             PG8_LDB(B0, 1, 0); PG8_LDB(B1, 1, 1); PG8_SCHED; PG8_LDA(At, 1, 0); PG8_STAGE(PG8_SA(0, 1), a2 + hstepA, voffA);
;             PG8_WAIT_V(8); PG8_WAIT_L(0); PG8_BAR; PG8_MMA(0, 0, At, B0); PG8_MMA(0, 1, At, B1); PG8_BAR; PG8_SCHED;
;             PG8_LDA(At, 1, 1); PG8_STAGE(PG8_SB(1, 0), b3, voffB); PG8_STAGE(PG8_SB(1, 1), b3 + hstep, voffB); PG8_STAGE(PG8_SA(1, 0), a3, voffA);
;             PG8_WAIT_V(8); PG8_WAIT_L(0); PG8_BAR; PG8_MMA(1, 0, At, B0); PG8_MMA(1, 1, At, B1); PG8_BAR; PG8_SCHED;
;     ...
;         if constexpr (ALIGN_EPI) { if (wr == 0) PG8_BAR; }
	s_setprio 0
	s_add_i32 s4, s25, s17
	v_lshl_add_u64 v[192:193], v[192:193], 0, s[14:15]
	s_mov_b32 m0, s4
	ds_read_b128 v[178:181], v197 offset:49152
	ds_read_b128 v[182:185], v197 offset:50176
	ds_read_b128 v[186:189], v197 offset:51200
	ds_read_b128 v[198:201], v197 offset:52224
	ds_read_b128 v[202:205], v197 offset:53248
	ds_read_b128 v[206:209], v197 offset:54272
	ds_read_b128 v[210:213], v197 offset:55296
	ds_read_b128 v[222:225], v197 offset:56320
	global_load_lds_dwordx4 v[192:193], off
	s_add_i32 m0, s4, 0x2000
	s_add_u32 s4, s6, 0x18080
	v_lshl_add_u64 v[192:193], v[226:227], 0, s[14:15]
	s_addc_u32 s5, s7, 0
	s_add_i32 s6, s38, s17
	global_load_lds_dwordx4 v[192:193], off
	v_lshl_add_u64 v[192:193], s[4:5], 0, v[0:1]
	s_mov_b32 m0, s6
	s_nop 0
	global_load_lds_dwordx4 v[192:193], off
	v_lshl_add_u64 v[192:193], s[4:5], 0, v[162:163]
	s_add_i32 m0, s6, 0x2000
	s_nop 0
	global_load_lds_dwordx4 v[192:193], off
	v_lshl_add_u64 v[192:193], v[228:229], 0, s[14:15]
	s_mov_b32 m0, s53
	s_nop 0
	global_load_lds_dwordx4 v[192:193], off
	v_lshl_add_u64 v[192:193], v[230:231], 0, s[14:15]
	s_mov_b32 m0, s54
	s_nop 0
	global_load_lds_dwordx4 v[192:193], off
	s_waitcnt vmcnt(8)
	s_waitcnt lgkmcnt(0)
	s_setprio 1
	s_barrier
	v_mfma_f32_16x16x32_bf16 v[62:65], v[74:77], v[178:181], v[62:65]
	v_mfma_f32_16x16x32_bf16 v[58:61], v[82:85], v[178:181], v[58:61]
	v_mfma_f32_16x16x32_bf16 v[46:49], v[74:77], v[186:189], v[46:49]
	v_mfma_f32_16x16x32_bf16 v[42:45], v[82:85], v[186:189], v[42:45]
	v_mfma_f32_16x16x32_bf16 v[30:33], v[74:77], v[202:205], v[30:33]
	v_mfma_f32_16x16x32_bf16 v[26:29], v[82:85], v[202:205], v[26:29]
	v_mfma_f32_16x16x32_bf16 v[14:17], v[74:77], v[210:213], v[14:17]
	v_mfma_f32_16x16x32_bf16 v[10:13], v[82:85], v[210:213], v[10:13]
	v_mfma_f32_16x16x32_bf16 v[62:65], v[78:81], v[182:185], v[62:65]
	v_mfma_f32_16x16x32_bf16 v[58:61], v[86:89], v[182:185], v[58:61]
	v_mfma_f32_16x16x32_bf16 v[46:49], v[78:81], v[198:201], v[46:49]
	v_mfma_f32_16x16x32_bf16 v[42:45], v[86:89], v[198:201], v[42:45]
	v_mfma_f32_16x16x32_bf16 v[30:33], v[78:81], v[206:209], v[30:33]
	v_mfma_f32_16x16x32_bf16 v[26:29], v[86:89], v[206:209], v[26:29]
	v_mfma_f32_16x16x32_bf16 v[14:17], v[78:81], v[222:225], v[14:17]
	v_mfma_f32_16x16x32_bf16 v[10:13], v[86:89], v[222:225], v[10:13]
	v_mfma_f32_16x16x32_bf16 v[54:57], v[114:117], v[178:181], v[54:57]
	v_mfma_f32_16x16x32_bf16 v[50:53], v[126:129], v[178:181], v[50:53]
	v_mfma_f32_16x16x32_bf16 v[38:41], v[114:117], v[186:189], v[38:41]
	v_mfma_f32_16x16x32_bf16 v[34:37], v[126:129], v[186:189], v[34:37]
	v_mfma_f32_16x16x32_bf16 v[22:25], v[114:117], v[202:205], v[22:25]
	v_mfma_f32_16x16x32_bf16 v[18:21], v[126:129], v[202:205], v[18:21]
	v_mfma_f32_16x16x32_bf16 v[6:9], v[114:117], v[210:213], v[6:9]
	v_mfma_f32_16x16x32_bf16 v[2:5], v[126:129], v[210:213], v[2:5]
	v_mfma_f32_16x16x32_bf16 v[54:57], v[118:121], v[182:185], v[54:57]
	v_mfma_f32_16x16x32_bf16 v[50:53], v[130:133], v[182:185], v[50:53]
	v_mfma_f32_16x16x32_bf16 v[38:41], v[118:121], v[198:201], v[38:41]
	v_mfma_f32_16x16x32_bf16 v[34:37], v[130:133], v[198:201], v[34:37]
	v_mfma_f32_16x16x32_bf16 v[22:25], v[118:121], v[206:209], v[22:25]
	v_mfma_f32_16x16x32_bf16 v[18:21], v[130:133], v[206:209], v[18:21]
	v_mfma_f32_16x16x32_bf16 v[6:9], v[118:121], v[222:225], v[6:9]
	v_mfma_f32_16x16x32_bf16 v[2:5], v[130:133], v[222:225], v[2:5]
	s_barrier
	s_setprio 0
	s_add_i32 s26, s26, 2
	s_add_u32 s23, s23, 0x100
	s_addc_u32 s24, s24, 0
	s_cmp_gt_u32 s26, 3
	s_mov_b64 s[4:5], s[0:1]
	s_cbranch_scc0 .LBB0_438
	s_and_b64 vcc, exec, s[46:47]
	s_cbranch_vccz .LBB0_441
	s_barrier

; #define PG8_STAGE(bufoff, gbase, voff) do { _Pragma("unroll") for (int _i = 0; _i < 2; ++_i) \
;         __builtin_amdgcn_global_load_lds((const unsigned*)((const char*)(gbase) + (voff)[_i]), (PG8_LAS unsigned*)(lds + (bufoff) + ldsw + _i * 8192), 16, 0, 0); } while (0)
; #define PG8_LDA(dst, b, h) do { _Pragma("unroll") for (int m = 0; m < 4; ++m) _Pragma("unroll") for (int k = 0; k < 2; ++k) dst[m][k] = *(const PG8_LAS bf16x8*)(lds + PG8_SA(b, h) + aoff + m * 2048 + k * 1024); } while (0)
; #define PG8_LDB(dst, b, h) do { _Pragma("unroll") for (int n = 0; n < 2; ++n) _Pragma("unroll") for (int k = 0; k < 2; ++k) dst[n][k] = *(const PG8_LAS bf16x8*)(lds + PG8_SB(b, h) + boff + n * 2048 + k * 1024); } while (0)
; template <class Epi, class Sched, bool ALIGN_EPI = false, bool SP2 = false>
; __device__ __forceinline__ void gemm_phase(PG8_LAS unsigned char* lds, const Gemm g, const Sched& S, const Epi& E, int wv) {
;     ...
;         for (int t = 0; t < nt; t += 2) {
;             const bool last = (t == nt - 2);
;             const char* a1 = cA + (size_t)(t + 1) * kstep;
;             const char* a2 = last ? nA : cA + (size_t)(t + 2) * kstep; const char* b2 = last ? nB : cB + (size_t)(t + 2) * kstep;
;             const char* a3 = a2 + kstep; const char* b3 = b2 + kstep;
;             if (last && has_next) S.a_ready(nxt);
;             if constexpr (SP2) {
;             PG8_LDB(B0, 0, 0); PG8_LDB(B1, 0, 1); PG8_SCHED; PG8_LDA(At, 0, 0); PG8_STAGE(PG8_SA(1, 1), a1 + hstepA, voffA);
;             PG8_WAIT_V(8); PG8_WAIT_L(0); PG8_BAR; PG8_MMA(0, 0, At, B0); PG8_MMA(0, 1, At, B1); PG8_BAR; PG8_SCHED;
;             PG8_LDA(At, 0, 1); PG8_STAGE(PG8_SB(0, 0), b2, voffB); PG8_STAGE(PG8_SB(0, 1), b2 + hstep, voffB); PG8_STAGE(PG8_SA(0, 0), a2, voffA);
;             PG8_WAIT_V(8); PG8_WAIT_L(0); PG8_BAR; PG8_MMA(1, 0, At, B0); PG8_MMA(1, 1, At, B1); PG8_BAR; PG8_SCHED;
;             PG8_LDB(B0, 1, 0); PG8_LDB(B1, 1, 1); PG8_SCHED; PG8_LDA(At, 1, 0); PG8_STAGE(PG8_SA(0, 1), a2 + hstepA, voffA);
;             PG8_WAIT_V(8); PG8_WAIT_L(0); PG8_BAR; PG8_MMA(0, 0, At, B0); PG8_MMA(0, 1, At, B1); PG8_BAR; PG8_SCHED;
;             PG8_LDA(At, 1, 1); PG8_STAGE(PG8_SB(1, 0), b3, voffB); PG8_STAGE(PG8_SB(1, 1), b3 + hstep, voffB); PG8_STAGE(PG8_SA(1, 0), a3, voffA);
;             PG8_WAIT_V(8); PG8_WAIT_L(0); PG8_BAR; PG8_MMA(1, 0, At, B0); PG8_MMA(1, 1, At, B1); PG8_BAR; PG8_SCHED;
.LBB0_512:
	s_add_u32 s41, s30, s25
	s_addc_u32 s54, s31, 0
	s_add_u32 s50, s41, 0x100
	s_addc_u32 s51, s54, 0
	s_and_b64 s[48:49], s[46:47], exec
	s_cselect_b32 s51, s43, s51
	s_cselect_b32 s50, s42, s50
	s_add_u32 s25, s28, s25
	s_addc_u32 s48, s29, 0
	s_add_u32 s25, s25, 0x100
	s_addc_u32 s48, s48, 0
	s_add_i32 s74, 0, 0x10000
	s_and_b64 s[46:47], s[46:47], exec
	s_cselect_b32 s53, s16, s48
	s_cselect_b32 s52, s17, s25
	s_add_i32 s47, 0, 0x14000
	s_add_u32 s56, s41, 0x60080
	s_addc_u32 s57, s54, 0
	s_add_i32 s73, s74, s26
	s_add_i32 m0, s58, 0xc000
	s_add_i32 s76, s58, 0xe000
	s_add_i32 s70, s73, 0x2000
	v_add_u32_e32 v0, s74, v171
	s_add_u32 s54, s52, 0x10000
	ds_read_b128 v[130:133], v0
	ds_read_b128 v[134:137], v0 offset:1024
	ds_read_b128 v[138:141], v0 offset:2048
	ds_read_b128 v[142:145], v0 offset:3072
	v_add_u32_e32 v0, s47, v171
	s_addc_u32 s55, s53, 0
	s_add_i32 s72, s47, s26
	ds_read_b128 v[146:149], v0
	ds_read_b128 v[150:153], v0 offset:1024
	ds_read_b128 v[154:157], v0 offset:2048
	ds_read_b128 v[174:177], v0 offset:3072
	s_add_i32 s71, s72, 0x2000
	s_add_i32 s69, 0, 0x18000
	s_add_i32 s68, 0, 0x1c000
	s_add_u32 s48, s50, 0x60000
	s_addc_u32 s49, s51, 0
	s_add_i32 s41, s69, s26
	s_add_i32 s25, s41, 0x2000
	s_add_u32 s46, s52, 0x10080
	s_addc_u32 s47, s53, 0
	s_add_i32 s75, s68, s26
	s_add_i32 s74, s75, 0x2000
	v_lshl_add_u64 v[158:159], s[56:57], 0, v[166:167]
	ds_read_b128 v[178:181], v184
	ds_read_b128 v[186:189], v184 offset:1024
	ds_read_b128 v[190:193], v184 offset:2048
	ds_read_b128 v[196:199], v184 offset:3072
	ds_read_b128 v[200:203], v184 offset:4096
	ds_read_b128 v[204:207], v184 offset:5120
	ds_read_b128 v[208:211], v184 offset:6144
	ds_read_b128 v[222:225], v184 offset:7168
	global_load_lds_dwordx4 v[158:159], off
	v_lshl_add_u64 v[158:159], s[56:57], 0, v[162:163]
	s_mov_b32 m0, s76
	s_nop 0
	global_load_lds_dwordx4 v[158:159], off
	s_waitcnt vmcnt(8)
	s_waitcnt lgkmcnt(0)
	s_setprio 1
	s_barrier
	v_mfma_f32_16x16x32_bf16 v[126:129], v[130:133], v[178:181], v[126:129]
	v_mfma_f32_16x16x32_bf16 v[122:125], v[138:141], v[178:181], v[122:125]
	v_mfma_f32_16x16x32_bf16 v[110:113], v[130:133], v[190:193], v[110:113]
	v_mfma_f32_16x16x32_bf16 v[106:109], v[138:141], v[190:193], v[106:109]
	v_mfma_f32_16x16x32_bf16 v[94:97], v[130:133], v[200:203], v[94:97]
	v_mfma_f32_16x16x32_bf16 v[90:93], v[138:141], v[200:203], v[90:93]
	v_mfma_f32_16x16x32_bf16 v[78:81], v[130:133], v[208:211], v[78:81]
	v_mfma_f32_16x16x32_bf16 v[74:77], v[138:141], v[208:211], v[74:77]
	v_mfma_f32_16x16x32_bf16 v[126:129], v[134:137], v[186:189], v[126:129]
	v_mfma_f32_16x16x32_bf16 v[122:125], v[142:145], v[186:189], v[122:125]
	v_mfma_f32_16x16x32_bf16 v[110:113], v[134:137], v[196:199], v[110:113]
	v_mfma_f32_16x16x32_bf16 v[106:109], v[142:145], v[196:199], v[106:109]
	v_mfma_f32_16x16x32_bf16 v[94:97], v[134:137], v[204:207], v[94:97]
	v_mfma_f32_16x16x32_bf16 v[90:93], v[142:145], v[204:207], v[90:93]
	v_mfma_f32_16x16x32_bf16 v[78:81], v[134:137], v[222:225], v[78:81]
	v_mfma_f32_16x16x32_bf16 v[74:77], v[142:145], v[222:225], v[74:77]
	v_mfma_f32_16x16x32_bf16 v[118:121], v[146:149], v[178:181], v[118:121]
	v_mfma_f32_16x16x32_bf16 v[114:117], v[154:157], v[178:181], v[114:117]
	v_mfma_f32_16x16x32_bf16 v[102:105], v[146:149], v[190:193], v[102:105]
	v_mfma_f32_16x16x32_bf16 v[98:101], v[154:157], v[190:193], v[98:101]
	v_mfma_f32_16x16x32_bf16 v[86:89], v[146:149], v[200:203], v[86:89]
	v_mfma_f32_16x16x32_bf16 v[82:85], v[154:157], v[200:203], v[82:85]
	v_mfma_f32_16x16x32_bf16 v[70:73], v[146:149], v[208:211], v[70:73]
	v_mfma_f32_16x16x32_bf16 v[66:69], v[154:157], v[208:211], v[66:69]
	v_mfma_f32_16x16x32_bf16 v[118:121], v[150:153], v[186:189], v[118:121]
	v_mfma_f32_16x16x32_bf16 v[114:117], v[174:177], v[186:189], v[114:117]
	v_mfma_f32_16x16x32_bf16 v[102:105], v[150:153], v[196:199], v[102:105]
	v_mfma_f32_16x16x32_bf16 v[98:101], v[174:177], v[196:199], v[98:101]
	v_mfma_f32_16x16x32_bf16 v[86:89], v[150:153], v[204:207], v[86:89]
	v_mfma_f32_16x16x32_bf16 v[82:85], v[174:177], v[204:207], v[82:85]
	v_mfma_f32_16x16x32_bf16 v[70:73], v[150:153], v[222:225], v[70:73]
	v_mfma_f32_16x16x32_bf16 v[66:69], v[174:177], v[222:225], v[66:69]
	s_barrier
	s_setprio 0
	s_mov_b32 m0, s73
	v_lshl_add_u64 v[158:159], s[52:53], 0, v[164:165]
	ds_read_b128 v[178:181], v184 offset:16384
	ds_read_b128 v[186:189], v184 offset:17408
	ds_read_b128 v[190:193], v184 offset:18432
	ds_read_b128 v[196:199], v184 offset:19456
	ds_read_b128 v[200:203], v184 offset:20480
	ds_read_b128 v[204:207], v184 offset:21504
	ds_read_b128 v[208:211], v184 offset:22528
	ds_read_b128 v[222:225], v184 offset:23552
	global_load_lds_dwordx4 v[158:159], off
	v_lshl_add_u64 v[182:183], s[52:53], 0, v[160:161]
	s_mov_b32 m0, s70
	v_lshl_add_u64 v[212:213], s[54:55], 0, v[164:165]
	global_load_lds_dwordx4 v[182:183], off
	s_mov_b32 m0, s72
	v_lshl_add_u64 v[226:227], s[50:51], 0, v[162:163]
	global_load_lds_dwordx4 v[212:213], off
	v_lshl_add_u64 v[212:213], s[54:55], 0, v[160:161]
	s_mov_b32 m0, s71
	s_nop 0
	global_load_lds_dwordx4 v[212:213], off
	v_lshl_add_u64 v[212:213], s[50:51], 0, v[166:167]
	s_mov_b32 m0, s58
	s_nop 0
	global_load_lds_dwordx4 v[212:213], off
	s_mov_b32 m0, s59
	s_nop 0
	global_load_lds_dwordx4 v[226:227], off
	s_waitcnt vmcnt(8)
	s_waitcnt lgkmcnt(0)
	s_setprio 1
	s_barrier
; #define PG8_STAGE(bufoff, gbase, voff) do { _Pragma("unroll") for (int _i = 0; _i < 2; ++_i) \
;         __builtin_amdgcn_global_load_lds((const unsigned*)((const char*)(gbase) + (voff)[_i]), (PG8_LAS unsigned*)(lds + (bufoff) + ldsw + _i * 8192), 16, 0, 0); } while (0)
; #define PG8_LDA(dst, b, h) do { _Pragma("unroll") for (int m = 0; m < 4; ++m) _Pragma("unroll") for (int k = 0; k < 2; ++k) dst[m][k] = *(const PG8_LAS bf16x8*)(lds + PG8_SA(b, h) + aoff + m * 2048 + k * 1024); } while (0)
; #define PG8_LDB(dst, b, h) do { _Pragma("unroll") for (int n = 0; n < 2; ++n) _Pragma("unroll") for (int k = 0; k < 2; ++k) dst[n][k] = *(const PG8_LAS bf16x8*)(lds + PG8_SB(b, h) + boff + n * 2048 + k * 1024); } while (0)
; #define PG8_MMA(ai, bj, At, Bt) do { __builtin_amdgcn_s_setprio(1); _Pragma("unroll") for (int m = 0; m < 4; ++m) _Pragma("unroll") for (int n = 0; n < 2; ++n) _Pragma("unroll") for (int k = 0; k < 2; ++k) \
;         acc[ai][bj][m][n] = __builtin_amdgcn_mfma_f32_16x16x32_bf16(Bt[n][k], At[m][k], acc[ai][bj][m][n], 0, 0, 0); __builtin_amdgcn_s_setprio(0); } while (0)
; #define PG8_BAR __builtin_amdgcn_s_barrier()
; template <class Epi, class Sched, bool ALIGN_EPI = false, bool SP2 = false>
; __device__ __forceinline__ void gemm_phase(PG8_LAS unsigned char* lds, const Gemm g, const Sched& S, const Epi& E, int wv) {
;     ...
;             PG8_LDB(B0, 0, 0); PG8_LDB(B1, 0, 1); PG8_SCHED; PG8_LDA(At, 0, 0); PG8_STAGE(PG8_SA(1, 1), a1 + hstepA, voffA);
;             PG8_WAIT_V(8); PG8_WAIT_L(0); PG8_BAR; PG8_MMA(0, 0, At, B0); PG8_MMA(0, 1, At, B1); PG8_BAR; PG8_SCHED;
;             PG8_LDA(At, 0, 1); PG8_STAGE(PG8_SB(0, 0), b2, voffB); PG8_STAGE(PG8_SB(0, 1), b2 + hstep, voffB); PG8_STAGE(PG8_SA(0, 0), a2, voffA);
;             PG8_WAIT_V(8); PG8_WAIT_L(0); PG8_BAR; PG8_MMA(1, 0, At, B0); PG8_MMA(1, 1, At, B1); PG8_BAR; PG8_SCHED;
;             PG8_LDB(B0, 1, 0); PG8_LDB(B1, 1, 1); PG8_SCHED; PG8_LDA(At, 1, 0); PG8_STAGE(PG8_SA(0, 1), a2 + hstepA, voffA);
;             PG8_WAIT_V(8); PG8_WAIT_L(0); PG8_BAR; PG8_MMA(0, 0, At, B0); PG8_MMA(0, 1, At, B1); PG8_BAR; PG8_SCHED;
;             PG8_LDA(At, 1, 1); PG8_STAGE(PG8_SB(1, 0), b3, voffB); PG8_STAGE(PG8_SB(1, 1), b3 + hstep, voffB); PG8_STAGE(PG8_SA(1, 0), a3, voffA);
;             PG8_WAIT_V(8); PG8_WAIT_L(0); PG8_BAR; PG8_MMA(1, 0, At, B0); PG8_MMA(1, 1, At, B1); PG8_BAR; PG8_SCHED;
	v_mfma_f32_16x16x32_bf16 v[62:65], v[130:133], v[178:181], v[62:65]
	v_mfma_f32_16x16x32_bf16 v[58:61], v[138:141], v[178:181], v[58:61]
	v_mfma_f32_16x16x32_bf16 v[46:49], v[130:133], v[190:193], v[46:49]
	v_mfma_f32_16x16x32_bf16 v[42:45], v[138:141], v[190:193], v[42:45]
	v_mfma_f32_16x16x32_bf16 v[30:33], v[130:133], v[200:203], v[30:33]
	v_mfma_f32_16x16x32_bf16 v[26:29], v[138:141], v[200:203], v[26:29]
	v_mfma_f32_16x16x32_bf16 v[14:17], v[130:133], v[208:211], v[14:17]
	v_mfma_f32_16x16x32_bf16 v[10:13], v[138:141], v[208:211], v[10:13]
	v_mfma_f32_16x16x32_bf16 v[62:65], v[134:137], v[186:189], v[62:65]
	v_mfma_f32_16x16x32_bf16 v[58:61], v[142:145], v[186:189], v[58:61]
	v_mfma_f32_16x16x32_bf16 v[46:49], v[134:137], v[196:199], v[46:49]
	v_mfma_f32_16x16x32_bf16 v[42:45], v[142:145], v[196:199], v[42:45]
	v_mfma_f32_16x16x32_bf16 v[30:33], v[134:137], v[204:207], v[30:33]
	v_mfma_f32_16x16x32_bf16 v[26:29], v[142:145], v[204:207], v[26:29]
	v_mfma_f32_16x16x32_bf16 v[14:17], v[134:137], v[222:225], v[14:17]
	v_mfma_f32_16x16x32_bf16 v[10:13], v[142:145], v[222:225], v[10:13]
	v_mfma_f32_16x16x32_bf16 v[54:57], v[146:149], v[178:181], v[54:57]
	v_mfma_f32_16x16x32_bf16 v[50:53], v[154:157], v[178:181], v[50:53]
	v_mfma_f32_16x16x32_bf16 v[38:41], v[146:149], v[190:193], v[38:41]
	v_mfma_f32_16x16x32_bf16 v[34:37], v[154:157], v[190:193], v[34:37]
	v_mfma_f32_16x16x32_bf16 v[22:25], v[146:149], v[200:203], v[22:25]
	v_mfma_f32_16x16x32_bf16 v[18:21], v[154:157], v[200:203], v[18:21]
	v_mfma_f32_16x16x32_bf16 v[6:9], v[146:149], v[208:211], v[6:9]
	v_mfma_f32_16x16x32_bf16 v[2:5], v[154:157], v[208:211], v[2:5]
	v_mfma_f32_16x16x32_bf16 v[54:57], v[150:153], v[186:189], v[54:57]
	v_mfma_f32_16x16x32_bf16 v[50:53], v[174:177], v[186:189], v[50:53]
	v_mfma_f32_16x16x32_bf16 v[38:41], v[150:153], v[196:199], v[38:41]
	v_mfma_f32_16x16x32_bf16 v[34:37], v[174:177], v[196:199], v[34:37]
	v_mfma_f32_16x16x32_bf16 v[22:25], v[150:153], v[204:207], v[22:25]
	v_mfma_f32_16x16x32_bf16 v[18:21], v[174:177], v[204:207], v[18:21]
	v_mfma_f32_16x16x32_bf16 v[6:9], v[150:153], v[222:225], v[6:9]
	v_mfma_f32_16x16x32_bf16 v[2:5], v[174:177], v[222:225], v[2:5]
	s_barrier
	s_setprio 0
	v_add_u32_e32 v0, s69, v171
	ds_read_b128 v[130:133], v0
	ds_read_b128 v[134:137], v0 offset:1024
	ds_read_b128 v[138:141], v0 offset:2048
	ds_read_b128 v[142:145], v0 offset:3072
	v_add_u32_e32 v0, s68, v171
	ds_read_b128 v[146:149], v0
	ds_read_b128 v[150:153], v0 offset:1024
	ds_read_b128 v[154:157], v0 offset:2048
	ds_read_b128 v[174:177], v0 offset:3072
	s_mov_b32 m0, s60
	v_lshl_add_u64 v[228:229], s[48:49], 0, v[166:167]
	ds_read_b128 v[178:181], v184 offset:32768
	ds_read_b128 v[186:189], v184 offset:33792
	ds_read_b128 v[190:193], v184 offset:34816
	ds_read_b128 v[196:199], v184 offset:35840
	ds_read_b128 v[200:203], v184 offset:36864
	ds_read_b128 v[204:207], v184 offset:37888
	ds_read_b128 v[208:211], v184 offset:38912
	ds_read_b128 v[222:225], v184 offset:39936
	global_load_lds_dwordx4 v[228:229], off
	v_lshl_add_u64 v[228:229], s[48:49], 0, v[162:163]
	s_mov_b32 m0, s61
	s_nop 0
	global_load_lds_dwordx4 v[228:229], off
	s_waitcnt vmcnt(8)
	s_waitcnt lgkmcnt(0)
	s_setprio 1
	s_barrier
	v_mfma_f32_16x16x32_bf16 v[126:129], v[130:133], v[178:181], v[126:129]
	v_mfma_f32_16x16x32_bf16 v[122:125], v[138:141], v[178:181], v[122:125]
	v_mfma_f32_16x16x32_bf16 v[110:113], v[130:133], v[190:193], v[110:113]
	v_mfma_f32_16x16x32_bf16 v[106:109], v[138:141], v[190:193], v[106:109]
	v_mfma_f32_16x16x32_bf16 v[94:97], v[130:133], v[200:203], v[94:97]
	v_mfma_f32_16x16x32_bf16 v[90:93], v[138:141], v[200:203], v[90:93]
	v_mfma_f32_16x16x32_bf16 v[78:81], v[130:133], v[208:211], v[78:81]
	v_mfma_f32_16x16x32_bf16 v[74:77], v[138:141], v[208:211], v[74:77]
	v_mfma_f32_16x16x32_bf16 v[126:129], v[134:137], v[186:189], v[126:129]
	v_mfma_f32_16x16x32_bf16 v[122:125], v[142:145], v[186:189], v[122:125]
	v_mfma_f32_16x16x32_bf16 v[110:113], v[134:137], v[196:199], v[110:113]
	v_mfma_f32_16x16x32_bf16 v[106:109], v[142:145], v[196:199], v[106:109]
	v_mfma_f32_16x16x32_bf16 v[94:97], v[134:137], v[204:207], v[94:97]
	v_mfma_f32_16x16x32_bf16 v[90:93], v[142:145], v[204:207], v[90:93]
	v_mfma_f32_16x16x32_bf16 v[78:81], v[134:137], v[222:225], v[78:81]
	v_mfma_f32_16x16x32_bf16 v[74:77], v[142:145], v[222:225], v[74:77]
	v_mfma_f32_16x16x32_bf16 v[118:121], v[146:149], v[178:181], v[118:121]
	v_mfma_f32_16x16x32_bf16 v[114:117], v[154:157], v[178:181], v[114:117]
	v_mfma_f32_16x16x32_bf16 v[102:105], v[146:149], v[190:193], v[102:105]
	v_mfma_f32_16x16x32_bf16 v[98:101], v[154:157], v[190:193], v[98:101]
	v_mfma_f32_16x16x32_bf16 v[86:89], v[146:149], v[200:203], v[86:89]
	v_mfma_f32_16x16x32_bf16 v[82:85], v[154:157], v[200:203], v[82:85]
	v_mfma_f32_16x16x32_bf16 v[70:73], v[146:149], v[208:211], v[70:73]
	v_mfma_f32_16x16x32_bf16 v[66:69], v[154:157], v[208:211], v[66:69]
	v_mfma_f32_16x16x32_bf16 v[118:121], v[150:153], v[186:189], v[118:121]
	v_mfma_f32_16x16x32_bf16 v[114:117], v[174:177], v[186:189], v[114:117]
	v_mfma_f32_16x16x32_bf16 v[102:105], v[150:153], v[196:199], v[102:105]
	v_mfma_f32_16x16x32_bf16 v[98:101], v[174:177], v[196:199], v[98:101]
	v_mfma_f32_16x16x32_bf16 v[86:89], v[150:153], v[204:207], v[86:89]
	v_mfma_f32_16x16x32_bf16 v[82:85], v[174:177], v[204:207], v[82:85]
	v_mfma_f32_16x16x32_bf16 v[70:73], v[150:153], v[222:225], v[70:73]
	v_mfma_f32_16x16x32_bf16 v[66:69], v[174:177], v[222:225], v[66:69]
	s_barrier
; #define PG8_STAGE(bufoff, gbase, voff) do { _Pragma("unroll") for (int _i = 0; _i < 2; ++_i) \
;         __builtin_amdgcn_global_load_lds((const unsigned*)((const char*)(gbase) + (voff)[_i]), (PG8_LAS unsigned*)(lds + (bufoff) + ldsw + _i * 8192), 16, 0, 0); } while (0)
; #define PG8_LDA(dst, b, h) do { _Pragma("unroll") for (int m = 0; m < 4; ++m) _Pragma("unroll") for (int k = 0; k < 2; ++k) dst[m][k] = *(const PG8_LAS bf16x8*)(lds + PG8_SA(b, h) + aoff + m * 2048 + k * 1024); } while (0)
; #define PG8_LDB(dst, b, h) do { _Pragma("unroll") for (int n = 0; n < 2; ++n) _Pragma("unroll") for (int k = 0; k < 2; ++k) dst[n][k] = *(const PG8_LAS bf16x8*)(lds + PG8_SB(b, h) + boff + n * 2048 + k * 1024); } while (0)
; #define PG8_MMA(ai, bj, At, Bt) do { __builtin_amdgcn_s_setprio(1); _Pragma("unroll") for (int m = 0; m < 4; ++m) _Pragma("unroll") for (int n = 0; n < 2; ++n) _Pragma("unroll") for (int k = 0; k < 2; ++k) \
;         acc[ai][bj][m][n] = __builtin_amdgcn_mfma_f32_16x16x32_bf16(Bt[n][k], At[m][k], acc[ai][bj][m][n], 0, 0, 0); __builtin_amdgcn_s_setprio(0); } while (0)
; template <class Epi, class Sched, bool ALIGN_EPI = false, bool SP2 = false>
; __device__ __forceinline__ void gemm_phase(PG8_LAS unsigned char* lds, const Gemm g, const Sched& S, const Epi& E, int wv) {
;     ...
;             PG8_LDB(B0, 0, 0); PG8_LDB(B1, 0, 1); PG8_SCHED; PG8_LDA(At, 0, 0); PG8_STAGE(PG8_SA(1, 1), a1 + hstepA, voffA);
;             PG8_WAIT_V(8); PG8_WAIT_L(0); PG8_BAR; PG8_MMA(0, 0, At, B0); PG8_MMA(0, 1, At, B1); PG8_BAR; PG8_SCHED;
;             PG8_LDA(At, 0, 1); PG8_STAGE(PG8_SB(0, 0), b2, voffB); PG8_STAGE(PG8_SB(0, 1), b2 + hstep, voffB); PG8_STAGE(PG8_SA(0, 0), a2, voffA);
;             PG8_WAIT_V(8); PG8_WAIT_L(0); PG8_BAR; PG8_MMA(1, 0, At, B0); PG8_MMA(1, 1, At, B1); PG8_BAR; PG8_SCHED;
;             PG8_LDB(B0, 1, 0); PG8_LDB(B1, 1, 1); PG8_SCHED; PG8_LDA(At, 1, 0); PG8_STAGE(PG8_SA(0, 1), a2 + hstepA, voffA);
;             PG8_WAIT_V(8); PG8_WAIT_L(0); PG8_BAR; PG8_MMA(0, 0, At, B0); PG8_MMA(0, 1, At, B1); PG8_BAR; PG8_SCHED;
;             PG8_LDA(At, 1, 1); PG8_STAGE(PG8_SB(1, 0), b3, voffB); PG8_STAGE(PG8_SB(1, 1), b3 + hstep, voffB); PG8_STAGE(PG8_SA(1, 0), a3, voffA);
;             PG8_WAIT_V(8); PG8_WAIT_L(0); PG8_BAR; PG8_MMA(1, 0, At, B0); PG8_MMA(1, 1, At, B1); PG8_BAR; PG8_SCHED;
;     ...
;         if constexpr (ALIGN_EPI) { if (wr == 0) PG8_BAR; }
	s_setprio 0
	s_mov_b32 m0, s41
	v_lshl_add_u64 v[158:159], v[158:159], 0, s[14:15]
	ds_read_b128 v[178:181], v184 offset:49152
	ds_read_b128 v[186:189], v184 offset:50176
	ds_read_b128 v[190:193], v184 offset:51200
	ds_read_b128 v[196:199], v184 offset:52224
	ds_read_b128 v[200:203], v184 offset:53248
	ds_read_b128 v[204:207], v184 offset:54272
	ds_read_b128 v[208:211], v184 offset:55296
	ds_read_b128 v[222:225], v184 offset:56320
	global_load_lds_dwordx4 v[158:159], off
	v_lshl_add_u64 v[158:159], v[182:183], 0, s[14:15]
	s_mov_b32 m0, s25
	s_nop 0
	global_load_lds_dwordx4 v[158:159], off
	v_lshl_add_u64 v[158:159], s[46:47], 0, v[164:165]
	s_mov_b32 m0, s75
	s_nop 0
	global_load_lds_dwordx4 v[158:159], off
	v_lshl_add_u64 v[158:159], s[46:47], 0, v[160:161]
	s_mov_b32 m0, s74
	s_nop 0
	global_load_lds_dwordx4 v[158:159], off
	v_lshl_add_u64 v[158:159], v[212:213], 0, s[14:15]
	s_mov_b32 m0, s63
	s_nop 0
	global_load_lds_dwordx4 v[158:159], off
	v_lshl_add_u64 v[158:159], v[226:227], 0, s[14:15]
	s_mov_b32 m0, s64
	s_nop 0
	global_load_lds_dwordx4 v[158:159], off
	s_waitcnt vmcnt(8)
	s_waitcnt lgkmcnt(0)
	s_setprio 1
	s_barrier
	v_mfma_f32_16x16x32_bf16 v[62:65], v[130:133], v[178:181], v[62:65]
	v_mfma_f32_16x16x32_bf16 v[58:61], v[138:141], v[178:181], v[58:61]
	v_mfma_f32_16x16x32_bf16 v[46:49], v[130:133], v[190:193], v[46:49]
	v_mfma_f32_16x16x32_bf16 v[42:45], v[138:141], v[190:193], v[42:45]
	v_mfma_f32_16x16x32_bf16 v[30:33], v[130:133], v[200:203], v[30:33]
	v_mfma_f32_16x16x32_bf16 v[26:29], v[138:141], v[200:203], v[26:29]
	v_mfma_f32_16x16x32_bf16 v[14:17], v[130:133], v[208:211], v[14:17]
	v_mfma_f32_16x16x32_bf16 v[10:13], v[138:141], v[208:211], v[10:13]
	v_mfma_f32_16x16x32_bf16 v[62:65], v[134:137], v[186:189], v[62:65]
	v_mfma_f32_16x16x32_bf16 v[58:61], v[142:145], v[186:189], v[58:61]
	v_mfma_f32_16x16x32_bf16 v[46:49], v[134:137], v[196:199], v[46:49]
	v_mfma_f32_16x16x32_bf16 v[42:45], v[142:145], v[196:199], v[42:45]
	v_mfma_f32_16x16x32_bf16 v[30:33], v[134:137], v[204:207], v[30:33]
	v_mfma_f32_16x16x32_bf16 v[26:29], v[142:145], v[204:207], v[26:29]
	v_mfma_f32_16x16x32_bf16 v[14:17], v[134:137], v[222:225], v[14:17]
	v_mfma_f32_16x16x32_bf16 v[10:13], v[142:145], v[222:225], v[10:13]
	v_mfma_f32_16x16x32_bf16 v[54:57], v[146:149], v[178:181], v[54:57]
	v_mfma_f32_16x16x32_bf16 v[50:53], v[154:157], v[178:181], v[50:53]
	v_mfma_f32_16x16x32_bf16 v[38:41], v[146:149], v[190:193], v[38:41]
	v_mfma_f32_16x16x32_bf16 v[34:37], v[154:157], v[190:193], v[34:37]
	v_mfma_f32_16x16x32_bf16 v[22:25], v[146:149], v[200:203], v[22:25]
	v_mfma_f32_16x16x32_bf16 v[18:21], v[154:157], v[200:203], v[18:21]
	v_mfma_f32_16x16x32_bf16 v[6:9], v[146:149], v[208:211], v[6:9]
	v_mfma_f32_16x16x32_bf16 v[2:5], v[154:157], v[208:211], v[2:5]
	v_mfma_f32_16x16x32_bf16 v[54:57], v[150:153], v[186:189], v[54:57]
	v_mfma_f32_16x16x32_bf16 v[50:53], v[174:177], v[186:189], v[50:53]
	v_mfma_f32_16x16x32_bf16 v[38:41], v[150:153], v[196:199], v[38:41]
	v_mfma_f32_16x16x32_bf16 v[34:37], v[174:177], v[196:199], v[34:37]
	v_mfma_f32_16x16x32_bf16 v[22:25], v[150:153], v[204:207], v[22:25]
	v_mfma_f32_16x16x32_bf16 v[18:21], v[174:177], v[204:207], v[18:21]
	v_mfma_f32_16x16x32_bf16 v[6:9], v[150:153], v[222:225], v[6:9]
	v_mfma_f32_16x16x32_bf16 v[2:5], v[174:177], v[222:225], v[2:5]
	s_barrier
	s_setprio 0
	s_movk_i32 s25, 0x100
	s_andn2_b64 vcc, exec, s[0:1]
	s_mov_b64 s[46:47], -1
	s_mov_b64 s[0:1], 0
	s_cbranch_vccz .LBB0_512
	s_and_b64 vcc, exec, s[8:9]
	s_cbranch_vccz .LBB0_515
	s_barrier

; #define PG8_STAGE(bufoff, gbase, voff) do { _Pragma("unroll") for (int _i = 0; _i < 2; ++_i) \
;         __builtin_amdgcn_global_load_lds((const unsigned*)((const char*)(gbase) + (voff)[_i]), (PG8_LAS unsigned*)(lds + (bufoff) + ldsw + _i * 8192), 16, 0, 0); } while (0)
; #define PG8_LDA(dst, b, h) do { _Pragma("unroll") for (int m = 0; m < 4; ++m) _Pragma("unroll") for (int k = 0; k < 2; ++k) dst[m][k] = *(const PG8_LAS bf16x8*)(lds + PG8_SA(b, h) + aoff + m * 2048 + k * 1024); } while (0)
; #define PG8_LDB(dst, b, h) do { _Pragma("unroll") for (int n = 0; n < 2; ++n) _Pragma("unroll") for (int k = 0; k < 2; ++k) dst[n][k] = *(const PG8_LAS bf16x8*)(lds + PG8_SB(b, h) + boff + n * 2048 + k * 1024); } while (0)
; template <class Epi, class Sched, bool ALIGN_EPI = false, bool SP2 = false>
; __device__ __forceinline__ void gemm_phase(PG8_LAS unsigned char* lds, const Gemm g, const Sched& S, const Epi& E, int wv) {
;     ...
;         for (int t = 0; t < nt; t += 2) {
;             const bool last = (t == nt - 2);
;             const char* a1 = cA + (size_t)(t + 1) * kstep;
;             const char* a2 = last ? nA : cA + (size_t)(t + 2) * kstep; const char* b2 = last ? nB : cB + (size_t)(t + 2) * kstep;
;             const char* a3 = a2 + kstep; const char* b3 = b2 + kstep;
;             if (last && has_next) S.a_ready(nxt);
;             if constexpr (SP2) {
;             PG8_LDB(B0, 0, 0); PG8_LDB(B1, 0, 1); PG8_SCHED; PG8_LDA(At, 0, 0); PG8_STAGE(PG8_SA(1, 1), a1 + hstepA, voffA);
;             PG8_WAIT_V(8); PG8_WAIT_L(0); PG8_BAR; PG8_MMA(0, 0, At, B0); PG8_MMA(0, 1, At, B1); PG8_BAR; PG8_SCHED;
;             PG8_LDA(At, 0, 1); PG8_STAGE(PG8_SB(0, 0), b2, voffB); PG8_STAGE(PG8_SB(0, 1), b2 + hstep, voffB); PG8_STAGE(PG8_SA(0, 0), a2, voffA);
;             PG8_WAIT_V(8); PG8_WAIT_L(0); PG8_BAR; PG8_MMA(1, 0, At, B0); PG8_MMA(1, 1, At, B1); PG8_BAR; PG8_SCHED;
;             PG8_LDB(B0, 1, 0); PG8_LDB(B1, 1, 1); PG8_SCHED; PG8_LDA(At, 1, 0); PG8_STAGE(PG8_SA(0, 1), a2 + hstepA, voffA);
;             PG8_WAIT_V(8); PG8_WAIT_L(0); PG8_BAR; PG8_MMA(0, 0, At, B0); PG8_MMA(0, 1, At, B1); PG8_BAR; PG8_SCHED;
;             PG8_LDA(At, 1, 1); PG8_STAGE(PG8_SB(1, 0), b3, voffB); PG8_STAGE(PG8_SB(1, 1), b3 + hstep, voffB); PG8_STAGE(PG8_SA(1, 0), a3, voffA);
;             PG8_WAIT_V(8); PG8_WAIT_L(0); PG8_BAR; PG8_MMA(1, 0, At, B0); PG8_MMA(1, 1, At, B1); PG8_BAR; PG8_SCHED;
.LBB0_995:
	s_add_u32 s25, s36, 0xfffe0080
	s_addc_u32 s38, s37, -1
	s_add_i32 s53, 0, 0x10000
	s_cmp_eq_u32 s52, 4
	s_cselect_b32 s41, s11, s38
	s_cselect_b32 s40, s16, s25
	s_cselect_b32 s39, s17, s51
	s_cselect_b32 s38, s29, s50
	s_add_i32 s25, 0, 0x14000
	v_add_u32_e32 v156, s53, v141
	v_add_u32_e32 v172, s25, v141
	ds_read_b128 v[144:147], v156
	ds_read_b128 v[148:151], v156 offset:1024
	ds_read_b128 v[152:155], v156 offset:2048
	ds_read_b128 v[156:159], v156 offset:3072
	ds_read_b128 v[160:163], v172
	ds_read_b128 v[164:167], v172 offset:1024
	ds_read_b128 v[168:171], v172 offset:2048
	ds_read_b128 v[172:175], v172 offset:3072
	v_lshl_add_u64 v[192:193], s[36:37], 0, v[136:137]
	s_add_i32 m0, s26, 0xc000
	ds_read_b128 v[176:179], v143
	ds_read_b128 v[180:183], v143 offset:1024
	ds_read_b128 v[184:187], v143 offset:2048
	ds_read_b128 v[188:191], v143 offset:3072
	ds_read_b128 v[196:199], v143 offset:4096
	ds_read_b128 v[200:203], v143 offset:5120
	ds_read_b128 v[204:207], v143 offset:6144
	ds_read_b128 v[208:211], v143 offset:7168
	global_load_lds_dwordx4 v[192:193], off
	v_lshl_add_u64 v[192:193], s[36:37], 0, v[138:139]
	s_add_i32 m0, s26, 0xe000
	s_nop 0
	global_load_lds_dwordx4 v[192:193], off
	s_waitcnt vmcnt(8)
	s_waitcnt lgkmcnt(0)
	s_setprio 1
	s_barrier
	v_mfma_f32_16x16x32_bf16 v[126:129], v[144:147], v[176:179], v[126:129]
	v_mfma_f32_16x16x32_bf16 v[122:125], v[152:155], v[176:179], v[122:125]
	v_mfma_f32_16x16x32_bf16 v[118:121], v[144:147], v[184:187], v[118:121]
	v_mfma_f32_16x16x32_bf16 v[114:117], v[152:155], v[184:187], v[114:117]
	v_mfma_f32_16x16x32_bf16 v[102:105], v[144:147], v[196:199], v[102:105]
	v_mfma_f32_16x16x32_bf16 v[98:101], v[152:155], v[196:199], v[98:101]
	v_mfma_f32_16x16x32_bf16 v[86:89], v[144:147], v[204:207], v[86:89]
	v_mfma_f32_16x16x32_bf16 v[82:85], v[152:155], v[204:207], v[82:85]
	v_mfma_f32_16x16x32_bf16 v[126:129], v[148:151], v[180:183], v[126:129]
	v_mfma_f32_16x16x32_bf16 v[122:125], v[156:159], v[180:183], v[122:125]
	v_mfma_f32_16x16x32_bf16 v[118:121], v[148:151], v[188:191], v[118:121]
	v_mfma_f32_16x16x32_bf16 v[114:117], v[156:159], v[188:191], v[114:117]
	v_mfma_f32_16x16x32_bf16 v[102:105], v[148:151], v[200:203], v[102:105]
	v_mfma_f32_16x16x32_bf16 v[98:101], v[156:159], v[200:203], v[98:101]
	v_mfma_f32_16x16x32_bf16 v[86:89], v[148:151], v[208:211], v[86:89]
	v_mfma_f32_16x16x32_bf16 v[82:85], v[156:159], v[208:211], v[82:85]
	v_mfma_f32_16x16x32_bf16 v[110:113], v[160:163], v[176:179], v[110:113]
	v_mfma_f32_16x16x32_bf16 v[106:109], v[168:171], v[176:179], v[106:109]
	v_mfma_f32_16x16x32_bf16 v[94:97], v[160:163], v[184:187], v[94:97]
	v_mfma_f32_16x16x32_bf16 v[90:93], v[168:171], v[184:187], v[90:93]
	v_mfma_f32_16x16x32_bf16 v[78:81], v[160:163], v[196:199], v[78:81]
	v_mfma_f32_16x16x32_bf16 v[74:77], v[168:171], v[196:199], v[74:77]
	v_mfma_f32_16x16x32_bf16 v[70:73], v[160:163], v[204:207], v[70:73]
	v_mfma_f32_16x16x32_bf16 v[66:69], v[168:171], v[204:207], v[66:69]
	v_mfma_f32_16x16x32_bf16 v[110:113], v[164:167], v[180:183], v[110:113]
	v_mfma_f32_16x16x32_bf16 v[106:109], v[172:175], v[180:183], v[106:109]
	v_mfma_f32_16x16x32_bf16 v[94:97], v[164:167], v[188:191], v[94:97]
	v_mfma_f32_16x16x32_bf16 v[90:93], v[172:175], v[188:191], v[90:93]
	v_mfma_f32_16x16x32_bf16 v[78:81], v[164:167], v[200:203], v[78:81]
	v_mfma_f32_16x16x32_bf16 v[74:77], v[172:175], v[200:203], v[74:77]
	v_mfma_f32_16x16x32_bf16 v[70:73], v[164:167], v[208:211], v[70:73]
	v_mfma_f32_16x16x32_bf16 v[66:69], v[172:175], v[208:211], v[66:69]
	s_barrier
	s_setprio 0
	s_add_i32 s53, s53, s24
	v_lshl_add_u64 v[192:193], s[38:39], 0, v[0:1]
	s_mov_b32 m0, s53
	ds_read_b128 v[176:179], v143 offset:16384
	ds_read_b128 v[180:183], v143 offset:17408
	ds_read_b128 v[184:187], v143 offset:18432
	ds_read_b128 v[188:191], v143 offset:19456
	ds_read_b128 v[196:199], v143 offset:20480
	ds_read_b128 v[200:203], v143 offset:21504
	ds_read_b128 v[204:207], v143 offset:22528
	ds_read_b128 v[208:211], v143 offset:23552
	global_load_lds_dwordx4 v[192:193], off
	s_add_i32 m0, s53, 0x2000
	s_add_u32 s54, s38, 0x20000
	v_lshl_add_u64 v[212:213], s[38:39], 0, v[130:131]
	s_addc_u32 s55, s39, 0
	s_add_i32 s25, s25, s24
	global_load_lds_dwordx4 v[212:213], off
	v_lshl_add_u64 v[222:223], s[54:55], 0, v[0:1]
	s_mov_b32 m0, s25
	v_lshl_add_u64 v[224:225], s[40:41], 0, v[132:133]
	global_load_lds_dwordx4 v[222:223], off
	v_lshl_add_u64 v[222:223], s[54:55], 0, v[130:131]
	s_add_i32 m0, s25, 0x2000
	s_nop 0
	global_load_lds_dwordx4 v[222:223], off
	v_lshl_add_u64 v[222:223], s[40:41], 0, v[134:135]
	s_mov_b32 m0, s26
	s_nop 0
	global_load_lds_dwordx4 v[222:223], off
	s_mov_b32 m0, s42
	s_nop 0
	global_load_lds_dwordx4 v[224:225], off
	s_waitcnt vmcnt(8)
	s_waitcnt lgkmcnt(0)
	s_setprio 1
	s_barrier
; #define PG8_STAGE(bufoff, gbase, voff) do { _Pragma("unroll") for (int _i = 0; _i < 2; ++_i) \
;         __builtin_amdgcn_global_load_lds((const unsigned*)((const char*)(gbase) + (voff)[_i]), (PG8_LAS unsigned*)(lds + (bufoff) + ldsw + _i * 8192), 16, 0, 0); } while (0)
; #define PG8_LDA(dst, b, h) do { _Pragma("unroll") for (int m = 0; m < 4; ++m) _Pragma("unroll") for (int k = 0; k < 2; ++k) dst[m][k] = *(const PG8_LAS bf16x8*)(lds + PG8_SA(b, h) + aoff + m * 2048 + k * 1024); } while (0)
; #define PG8_LDB(dst, b, h) do { _Pragma("unroll") for (int n = 0; n < 2; ++n) _Pragma("unroll") for (int k = 0; k < 2; ++k) dst[n][k] = *(const PG8_LAS bf16x8*)(lds + PG8_SB(b, h) + boff + n * 2048 + k * 1024); } while (0)
; #define PG8_MMA(ai, bj, At, Bt) do { __builtin_amdgcn_s_setprio(1); _Pragma("unroll") for (int m = 0; m < 4; ++m) _Pragma("unroll") for (int n = 0; n < 2; ++n) _Pragma("unroll") for (int k = 0; k < 2; ++k) \
;         acc[ai][bj][m][n] = __builtin_amdgcn_mfma_f32_16x16x32_bf16(Bt[n][k], At[m][k], acc[ai][bj][m][n], 0, 0, 0); __builtin_amdgcn_s_setprio(0); } while (0)
; #define PG8_BAR __builtin_amdgcn_s_barrier()
; template <class Epi, class Sched, bool ALIGN_EPI = false, bool SP2 = false>
; __device__ __forceinline__ void gemm_phase(PG8_LAS unsigned char* lds, const Gemm g, const Sched& S, const Epi& E, int wv) {
;     ...
;             PG8_LDB(B0, 0, 0); PG8_LDB(B1, 0, 1); PG8_SCHED; PG8_LDA(At, 0, 0); PG8_STAGE(PG8_SA(1, 1), a1 + hstepA, voffA);
;             PG8_WAIT_V(8); PG8_WAIT_L(0); PG8_BAR; PG8_MMA(0, 0, At, B0); PG8_MMA(0, 1, At, B1); PG8_BAR; PG8_SCHED;
;             PG8_LDA(At, 0, 1); PG8_STAGE(PG8_SB(0, 0), b2, voffB); PG8_STAGE(PG8_SB(0, 1), b2 + hstep, voffB); PG8_STAGE(PG8_SA(0, 0), a2, voffA);
;             PG8_WAIT_V(8); PG8_WAIT_L(0); PG8_BAR; PG8_MMA(1, 0, At, B0); PG8_MMA(1, 1, At, B1); PG8_BAR; PG8_SCHED;
;             PG8_LDB(B0, 1, 0); PG8_LDB(B1, 1, 1); PG8_SCHED; PG8_LDA(At, 1, 0); PG8_STAGE(PG8_SA(0, 1), a2 + hstepA, voffA);
;             PG8_WAIT_V(8); PG8_WAIT_L(0); PG8_BAR; PG8_MMA(0, 0, At, B0); PG8_MMA(0, 1, At, B1); PG8_BAR; PG8_SCHED;
;             PG8_LDA(At, 1, 1); PG8_STAGE(PG8_SB(1, 0), b3, voffB); PG8_STAGE(PG8_SB(1, 1), b3 + hstep, voffB); PG8_STAGE(PG8_SA(1, 0), a3, voffA);
;             PG8_WAIT_V(8); PG8_WAIT_L(0); PG8_BAR; PG8_MMA(1, 0, At, B0); PG8_MMA(1, 1, At, B1); PG8_BAR; PG8_SCHED;
	v_mfma_f32_16x16x32_bf16 v[62:65], v[144:147], v[176:179], v[62:65]
	v_mfma_f32_16x16x32_bf16 v[58:61], v[152:155], v[176:179], v[58:61]
	v_mfma_f32_16x16x32_bf16 v[54:57], v[144:147], v[184:187], v[54:57]
	v_mfma_f32_16x16x32_bf16 v[50:53], v[152:155], v[184:187], v[50:53]
	v_mfma_f32_16x16x32_bf16 v[38:41], v[144:147], v[196:199], v[38:41]
	v_mfma_f32_16x16x32_bf16 v[34:37], v[152:155], v[196:199], v[34:37]
	v_mfma_f32_16x16x32_bf16 v[22:25], v[144:147], v[204:207], v[22:25]
	v_mfma_f32_16x16x32_bf16 v[18:21], v[152:155], v[204:207], v[18:21]
	v_mfma_f32_16x16x32_bf16 v[62:65], v[148:151], v[180:183], v[62:65]
	v_mfma_f32_16x16x32_bf16 v[58:61], v[156:159], v[180:183], v[58:61]
	v_mfma_f32_16x16x32_bf16 v[54:57], v[148:151], v[188:191], v[54:57]
	v_mfma_f32_16x16x32_bf16 v[50:53], v[156:159], v[188:191], v[50:53]
	v_mfma_f32_16x16x32_bf16 v[38:41], v[148:151], v[200:203], v[38:41]
	v_mfma_f32_16x16x32_bf16 v[34:37], v[156:159], v[200:203], v[34:37]
	v_mfma_f32_16x16x32_bf16 v[22:25], v[148:151], v[208:211], v[22:25]
	v_mfma_f32_16x16x32_bf16 v[18:21], v[156:159], v[208:211], v[18:21]
	v_mfma_f32_16x16x32_bf16 v[46:49], v[160:163], v[176:179], v[46:49]
	v_mfma_f32_16x16x32_bf16 v[42:45], v[168:171], v[176:179], v[42:45]
	v_mfma_f32_16x16x32_bf16 v[30:33], v[160:163], v[184:187], v[30:33]
	v_mfma_f32_16x16x32_bf16 v[26:29], v[168:171], v[184:187], v[26:29]
	v_mfma_f32_16x16x32_bf16 v[14:17], v[160:163], v[196:199], v[14:17]
	v_mfma_f32_16x16x32_bf16 v[10:13], v[168:171], v[196:199], v[10:13]
	v_mfma_f32_16x16x32_bf16 v[6:9], v[160:163], v[204:207], v[6:9]
	v_mfma_f32_16x16x32_bf16 v[2:5], v[168:171], v[204:207], v[2:5]
	v_mfma_f32_16x16x32_bf16 v[46:49], v[164:167], v[180:183], v[46:49]
	v_mfma_f32_16x16x32_bf16 v[42:45], v[172:175], v[180:183], v[42:45]
	v_mfma_f32_16x16x32_bf16 v[30:33], v[164:167], v[188:191], v[30:33]
	v_mfma_f32_16x16x32_bf16 v[26:29], v[172:175], v[188:191], v[26:29]
	v_mfma_f32_16x16x32_bf16 v[14:17], v[164:167], v[200:203], v[14:17]
	v_mfma_f32_16x16x32_bf16 v[10:13], v[172:175], v[200:203], v[10:13]
	v_mfma_f32_16x16x32_bf16 v[6:9], v[164:167], v[208:211], v[6:9]
	v_mfma_f32_16x16x32_bf16 v[2:5], v[172:175], v[208:211], v[2:5]
	s_barrier
	s_setprio 0
	s_add_i32 s25, 0, 0x18000
	s_add_i32 s53, 0, 0x1c000
	v_add_u32_e32 v156, s25, v141
	v_add_u32_e32 v172, s53, v141
	ds_read_b128 v[144:147], v156
	ds_read_b128 v[148:151], v156 offset:1024
	ds_read_b128 v[152:155], v156 offset:2048
	ds_read_b128 v[156:159], v156 offset:3072
	ds_read_b128 v[160:163], v172
	ds_read_b128 v[164:167], v172 offset:1024
	ds_read_b128 v[168:171], v172 offset:2048
	ds_read_b128 v[172:175], v172 offset:3072
	s_add_u32 s40, s40, 0x20000
	s_addc_u32 s41, s41, 0
	s_mov_b32 m0, s43
	v_lshl_add_u64 v[226:227], s[40:41], 0, v[134:135]
	ds_read_b128 v[176:179], v143 offset:32768
	ds_read_b128 v[180:183], v143 offset:33792
	ds_read_b128 v[184:187], v143 offset:34816
	ds_read_b128 v[188:191], v143 offset:35840
	ds_read_b128 v[196:199], v143 offset:36864
	ds_read_b128 v[200:203], v143 offset:37888
	ds_read_b128 v[204:207], v143 offset:38912
	ds_read_b128 v[208:211], v143 offset:39936
	global_load_lds_dwordx4 v[226:227], off
	v_lshl_add_u64 v[226:227], s[40:41], 0, v[132:133]
	s_mov_b32 m0, s44
	s_nop 0
	global_load_lds_dwordx4 v[226:227], off
	s_waitcnt vmcnt(8)
	s_waitcnt lgkmcnt(0)
	s_setprio 1
	s_barrier
	v_mfma_f32_16x16x32_bf16 v[126:129], v[144:147], v[176:179], v[126:129]
	v_mfma_f32_16x16x32_bf16 v[122:125], v[152:155], v[176:179], v[122:125]
	v_mfma_f32_16x16x32_bf16 v[118:121], v[144:147], v[184:187], v[118:121]
	v_mfma_f32_16x16x32_bf16 v[114:117], v[152:155], v[184:187], v[114:117]
	v_mfma_f32_16x16x32_bf16 v[102:105], v[144:147], v[196:199], v[102:105]
	v_mfma_f32_16x16x32_bf16 v[98:101], v[152:155], v[196:199], v[98:101]
	v_mfma_f32_16x16x32_bf16 v[86:89], v[144:147], v[204:207], v[86:89]
	v_mfma_f32_16x16x32_bf16 v[82:85], v[152:155], v[204:207], v[82:85]
	v_mfma_f32_16x16x32_bf16 v[126:129], v[148:151], v[180:183], v[126:129]
	v_mfma_f32_16x16x32_bf16 v[122:125], v[156:159], v[180:183], v[122:125]
	v_mfma_f32_16x16x32_bf16 v[118:121], v[148:151], v[188:191], v[118:121]
	v_mfma_f32_16x16x32_bf16 v[114:117], v[156:159], v[188:191], v[114:117]
	v_mfma_f32_16x16x32_bf16 v[102:105], v[148:151], v[200:203], v[102:105]
	v_mfma_f32_16x16x32_bf16 v[98:101], v[156:159], v[200:203], v[98:101]
	v_mfma_f32_16x16x32_bf16 v[86:89], v[148:151], v[208:211], v[86:89]
	v_mfma_f32_16x16x32_bf16 v[82:85], v[156:159], v[208:211], v[82:85]
	v_mfma_f32_16x16x32_bf16 v[110:113], v[160:163], v[176:179], v[110:113]
	v_mfma_f32_16x16x32_bf16 v[106:109], v[168:171], v[176:179], v[106:109]
	v_mfma_f32_16x16x32_bf16 v[94:97], v[160:163], v[184:187], v[94:97]
	v_mfma_f32_16x16x32_bf16 v[90:93], v[168:171], v[184:187], v[90:93]
	v_mfma_f32_16x16x32_bf16 v[78:81], v[160:163], v[196:199], v[78:81]
	v_mfma_f32_16x16x32_bf16 v[74:77], v[168:171], v[196:199], v[74:77]
	v_mfma_f32_16x16x32_bf16 v[70:73], v[160:163], v[204:207], v[70:73]
	v_mfma_f32_16x16x32_bf16 v[66:69], v[168:171], v[204:207], v[66:69]
	v_mfma_f32_16x16x32_bf16 v[110:113], v[164:167], v[180:183], v[110:113]
	v_mfma_f32_16x16x32_bf16 v[106:109], v[172:175], v[180:183], v[106:109]
	v_mfma_f32_16x16x32_bf16 v[94:97], v[164:167], v[188:191], v[94:97]
	v_mfma_f32_16x16x32_bf16 v[90:93], v[172:175], v[188:191], v[90:93]
	v_mfma_f32_16x16x32_bf16 v[78:81], v[164:167], v[200:203], v[78:81]
	v_mfma_f32_16x16x32_bf16 v[74:77], v[172:175], v[200:203], v[74:77]
	v_mfma_f32_16x16x32_bf16 v[70:73], v[164:167], v[208:211], v[70:73]
	v_mfma_f32_16x16x32_bf16 v[66:69], v[172:175], v[208:211], v[66:69]
	s_barrier
; #define PG8_STAGE(bufoff, gbase, voff) do { _Pragma("unroll") for (int _i = 0; _i < 2; ++_i) \
;         __builtin_amdgcn_global_load_lds((const unsigned*)((const char*)(gbase) + (voff)[_i]), (PG8_LAS unsigned*)(lds + (bufoff) + ldsw + _i * 8192), 16, 0, 0); } while (0)
; #define PG8_LDA(dst, b, h) do { _Pragma("unroll") for (int m = 0; m < 4; ++m) _Pragma("unroll") for (int k = 0; k < 2; ++k) dst[m][k] = *(const PG8_LAS bf16x8*)(lds + PG8_SA(b, h) + aoff + m * 2048 + k * 1024); } while (0)
; #define PG8_LDB(dst, b, h) do { _Pragma("unroll") for (int n = 0; n < 2; ++n) _Pragma("unroll") for (int k = 0; k < 2; ++k) dst[n][k] = *(const PG8_LAS bf16x8*)(lds + PG8_SB(b, h) + boff + n * 2048 + k * 1024); } while (0)
; #define PG8_MMA(ai, bj, At, Bt) do { __builtin_amdgcn_s_setprio(1); _Pragma("unroll") for (int m = 0; m < 4; ++m) _Pragma("unroll") for (int n = 0; n < 2; ++n) _Pragma("unroll") for (int k = 0; k < 2; ++k) \
;         acc[ai][bj][m][n] = __builtin_amdgcn_mfma_f32_16x16x32_bf16(Bt[n][k], At[m][k], acc[ai][bj][m][n], 0, 0, 0); __builtin_amdgcn_s_setprio(0); } while (0)
; template <class Epi, class Sched, bool ALIGN_EPI = false, bool SP2 = false>
; __device__ __forceinline__ void gemm_phase(PG8_LAS unsigned char* lds, const Gemm g, const Sched& S, const Epi& E, int wv) {
;     ...
;             PG8_LDB(B0, 0, 0); PG8_LDB(B1, 0, 1); PG8_SCHED; PG8_LDA(At, 0, 0); PG8_STAGE(PG8_SA(1, 1), a1 + hstepA, voffA);
;             PG8_WAIT_V(8); PG8_WAIT_L(0); PG8_BAR; PG8_MMA(0, 0, At, B0); PG8_MMA(0, 1, At, B1); PG8_BAR; PG8_SCHED;
;             PG8_LDA(At, 0, 1); PG8_STAGE(PG8_SB(0, 0), b2, voffB); PG8_STAGE(PG8_SB(0, 1), b2 + hstep, voffB); PG8_STAGE(PG8_SA(0, 0), a2, voffA);
;             PG8_WAIT_V(8); PG8_WAIT_L(0); PG8_BAR; PG8_MMA(1, 0, At, B0); PG8_MMA(1, 1, At, B1); PG8_BAR; PG8_SCHED;
;             PG8_LDB(B0, 1, 0); PG8_LDB(B1, 1, 1); PG8_SCHED; PG8_LDA(At, 1, 0); PG8_STAGE(PG8_SA(0, 1), a2 + hstepA, voffA);
;             PG8_WAIT_V(8); PG8_WAIT_L(0); PG8_BAR; PG8_MMA(0, 0, At, B0); PG8_MMA(0, 1, At, B1); PG8_BAR; PG8_SCHED;
;             PG8_LDA(At, 1, 1); PG8_STAGE(PG8_SB(1, 0), b3, voffB); PG8_STAGE(PG8_SB(1, 1), b3 + hstep, voffB); PG8_STAGE(PG8_SA(1, 0), a3, voffA);
;             PG8_WAIT_V(8); PG8_WAIT_L(0); PG8_BAR; PG8_MMA(1, 0, At, B0); PG8_MMA(1, 1, At, B1); PG8_BAR; PG8_SCHED;
;     ...
;         if constexpr (ALIGN_EPI) { if (wr == 0) PG8_BAR; }
	s_setprio 0
	s_add_i32 s25, s25, s24
	v_lshl_add_u64 v[192:193], v[192:193], 0, s[14:15]
	s_mov_b32 m0, s25
	ds_read_b128 v[176:179], v143 offset:49152
	ds_read_b128 v[180:183], v143 offset:50176
	ds_read_b128 v[184:187], v143 offset:51200
	ds_read_b128 v[188:191], v143 offset:52224
	ds_read_b128 v[196:199], v143 offset:53248
	ds_read_b128 v[200:203], v143 offset:54272
	ds_read_b128 v[204:207], v143 offset:55296
	ds_read_b128 v[208:211], v143 offset:56320
	global_load_lds_dwordx4 v[192:193], off
	s_add_i32 m0, s25, 0x2000
	s_add_u32 s38, s38, 0x20080
	v_lshl_add_u64 v[192:193], v[212:213], 0, s[14:15]
	s_addc_u32 s39, s39, 0
	s_add_i32 s25, s53, s24
	global_load_lds_dwordx4 v[192:193], off
	v_lshl_add_u64 v[192:193], s[38:39], 0, v[0:1]
	s_mov_b32 m0, s25
	s_nop 0
	global_load_lds_dwordx4 v[192:193], off
	v_lshl_add_u64 v[192:193], s[38:39], 0, v[130:131]
	s_add_i32 m0, s25, 0x2000
	s_nop 0
	global_load_lds_dwordx4 v[192:193], off
	v_lshl_add_u64 v[192:193], v[222:223], 0, s[14:15]
	s_mov_b32 m0, s45
	s_nop 0
	global_load_lds_dwordx4 v[192:193], off
	v_lshl_add_u64 v[192:193], v[224:225], 0, s[14:15]
	s_mov_b32 m0, s46
	s_nop 0
	global_load_lds_dwordx4 v[192:193], off
	s_waitcnt vmcnt(8)
	s_waitcnt lgkmcnt(0)
	s_setprio 1
	s_barrier
	v_mfma_f32_16x16x32_bf16 v[62:65], v[144:147], v[176:179], v[62:65]
	v_mfma_f32_16x16x32_bf16 v[58:61], v[152:155], v[176:179], v[58:61]
	v_mfma_f32_16x16x32_bf16 v[54:57], v[144:147], v[184:187], v[54:57]
	v_mfma_f32_16x16x32_bf16 v[50:53], v[152:155], v[184:187], v[50:53]
	v_mfma_f32_16x16x32_bf16 v[38:41], v[144:147], v[196:199], v[38:41]
	v_mfma_f32_16x16x32_bf16 v[34:37], v[152:155], v[196:199], v[34:37]
	v_mfma_f32_16x16x32_bf16 v[22:25], v[144:147], v[204:207], v[22:25]
	v_mfma_f32_16x16x32_bf16 v[18:21], v[152:155], v[204:207], v[18:21]
	v_mfma_f32_16x16x32_bf16 v[62:65], v[148:151], v[180:183], v[62:65]
	v_mfma_f32_16x16x32_bf16 v[58:61], v[156:159], v[180:183], v[58:61]
	v_mfma_f32_16x16x32_bf16 v[54:57], v[148:151], v[188:191], v[54:57]
	v_mfma_f32_16x16x32_bf16 v[50:53], v[156:159], v[188:191], v[50:53]
	v_mfma_f32_16x16x32_bf16 v[38:41], v[148:151], v[200:203], v[38:41]
	v_mfma_f32_16x16x32_bf16 v[34:37], v[156:159], v[200:203], v[34:37]
	v_mfma_f32_16x16x32_bf16 v[22:25], v[148:151], v[208:211], v[22:25]
	v_mfma_f32_16x16x32_bf16 v[18:21], v[156:159], v[208:211], v[18:21]
	v_mfma_f32_16x16x32_bf16 v[46:49], v[160:163], v[176:179], v[46:49]
	v_mfma_f32_16x16x32_bf16 v[42:45], v[168:171], v[176:179], v[42:45]
	v_mfma_f32_16x16x32_bf16 v[30:33], v[160:163], v[184:187], v[30:33]
	v_mfma_f32_16x16x32_bf16 v[26:29], v[168:171], v[184:187], v[26:29]
	v_mfma_f32_16x16x32_bf16 v[14:17], v[160:163], v[196:199], v[14:17]
	v_mfma_f32_16x16x32_bf16 v[10:13], v[168:171], v[196:199], v[10:13]
	v_mfma_f32_16x16x32_bf16 v[6:9], v[160:163], v[204:207], v[6:9]
	v_mfma_f32_16x16x32_bf16 v[2:5], v[168:171], v[204:207], v[2:5]
	v_mfma_f32_16x16x32_bf16 v[46:49], v[164:167], v[180:183], v[46:49]
	v_mfma_f32_16x16x32_bf16 v[42:45], v[172:175], v[180:183], v[42:45]
	v_mfma_f32_16x16x32_bf16 v[30:33], v[164:167], v[188:191], v[30:33]
	v_mfma_f32_16x16x32_bf16 v[26:29], v[172:175], v[188:191], v[26:29]
	v_mfma_f32_16x16x32_bf16 v[14:17], v[164:167], v[200:203], v[14:17]
	v_mfma_f32_16x16x32_bf16 v[10:13], v[172:175], v[200:203], v[10:13]
	v_mfma_f32_16x16x32_bf16 v[6:9], v[164:167], v[208:211], v[6:9]
	v_mfma_f32_16x16x32_bf16 v[2:5], v[172:175], v[208:211], v[2:5]
	s_barrier
	s_setprio 0
	s_add_i32 s52, s52, 2
	s_add_u32 s36, s36, 0x100
	s_addc_u32 s37, s37, 0
	s_add_u32 s50, s50, 0x100
	s_addc_u32 s51, s51, 0
	s_cmp_gt_u32 s52, 5
	s_cbranch_scc0 .LBB0_995
	s_and_b64 vcc, exec, s[8:9]
	s_cbranch_vccz .LBB0_998
	s_barrier

; #define PG8_STAGE(bufoff, gbase, voff) do { _Pragma("unroll") for (int _i = 0; _i < 2; ++_i) \
;         __builtin_amdgcn_global_load_lds((const unsigned*)((const char*)(gbase) + (voff)[_i]), (PG8_LAS unsigned*)(lds + (bufoff) + ldsw + _i * 8192), 16, 0, 0); } while (0)
; #define PG8_LDA(dst, b, h) do { _Pragma("unroll") for (int m = 0; m < 4; ++m) _Pragma("unroll") for (int k = 0; k < 2; ++k) dst[m][k] = *(const PG8_LAS bf16x8*)(lds + PG8_SA(b, h) + aoff + m * 2048 + k * 1024); } while (0)
; #define PG8_LDB(dst, b, h) do { _Pragma("unroll") for (int n = 0; n < 2; ++n) _Pragma("unroll") for (int k = 0; k < 2; ++k) dst[n][k] = *(const PG8_LAS bf16x8*)(lds + PG8_SB(b, h) + boff + n * 2048 + k * 1024); } while (0)
; template <class Epi, class Sched, bool ALIGN_EPI = false, bool SP2 = false>
; __device__ __forceinline__ void gemm_phase(PG8_LAS unsigned char* lds, const Gemm g, const Sched& S, const Epi& E, int wv) {
;     ...
;         for (int t = 0; t < nt; t += 2) {
;             const bool last = (t == nt - 2);
;             const char* a1 = cA + (size_t)(t + 1) * kstep;
;             const char* a2 = last ? nA : cA + (size_t)(t + 2) * kstep; const char* b2 = last ? nB : cB + (size_t)(t + 2) * kstep;
;             const char* a3 = a2 + kstep; const char* b3 = b2 + kstep;
;             if (last && has_next) S.a_ready(nxt);
;             if constexpr (SP2) {
;             PG8_LDB(B0, 0, 0); PG8_LDB(B1, 0, 1); PG8_SCHED; PG8_LDA(At, 0, 0); PG8_STAGE(PG8_SA(1, 1), a1 + hstepA, voffA);
;             PG8_WAIT_V(8); PG8_WAIT_L(0); PG8_BAR; PG8_MMA(0, 0, At, B0); PG8_MMA(0, 1, At, B1); PG8_BAR; PG8_SCHED;
;             PG8_LDA(At, 0, 1); PG8_STAGE(PG8_SB(0, 0), b2, voffB); PG8_STAGE(PG8_SB(0, 1), b2 + hstep, voffB); PG8_STAGE(PG8_SA(0, 0), a2, voffA);
;             PG8_WAIT_V(8); PG8_WAIT_L(0); PG8_BAR; PG8_MMA(1, 0, At, B0); PG8_MMA(1, 1, At, B1); PG8_BAR; PG8_SCHED;
;             PG8_LDB(B0, 1, 0); PG8_LDB(B1, 1, 1); PG8_SCHED; PG8_LDA(At, 1, 0); PG8_STAGE(PG8_SA(0, 1), a2 + hstepA, voffA);
;             PG8_WAIT_V(8); PG8_WAIT_L(0); PG8_BAR; PG8_MMA(0, 0, At, B0); PG8_MMA(0, 1, At, B1); PG8_BAR; PG8_SCHED;
;             PG8_LDA(At, 1, 1); PG8_STAGE(PG8_SB(1, 0), b3, voffB); PG8_STAGE(PG8_SB(1, 1), b3 + hstep, voffB); PG8_STAGE(PG8_SA(1, 0), a3, voffA);
;             PG8_WAIT_V(8); PG8_WAIT_L(0); PG8_BAR; PG8_MMA(1, 0, At, B0); PG8_MMA(1, 1, At, B1); PG8_BAR; PG8_SCHED;
.LBB0_1079:
	s_add_u32 s6, s4, 0xfffc0080
	s_addc_u32 s7, s5, -1
	s_add_i32 s25, 0, 0x10000
	s_cmp_eq_u32 s57, 12
	s_cselect_b32 s9, s23, s7
	s_cselect_b32 s8, s24, s6
	s_cselect_b32 s7, s26, s56
	s_cselect_b32 s6, s47, s49
	s_add_i32 s60, 0, 0x14000
	v_add_u32_e32 v142, s25, v181
	v_add_u32_e32 v158, s60, v181
	ds_read_b128 v[130:133], v142
	ds_read_b128 v[134:137], v142 offset:1024
	ds_read_b128 v[138:141], v142 offset:2048
	ds_read_b128 v[142:145], v142 offset:3072
	ds_read_b128 v[146:149], v158
	ds_read_b128 v[150:153], v158 offset:1024
	ds_read_b128 v[154:157], v158 offset:2048
	ds_read_b128 v[158:161], v158 offset:3072
	v_lshl_add_u64 v[178:179], s[4:5], 0, v[174:175]
	s_add_i32 m0, s29, 0xc000
	ds_read_b128 v[182:185], v187
	ds_read_b128 v[188:191], v187 offset:1024
	ds_read_b128 v[196:199], v187 offset:2048
	ds_read_b128 v[200:203], v187 offset:3072
	ds_read_b128 v[204:207], v187 offset:4096
	ds_read_b128 v[208:211], v187 offset:5120
	ds_read_b128 v[222:225], v187 offset:6144
	ds_read_b128 v[226:229], v187 offset:7168
	global_load_lds_dwordx4 v[178:179], off
	v_lshl_add_u64 v[178:179], s[4:5], 0, v[176:177]
	s_add_i32 m0, s29, 0xe000
	s_nop 0
	global_load_lds_dwordx4 v[178:179], off
	s_waitcnt vmcnt(8)
	s_waitcnt lgkmcnt(0)
	s_setprio 1
	s_barrier
	v_mfma_f32_16x16x32_bf16 v[126:129], v[130:133], v[182:185], v[126:129]
	v_mfma_f32_16x16x32_bf16 v[122:125], v[138:141], v[182:185], v[122:125]
	v_mfma_f32_16x16x32_bf16 v[110:113], v[130:133], v[196:199], v[110:113]
	v_mfma_f32_16x16x32_bf16 v[106:109], v[138:141], v[196:199], v[106:109]
	v_mfma_f32_16x16x32_bf16 v[94:97], v[130:133], v[204:207], v[94:97]
	v_mfma_f32_16x16x32_bf16 v[90:93], v[138:141], v[204:207], v[90:93]
	v_mfma_f32_16x16x32_bf16 v[78:81], v[130:133], v[222:225], v[78:81]
	v_mfma_f32_16x16x32_bf16 v[74:77], v[138:141], v[222:225], v[74:77]
	v_mfma_f32_16x16x32_bf16 v[126:129], v[134:137], v[188:191], v[126:129]
	v_mfma_f32_16x16x32_bf16 v[122:125], v[142:145], v[188:191], v[122:125]
	v_mfma_f32_16x16x32_bf16 v[110:113], v[134:137], v[200:203], v[110:113]
	v_mfma_f32_16x16x32_bf16 v[106:109], v[142:145], v[200:203], v[106:109]
	v_mfma_f32_16x16x32_bf16 v[94:97], v[134:137], v[208:211], v[94:97]
	v_mfma_f32_16x16x32_bf16 v[90:93], v[142:145], v[208:211], v[90:93]
	v_mfma_f32_16x16x32_bf16 v[78:81], v[134:137], v[226:229], v[78:81]
	v_mfma_f32_16x16x32_bf16 v[74:77], v[142:145], v[226:229], v[74:77]
	v_mfma_f32_16x16x32_bf16 v[118:121], v[146:149], v[182:185], v[118:121]
	v_mfma_f32_16x16x32_bf16 v[114:117], v[154:157], v[182:185], v[114:117]
	v_mfma_f32_16x16x32_bf16 v[102:105], v[146:149], v[196:199], v[102:105]
	v_mfma_f32_16x16x32_bf16 v[98:101], v[154:157], v[196:199], v[98:101]
	v_mfma_f32_16x16x32_bf16 v[86:89], v[146:149], v[204:207], v[86:89]
	v_mfma_f32_16x16x32_bf16 v[82:85], v[154:157], v[204:207], v[82:85]
	v_mfma_f32_16x16x32_bf16 v[70:73], v[146:149], v[222:225], v[70:73]
	v_mfma_f32_16x16x32_bf16 v[66:69], v[154:157], v[222:225], v[66:69]
	v_mfma_f32_16x16x32_bf16 v[118:121], v[150:153], v[188:191], v[118:121]
	v_mfma_f32_16x16x32_bf16 v[114:117], v[158:161], v[188:191], v[114:117]
	v_mfma_f32_16x16x32_bf16 v[102:105], v[150:153], v[200:203], v[102:105]
	v_mfma_f32_16x16x32_bf16 v[98:101], v[158:161], v[200:203], v[98:101]
	v_mfma_f32_16x16x32_bf16 v[86:89], v[150:153], v[208:211], v[86:89]
	v_mfma_f32_16x16x32_bf16 v[82:85], v[158:161], v[208:211], v[82:85]
	v_mfma_f32_16x16x32_bf16 v[70:73], v[150:153], v[226:229], v[70:73]
	v_mfma_f32_16x16x32_bf16 v[66:69], v[158:161], v[226:229], v[66:69]
	s_barrier
	s_setprio 0
	s_add_i32 s25, s25, s28
	v_lshl_add_u64 v[178:179], s[6:7], 0, v[166:167]
	s_mov_b32 m0, s25
	ds_read_b128 v[182:185], v187 offset:16384
	ds_read_b128 v[188:191], v187 offset:17408
	ds_read_b128 v[196:199], v187 offset:18432
	ds_read_b128 v[200:203], v187 offset:19456
	ds_read_b128 v[204:207], v187 offset:20480
	ds_read_b128 v[208:211], v187 offset:21504
	ds_read_b128 v[222:225], v187 offset:22528
	ds_read_b128 v[226:229], v187 offset:23552
	global_load_lds_dwordx4 v[178:179], off
	s_add_i32 m0, s25, 0x2000
	s_add_u32 s58, s6, 0x40000
	v_lshl_add_u64 v[192:193], s[6:7], 0, v[162:163]
	s_addc_u32 s59, s7, 0
	s_add_i32 s25, s60, s28
	global_load_lds_dwordx4 v[192:193], off
	v_lshl_add_u64 v[212:213], s[58:59], 0, v[166:167]
	s_mov_b32 m0, s25
	v_lshl_add_u64 v[230:231], s[8:9], 0, v[164:165]
	global_load_lds_dwordx4 v[212:213], off
	v_lshl_add_u64 v[212:213], s[58:59], 0, v[162:163]
	s_add_i32 m0, s25, 0x2000
	s_nop 0
	global_load_lds_dwordx4 v[212:213], off
	v_lshl_add_u64 v[212:213], s[8:9], 0, v[168:169]
	s_mov_b32 m0, s29
	s_nop 0
	global_load_lds_dwordx4 v[212:213], off
	s_mov_b32 m0, s30
	s_nop 0
	global_load_lds_dwordx4 v[230:231], off
	s_waitcnt vmcnt(8)
	s_waitcnt lgkmcnt(0)
	s_setprio 1
	s_barrier
; #define PG8_STAGE(bufoff, gbase, voff) do { _Pragma("unroll") for (int _i = 0; _i < 2; ++_i) \
;         __builtin_amdgcn_global_load_lds((const unsigned*)((const char*)(gbase) + (voff)[_i]), (PG8_LAS unsigned*)(lds + (bufoff) + ldsw + _i * 8192), 16, 0, 0); } while (0)
; #define PG8_LDA(dst, b, h) do { _Pragma("unroll") for (int m = 0; m < 4; ++m) _Pragma("unroll") for (int k = 0; k < 2; ++k) dst[m][k] = *(const PG8_LAS bf16x8*)(lds + PG8_SA(b, h) + aoff + m * 2048 + k * 1024); } while (0)
; #define PG8_LDB(dst, b, h) do { _Pragma("unroll") for (int n = 0; n < 2; ++n) _Pragma("unroll") for (int k = 0; k < 2; ++k) dst[n][k] = *(const PG8_LAS bf16x8*)(lds + PG8_SB(b, h) + boff + n * 2048 + k * 1024); } while (0)
; #define PG8_MMA(ai, bj, At, Bt) do { __builtin_amdgcn_s_setprio(1); _Pragma("unroll") for (int m = 0; m < 4; ++m) _Pragma("unroll") for (int n = 0; n < 2; ++n) _Pragma("unroll") for (int k = 0; k < 2; ++k) \
;         acc[ai][bj][m][n] = __builtin_amdgcn_mfma_f32_16x16x32_bf16(Bt[n][k], At[m][k], acc[ai][bj][m][n], 0, 0, 0); __builtin_amdgcn_s_setprio(0); } while (0)
; #define PG8_BAR __builtin_amdgcn_s_barrier()
; template <class Epi, class Sched, bool ALIGN_EPI = false, bool SP2 = false>
; __device__ __forceinline__ void gemm_phase(PG8_LAS unsigned char* lds, const Gemm g, const Sched& S, const Epi& E, int wv) {
;     ...
;             PG8_LDB(B0, 0, 0); PG8_LDB(B1, 0, 1); PG8_SCHED; PG8_LDA(At, 0, 0); PG8_STAGE(PG8_SA(1, 1), a1 + hstepA, voffA);
;             PG8_WAIT_V(8); PG8_WAIT_L(0); PG8_BAR; PG8_MMA(0, 0, At, B0); PG8_MMA(0, 1, At, B1); PG8_BAR; PG8_SCHED;
;             PG8_LDA(At, 0, 1); PG8_STAGE(PG8_SB(0, 0), b2, voffB); PG8_STAGE(PG8_SB(0, 1), b2 + hstep, voffB); PG8_STAGE(PG8_SA(0, 0), a2, voffA);
;             PG8_WAIT_V(8); PG8_WAIT_L(0); PG8_BAR; PG8_MMA(1, 0, At, B0); PG8_MMA(1, 1, At, B1); PG8_BAR; PG8_SCHED;
;             PG8_LDB(B0, 1, 0); PG8_LDB(B1, 1, 1); PG8_SCHED; PG8_LDA(At, 1, 0); PG8_STAGE(PG8_SA(0, 1), a2 + hstepA, voffA);
;             PG8_WAIT_V(8); PG8_WAIT_L(0); PG8_BAR; PG8_MMA(0, 0, At, B0); PG8_MMA(0, 1, At, B1); PG8_BAR; PG8_SCHED;
;             PG8_LDA(At, 1, 1); PG8_STAGE(PG8_SB(1, 0), b3, voffB); PG8_STAGE(PG8_SB(1, 1), b3 + hstep, voffB); PG8_STAGE(PG8_SA(1, 0), a3, voffA);
;             PG8_WAIT_V(8); PG8_WAIT_L(0); PG8_BAR; PG8_MMA(1, 0, At, B0); PG8_MMA(1, 1, At, B1); PG8_BAR; PG8_SCHED;
	v_mfma_f32_16x16x32_bf16 v[62:65], v[130:133], v[182:185], v[62:65]
	v_mfma_f32_16x16x32_bf16 v[58:61], v[138:141], v[182:185], v[58:61]
	v_mfma_f32_16x16x32_bf16 v[46:49], v[130:133], v[196:199], v[46:49]
	v_mfma_f32_16x16x32_bf16 v[42:45], v[138:141], v[196:199], v[42:45]
	v_mfma_f32_16x16x32_bf16 v[30:33], v[130:133], v[204:207], v[30:33]
	v_mfma_f32_16x16x32_bf16 v[26:29], v[138:141], v[204:207], v[26:29]
	v_mfma_f32_16x16x32_bf16 v[14:17], v[130:133], v[222:225], v[14:17]
	v_mfma_f32_16x16x32_bf16 v[10:13], v[138:141], v[222:225], v[10:13]
	v_mfma_f32_16x16x32_bf16 v[62:65], v[134:137], v[188:191], v[62:65]
	v_mfma_f32_16x16x32_bf16 v[58:61], v[142:145], v[188:191], v[58:61]
	v_mfma_f32_16x16x32_bf16 v[46:49], v[134:137], v[200:203], v[46:49]
	v_mfma_f32_16x16x32_bf16 v[42:45], v[142:145], v[200:203], v[42:45]
	v_mfma_f32_16x16x32_bf16 v[30:33], v[134:137], v[208:211], v[30:33]
	v_mfma_f32_16x16x32_bf16 v[26:29], v[142:145], v[208:211], v[26:29]
	v_mfma_f32_16x16x32_bf16 v[14:17], v[134:137], v[226:229], v[14:17]
	v_mfma_f32_16x16x32_bf16 v[10:13], v[142:145], v[226:229], v[10:13]
	v_mfma_f32_16x16x32_bf16 v[54:57], v[146:149], v[182:185], v[54:57]
	v_mfma_f32_16x16x32_bf16 v[50:53], v[154:157], v[182:185], v[50:53]
	v_mfma_f32_16x16x32_bf16 v[38:41], v[146:149], v[196:199], v[38:41]
	v_mfma_f32_16x16x32_bf16 v[34:37], v[154:157], v[196:199], v[34:37]
	v_mfma_f32_16x16x32_bf16 v[22:25], v[146:149], v[204:207], v[22:25]
	v_mfma_f32_16x16x32_bf16 v[18:21], v[154:157], v[204:207], v[18:21]
	v_mfma_f32_16x16x32_bf16 v[6:9], v[146:149], v[222:225], v[6:9]
	v_mfma_f32_16x16x32_bf16 v[2:5], v[154:157], v[222:225], v[2:5]
	v_mfma_f32_16x16x32_bf16 v[54:57], v[150:153], v[188:191], v[54:57]
	v_mfma_f32_16x16x32_bf16 v[50:53], v[158:161], v[188:191], v[50:53]
	v_mfma_f32_16x16x32_bf16 v[38:41], v[150:153], v[200:203], v[38:41]
	v_mfma_f32_16x16x32_bf16 v[34:37], v[158:161], v[200:203], v[34:37]
	v_mfma_f32_16x16x32_bf16 v[22:25], v[150:153], v[208:211], v[22:25]
	v_mfma_f32_16x16x32_bf16 v[18:21], v[158:161], v[208:211], v[18:21]
	v_mfma_f32_16x16x32_bf16 v[6:9], v[150:153], v[226:229], v[6:9]
	v_mfma_f32_16x16x32_bf16 v[2:5], v[158:161], v[226:229], v[2:5]
	s_barrier
	s_setprio 0
	s_add_i32 s25, 0, 0x18000
	s_add_i32 s58, 0, 0x1c000
	v_add_u32_e32 v142, s25, v181
	v_add_u32_e32 v158, s58, v181
	ds_read_b128 v[130:133], v142
	ds_read_b128 v[134:137], v142 offset:1024
	ds_read_b128 v[138:141], v142 offset:2048
	ds_read_b128 v[142:145], v142 offset:3072
	ds_read_b128 v[146:149], v158
	ds_read_b128 v[150:153], v158 offset:1024
	ds_read_b128 v[154:157], v158 offset:2048
	ds_read_b128 v[158:161], v158 offset:3072
	s_add_u32 s8, s8, 0x40000
	s_addc_u32 s9, s9, 0
	s_mov_b32 m0, s31
	v_lshl_add_u64 v[232:233], s[8:9], 0, v[168:169]
	ds_read_b128 v[182:185], v187 offset:32768
	ds_read_b128 v[188:191], v187 offset:33792
	ds_read_b128 v[196:199], v187 offset:34816
	ds_read_b128 v[200:203], v187 offset:35840
	ds_read_b128 v[204:207], v187 offset:36864
	ds_read_b128 v[208:211], v187 offset:37888
	ds_read_b128 v[222:225], v187 offset:38912
	ds_read_b128 v[226:229], v187 offset:39936
	global_load_lds_dwordx4 v[232:233], off
	v_lshl_add_u64 v[232:233], s[8:9], 0, v[164:165]
	s_mov_b32 m0, s34
	s_nop 0
	global_load_lds_dwordx4 v[232:233], off
	s_waitcnt vmcnt(8)
	s_waitcnt lgkmcnt(0)
	s_setprio 1
	s_barrier
	v_mfma_f32_16x16x32_bf16 v[126:129], v[130:133], v[182:185], v[126:129]
	v_mfma_f32_16x16x32_bf16 v[122:125], v[138:141], v[182:185], v[122:125]
	v_mfma_f32_16x16x32_bf16 v[110:113], v[130:133], v[196:199], v[110:113]
	v_mfma_f32_16x16x32_bf16 v[106:109], v[138:141], v[196:199], v[106:109]
	v_mfma_f32_16x16x32_bf16 v[94:97], v[130:133], v[204:207], v[94:97]
	v_mfma_f32_16x16x32_bf16 v[90:93], v[138:141], v[204:207], v[90:93]
	v_mfma_f32_16x16x32_bf16 v[78:81], v[130:133], v[222:225], v[78:81]
	v_mfma_f32_16x16x32_bf16 v[74:77], v[138:141], v[222:225], v[74:77]
	v_mfma_f32_16x16x32_bf16 v[126:129], v[134:137], v[188:191], v[126:129]
	v_mfma_f32_16x16x32_bf16 v[122:125], v[142:145], v[188:191], v[122:125]
	v_mfma_f32_16x16x32_bf16 v[110:113], v[134:137], v[200:203], v[110:113]
	v_mfma_f32_16x16x32_bf16 v[106:109], v[142:145], v[200:203], v[106:109]
	v_mfma_f32_16x16x32_bf16 v[94:97], v[134:137], v[208:211], v[94:97]
	v_mfma_f32_16x16x32_bf16 v[90:93], v[142:145], v[208:211], v[90:93]
	v_mfma_f32_16x16x32_bf16 v[78:81], v[134:137], v[226:229], v[78:81]
	v_mfma_f32_16x16x32_bf16 v[74:77], v[142:145], v[226:229], v[74:77]
	v_mfma_f32_16x16x32_bf16 v[118:121], v[146:149], v[182:185], v[118:121]
	v_mfma_f32_16x16x32_bf16 v[114:117], v[154:157], v[182:185], v[114:117]
	v_mfma_f32_16x16x32_bf16 v[102:105], v[146:149], v[196:199], v[102:105]
	v_mfma_f32_16x16x32_bf16 v[98:101], v[154:157], v[196:199], v[98:101]
	v_mfma_f32_16x16x32_bf16 v[86:89], v[146:149], v[204:207], v[86:89]
	v_mfma_f32_16x16x32_bf16 v[82:85], v[154:157], v[204:207], v[82:85]
	v_mfma_f32_16x16x32_bf16 v[70:73], v[146:149], v[222:225], v[70:73]
	v_mfma_f32_16x16x32_bf16 v[66:69], v[154:157], v[222:225], v[66:69]
	v_mfma_f32_16x16x32_bf16 v[118:121], v[150:153], v[188:191], v[118:121]
	v_mfma_f32_16x16x32_bf16 v[114:117], v[158:161], v[188:191], v[114:117]
	v_mfma_f32_16x16x32_bf16 v[102:105], v[150:153], v[200:203], v[102:105]
	v_mfma_f32_16x16x32_bf16 v[98:101], v[158:161], v[200:203], v[98:101]
	v_mfma_f32_16x16x32_bf16 v[86:89], v[150:153], v[208:211], v[86:89]
	v_mfma_f32_16x16x32_bf16 v[82:85], v[158:161], v[208:211], v[82:85]
	v_mfma_f32_16x16x32_bf16 v[70:73], v[150:153], v[226:229], v[70:73]
	v_mfma_f32_16x16x32_bf16 v[66:69], v[158:161], v[226:229], v[66:69]
	s_barrier
; #define PG8_STAGE(bufoff, gbase, voff) do { _Pragma("unroll") for (int _i = 0; _i < 2; ++_i) \
;         __builtin_amdgcn_global_load_lds((const unsigned*)((const char*)(gbase) + (voff)[_i]), (PG8_LAS unsigned*)(lds + (bufoff) + ldsw + _i * 8192), 16, 0, 0); } while (0)
; #define PG8_LDA(dst, b, h) do { _Pragma("unroll") for (int m = 0; m < 4; ++m) _Pragma("unroll") for (int k = 0; k < 2; ++k) dst[m][k] = *(const PG8_LAS bf16x8*)(lds + PG8_SA(b, h) + aoff + m * 2048 + k * 1024); } while (0)
; #define PG8_LDB(dst, b, h) do { _Pragma("unroll") for (int n = 0; n < 2; ++n) _Pragma("unroll") for (int k = 0; k < 2; ++k) dst[n][k] = *(const PG8_LAS bf16x8*)(lds + PG8_SB(b, h) + boff + n * 2048 + k * 1024); } while (0)
; #define PG8_MMA(ai, bj, At, Bt) do { __builtin_amdgcn_s_setprio(1); _Pragma("unroll") for (int m = 0; m < 4; ++m) _Pragma("unroll") for (int n = 0; n < 2; ++n) _Pragma("unroll") for (int k = 0; k < 2; ++k) \
;         acc[ai][bj][m][n] = __builtin_amdgcn_mfma_f32_16x16x32_bf16(Bt[n][k], At[m][k], acc[ai][bj][m][n], 0, 0, 0); __builtin_amdgcn_s_setprio(0); } while (0)
; template <class Epi, class Sched, bool ALIGN_EPI = false, bool SP2 = false>
; __device__ __forceinline__ void gemm_phase(PG8_LAS unsigned char* lds, const Gemm g, const Sched& S, const Epi& E, int wv) {
;     ...
;             PG8_LDB(B0, 0, 0); PG8_LDB(B1, 0, 1); PG8_SCHED; PG8_LDA(At, 0, 0); PG8_STAGE(PG8_SA(1, 1), a1 + hstepA, voffA);
;             PG8_WAIT_V(8); PG8_WAIT_L(0); PG8_BAR; PG8_MMA(0, 0, At, B0); PG8_MMA(0, 1, At, B1); PG8_BAR; PG8_SCHED;
;             PG8_LDA(At, 0, 1); PG8_STAGE(PG8_SB(0, 0), b2, voffB); PG8_STAGE(PG8_SB(0, 1), b2 + hstep, voffB); PG8_STAGE(PG8_SA(0, 0), a2, voffA);
;             PG8_WAIT_V(8); PG8_WAIT_L(0); PG8_BAR; PG8_MMA(1, 0, At, B0); PG8_MMA(1, 1, At, B1); PG8_BAR; PG8_SCHED;
;             PG8_LDB(B0, 1, 0); PG8_LDB(B1, 1, 1); PG8_SCHED; PG8_LDA(At, 1, 0); PG8_STAGE(PG8_SA(0, 1), a2 + hstepA, voffA);
;             PG8_WAIT_V(8); PG8_WAIT_L(0); PG8_BAR; PG8_MMA(0, 0, At, B0); PG8_MMA(0, 1, At, B1); PG8_BAR; PG8_SCHED;
;             PG8_LDA(At, 1, 1); PG8_STAGE(PG8_SB(1, 0), b3, voffB); PG8_STAGE(PG8_SB(1, 1), b3 + hstep, voffB); PG8_STAGE(PG8_SA(1, 0), a3, voffA);
;             PG8_WAIT_V(8); PG8_WAIT_L(0); PG8_BAR; PG8_MMA(1, 0, At, B0); PG8_MMA(1, 1, At, B1); PG8_BAR; PG8_SCHED;
;     ...
;         if constexpr (ALIGN_EPI) { if (wr == 0) PG8_BAR; }
	s_setprio 0
	s_add_i32 s8, s25, s28
	v_lshl_add_u64 v[178:179], v[178:179], 0, s[14:15]
	s_mov_b32 m0, s8
	ds_read_b128 v[182:185], v187 offset:49152
	ds_read_b128 v[188:191], v187 offset:50176
	ds_read_b128 v[196:199], v187 offset:51200
	ds_read_b128 v[200:203], v187 offset:52224
	ds_read_b128 v[204:207], v187 offset:53248
	ds_read_b128 v[208:211], v187 offset:54272
	ds_read_b128 v[222:225], v187 offset:55296
	ds_read_b128 v[226:229], v187 offset:56320
	global_load_lds_dwordx4 v[178:179], off
	s_add_i32 m0, s8, 0x2000
	s_add_u32 s6, s6, 0x40080
	v_lshl_add_u64 v[178:179], v[192:193], 0, s[14:15]
	s_addc_u32 s7, s7, 0
	s_add_i32 s8, s58, s28
	global_load_lds_dwordx4 v[178:179], off
	v_lshl_add_u64 v[178:179], s[6:7], 0, v[166:167]
	s_mov_b32 m0, s8
	s_nop 0
	global_load_lds_dwordx4 v[178:179], off
	v_lshl_add_u64 v[178:179], s[6:7], 0, v[162:163]
	s_add_i32 m0, s8, 0x2000
	s_nop 0
	global_load_lds_dwordx4 v[178:179], off
	v_lshl_add_u64 v[178:179], v[212:213], 0, s[14:15]
	s_mov_b32 m0, s35
	s_nop 0
	global_load_lds_dwordx4 v[178:179], off
	v_lshl_add_u64 v[178:179], v[230:231], 0, s[14:15]
	s_mov_b32 m0, s54
	s_nop 0
	global_load_lds_dwordx4 v[178:179], off
	s_waitcnt vmcnt(8)
	s_waitcnt lgkmcnt(0)
	s_setprio 1
	s_barrier
	v_mfma_f32_16x16x32_bf16 v[62:65], v[130:133], v[182:185], v[62:65]
	v_mfma_f32_16x16x32_bf16 v[58:61], v[138:141], v[182:185], v[58:61]
	v_mfma_f32_16x16x32_bf16 v[46:49], v[130:133], v[196:199], v[46:49]
	v_mfma_f32_16x16x32_bf16 v[42:45], v[138:141], v[196:199], v[42:45]
	v_mfma_f32_16x16x32_bf16 v[30:33], v[130:133], v[204:207], v[30:33]
	v_mfma_f32_16x16x32_bf16 v[26:29], v[138:141], v[204:207], v[26:29]
	v_mfma_f32_16x16x32_bf16 v[14:17], v[130:133], v[222:225], v[14:17]
	v_mfma_f32_16x16x32_bf16 v[10:13], v[138:141], v[222:225], v[10:13]
	v_mfma_f32_16x16x32_bf16 v[62:65], v[134:137], v[188:191], v[62:65]
	v_mfma_f32_16x16x32_bf16 v[58:61], v[142:145], v[188:191], v[58:61]
	v_mfma_f32_16x16x32_bf16 v[46:49], v[134:137], v[200:203], v[46:49]
	v_mfma_f32_16x16x32_bf16 v[42:45], v[142:145], v[200:203], v[42:45]
	v_mfma_f32_16x16x32_bf16 v[30:33], v[134:137], v[208:211], v[30:33]
	v_mfma_f32_16x16x32_bf16 v[26:29], v[142:145], v[208:211], v[26:29]
	v_mfma_f32_16x16x32_bf16 v[14:17], v[134:137], v[226:229], v[14:17]
	v_mfma_f32_16x16x32_bf16 v[10:13], v[142:145], v[226:229], v[10:13]
	v_mfma_f32_16x16x32_bf16 v[54:57], v[146:149], v[182:185], v[54:57]
	v_mfma_f32_16x16x32_bf16 v[50:53], v[154:157], v[182:185], v[50:53]
	v_mfma_f32_16x16x32_bf16 v[38:41], v[146:149], v[196:199], v[38:41]
	v_mfma_f32_16x16x32_bf16 v[34:37], v[154:157], v[196:199], v[34:37]
	v_mfma_f32_16x16x32_bf16 v[22:25], v[146:149], v[204:207], v[22:25]
	v_mfma_f32_16x16x32_bf16 v[18:21], v[154:157], v[204:207], v[18:21]
	v_mfma_f32_16x16x32_bf16 v[6:9], v[146:149], v[222:225], v[6:9]
	v_mfma_f32_16x16x32_bf16 v[2:5], v[154:157], v[222:225], v[2:5]
	v_mfma_f32_16x16x32_bf16 v[54:57], v[150:153], v[188:191], v[54:57]
	v_mfma_f32_16x16x32_bf16 v[50:53], v[158:161], v[188:191], v[50:53]
	v_mfma_f32_16x16x32_bf16 v[38:41], v[150:153], v[200:203], v[38:41]
	v_mfma_f32_16x16x32_bf16 v[34:37], v[158:161], v[200:203], v[34:37]
	v_mfma_f32_16x16x32_bf16 v[22:25], v[150:153], v[208:211], v[22:25]
	v_mfma_f32_16x16x32_bf16 v[18:21], v[158:161], v[208:211], v[18:21]
	v_mfma_f32_16x16x32_bf16 v[6:9], v[150:153], v[226:229], v[6:9]
	v_mfma_f32_16x16x32_bf16 v[2:5], v[158:161], v[226:229], v[2:5]
	s_barrier
	s_setprio 0
	s_add_i32 s57, s57, 2
	s_add_u32 s4, s4, 0x100
	s_addc_u32 s5, s5, 0
	s_add_u32 s49, s49, 0x100
	s_addc_u32 s56, s56, 0
	s_cmp_gt_u32 s57, 13
	s_cbranch_scc0 .LBB0_1079
	v_mov_b64_e32 v[218:219], 0x400
	s_and_b64 vcc, exec, s[44:45]
	s_cbranch_vccz .LBB0_1082
	s_barrier

; #define PG8_STAGE(bufoff, gbase, voff) do { _Pragma("unroll") for (int _i = 0; _i < 2; ++_i) \
;         __builtin_amdgcn_global_load_lds((const unsigned*)((const char*)(gbase) + (voff)[_i]), (PG8_LAS unsigned*)(lds + (bufoff) + ldsw + _i * 8192), 16, 0, 0); } while (0)
; #define PG8_LDA(dst, b, h) do { _Pragma("unroll") for (int m = 0; m < 4; ++m) _Pragma("unroll") for (int k = 0; k < 2; ++k) dst[m][k] = *(const PG8_LAS bf16x8*)(lds + PG8_SA(b, h) + aoff + m * 2048 + k * 1024); } while (0)
; #define PG8_LDB(dst, b, h) do { _Pragma("unroll") for (int n = 0; n < 2; ++n) _Pragma("unroll") for (int k = 0; k < 2; ++k) dst[n][k] = *(const PG8_LAS bf16x8*)(lds + PG8_SB(b, h) + boff + n * 2048 + k * 1024); } while (0)
; template <class Epi, class Sched, bool ALIGN_EPI = false, bool SP2 = false>
; __device__ __forceinline__ void gemm_phase(PG8_LAS unsigned char* lds, const Gemm g, const Sched& S, const Epi& E, int wv) {
;     ...
;         for (int t = 0; t < nt; t += 2) {
;             const bool last = (t == nt - 2);
;             const char* a1 = cA + (size_t)(t + 1) * kstep;
;             const char* a2 = last ? nA : cA + (size_t)(t + 2) * kstep; const char* b2 = last ? nB : cB + (size_t)(t + 2) * kstep;
;             const char* a3 = a2 + kstep; const char* b3 = b2 + kstep;
;             if (last && has_next) S.a_ready(nxt);
;             if constexpr (SP2) {
;             PG8_LDB(B0, 0, 0); PG8_LDB(B1, 0, 1); PG8_SCHED; PG8_LDA(At, 0, 0); PG8_STAGE(PG8_SA(1, 1), a1 + hstepA, voffA);
;             PG8_WAIT_V(8); PG8_WAIT_L(0); PG8_BAR; PG8_MMA(0, 0, At, B0); PG8_MMA(0, 1, At, B1); PG8_BAR; PG8_SCHED;
;             PG8_LDA(At, 0, 1); PG8_STAGE(PG8_SB(0, 0), b2, voffB); PG8_STAGE(PG8_SB(0, 1), b2 + hstep, voffB); PG8_STAGE(PG8_SA(0, 0), a2, voffA);
;             PG8_WAIT_V(8); PG8_WAIT_L(0); PG8_BAR; PG8_MMA(1, 0, At, B0); PG8_MMA(1, 1, At, B1); PG8_BAR; PG8_SCHED;
;             PG8_LDB(B0, 1, 0); PG8_LDB(B1, 1, 1); PG8_SCHED; PG8_LDA(At, 1, 0); PG8_STAGE(PG8_SA(0, 1), a2 + hstepA, voffA);
;             PG8_WAIT_V(8); PG8_WAIT_L(0); PG8_BAR; PG8_MMA(0, 0, At, B0); PG8_MMA(0, 1, At, B1); PG8_BAR; PG8_SCHED;
;             PG8_LDA(At, 1, 1); PG8_STAGE(PG8_SB(1, 0), b3, voffB); PG8_STAGE(PG8_SB(1, 1), b3 + hstep, voffB); PG8_STAGE(PG8_SA(1, 0), a3, voffA);
;             PG8_WAIT_V(8); PG8_WAIT_L(0); PG8_BAR; PG8_MMA(1, 0, At, B0); PG8_MMA(1, 1, At, B1); PG8_BAR; PG8_SCHED;
.LBB0_1147:
	s_add_u32 s25, s28, 0xfffc0080
	s_addc_u32 s30, s29, -1
	s_add_i32 s58, 0, 0x10000
	s_cmp_eq_u32 s57, 12
	s_cselect_b32 s45, s16, s30
	s_cselect_b32 s44, s17, s25
	s_cselect_b32 s31, s35, s56
	s_cselect_b32 s30, s39, s55
	s_add_i32 s25, 0, 0x14000
	v_add_u32_e32 v142, s58, v189
	v_add_u32_e32 v170, s25, v189
	ds_read_b128 v[130:133], v142
	ds_read_b128 v[134:137], v142 offset:1024
	ds_read_b128 v[138:141], v142 offset:2048
	ds_read_b128 v[142:145], v142 offset:3072
	ds_read_b128 v[146:149], v170
	ds_read_b128 v[150:153], v170 offset:1024
	ds_read_b128 v[154:157], v170 offset:2048
	ds_read_b128 v[170:173], v170 offset:3072
	v_lshl_add_u64 v[186:187], s[28:29], 0, v[166:167]
	s_add_i32 m0, s46, 0xc000
	ds_read_b128 v[174:177], v191
	ds_read_b128 v[178:181], v191 offset:1024
	ds_read_b128 v[182:185], v191 offset:2048
	ds_read_b128 v[196:199], v191 offset:3072
	ds_read_b128 v[200:203], v191 offset:4096
	ds_read_b128 v[204:207], v191 offset:5120
	ds_read_b128 v[208:211], v191 offset:6144
	ds_read_b128 v[222:225], v191 offset:7168
	global_load_lds_dwordx4 v[186:187], off
	v_lshl_add_u64 v[186:187], s[28:29], 0, v[168:169]
	s_add_i32 m0, s46, 0xe000
	s_nop 0
	global_load_lds_dwordx4 v[186:187], off
	s_waitcnt vmcnt(8)
	s_waitcnt lgkmcnt(0)
	s_setprio 1
	s_barrier
	v_mfma_f32_16x16x32_bf16 v[126:129], v[130:133], v[174:177], v[126:129]
	v_mfma_f32_16x16x32_bf16 v[122:125], v[138:141], v[174:177], v[122:125]
	v_mfma_f32_16x16x32_bf16 v[110:113], v[130:133], v[182:185], v[110:113]
	v_mfma_f32_16x16x32_bf16 v[106:109], v[138:141], v[182:185], v[106:109]
	v_mfma_f32_16x16x32_bf16 v[94:97], v[130:133], v[200:203], v[94:97]
	v_mfma_f32_16x16x32_bf16 v[90:93], v[138:141], v[200:203], v[90:93]
	v_mfma_f32_16x16x32_bf16 v[78:81], v[130:133], v[208:211], v[78:81]
	v_mfma_f32_16x16x32_bf16 v[74:77], v[138:141], v[208:211], v[74:77]
	v_mfma_f32_16x16x32_bf16 v[126:129], v[134:137], v[178:181], v[126:129]
	v_mfma_f32_16x16x32_bf16 v[122:125], v[142:145], v[178:181], v[122:125]
	v_mfma_f32_16x16x32_bf16 v[110:113], v[134:137], v[196:199], v[110:113]
	v_mfma_f32_16x16x32_bf16 v[106:109], v[142:145], v[196:199], v[106:109]
	v_mfma_f32_16x16x32_bf16 v[94:97], v[134:137], v[204:207], v[94:97]
	v_mfma_f32_16x16x32_bf16 v[90:93], v[142:145], v[204:207], v[90:93]
	v_mfma_f32_16x16x32_bf16 v[78:81], v[134:137], v[222:225], v[78:81]
	v_mfma_f32_16x16x32_bf16 v[74:77], v[142:145], v[222:225], v[74:77]
	v_mfma_f32_16x16x32_bf16 v[118:121], v[146:149], v[174:177], v[118:121]
	v_mfma_f32_16x16x32_bf16 v[114:117], v[154:157], v[174:177], v[114:117]
	v_mfma_f32_16x16x32_bf16 v[102:105], v[146:149], v[182:185], v[102:105]
	v_mfma_f32_16x16x32_bf16 v[98:101], v[154:157], v[182:185], v[98:101]
	v_mfma_f32_16x16x32_bf16 v[86:89], v[146:149], v[200:203], v[86:89]
	v_mfma_f32_16x16x32_bf16 v[82:85], v[154:157], v[200:203], v[82:85]
	v_mfma_f32_16x16x32_bf16 v[70:73], v[146:149], v[208:211], v[70:73]
	v_mfma_f32_16x16x32_bf16 v[66:69], v[154:157], v[208:211], v[66:69]
	v_mfma_f32_16x16x32_bf16 v[118:121], v[150:153], v[178:181], v[118:121]
	v_mfma_f32_16x16x32_bf16 v[114:117], v[170:173], v[178:181], v[114:117]
	v_mfma_f32_16x16x32_bf16 v[102:105], v[150:153], v[196:199], v[102:105]
	v_mfma_f32_16x16x32_bf16 v[98:101], v[170:173], v[196:199], v[98:101]
	v_mfma_f32_16x16x32_bf16 v[86:89], v[150:153], v[204:207], v[86:89]
	v_mfma_f32_16x16x32_bf16 v[82:85], v[170:173], v[204:207], v[82:85]
	v_mfma_f32_16x16x32_bf16 v[70:73], v[150:153], v[222:225], v[70:73]
	v_mfma_f32_16x16x32_bf16 v[66:69], v[170:173], v[222:225], v[66:69]
	s_barrier
	s_setprio 0
	s_add_i32 s58, s58, s26
	v_lshl_add_u64 v[186:187], s[30:31], 0, v[0:1]
	s_mov_b32 m0, s58
	ds_read_b128 v[174:177], v191 offset:16384
	ds_read_b128 v[178:181], v191 offset:17408
	ds_read_b128 v[182:185], v191 offset:18432
	ds_read_b128 v[196:199], v191 offset:19456
	ds_read_b128 v[200:203], v191 offset:20480
	ds_read_b128 v[204:207], v191 offset:21504
	ds_read_b128 v[208:211], v191 offset:22528
	ds_read_b128 v[222:225], v191 offset:23552
	global_load_lds_dwordx4 v[186:187], off
	s_add_i32 m0, s58, 0x2000
	s_add_u32 s58, s30, 0x40000
	v_lshl_add_u64 v[192:193], s[30:31], 0, v[158:159]
	s_addc_u32 s59, s31, 0
	s_add_i32 s25, s25, s26
	global_load_lds_dwordx4 v[192:193], off
	v_lshl_add_u64 v[212:213], s[58:59], 0, v[0:1]
	s_mov_b32 m0, s25
	v_lshl_add_u64 v[226:227], s[44:45], 0, v[160:161]
	global_load_lds_dwordx4 v[212:213], off
	v_lshl_add_u64 v[212:213], s[58:59], 0, v[158:159]
	s_add_i32 m0, s25, 0x2000
	s_nop 0
	global_load_lds_dwordx4 v[212:213], off
	v_lshl_add_u64 v[212:213], s[44:45], 0, v[162:163]
	s_mov_b32 m0, s46
	s_nop 0
	global_load_lds_dwordx4 v[212:213], off
	s_mov_b32 m0, s47
	s_nop 0
	global_load_lds_dwordx4 v[226:227], off
	s_waitcnt vmcnt(8)
	s_waitcnt lgkmcnt(0)
	s_setprio 1
	s_barrier
; #define PG8_STAGE(bufoff, gbase, voff) do { _Pragma("unroll") for (int _i = 0; _i < 2; ++_i) \
;         __builtin_amdgcn_global_load_lds((const unsigned*)((const char*)(gbase) + (voff)[_i]), (PG8_LAS unsigned*)(lds + (bufoff) + ldsw + _i * 8192), 16, 0, 0); } while (0)
; #define PG8_LDA(dst, b, h) do { _Pragma("unroll") for (int m = 0; m < 4; ++m) _Pragma("unroll") for (int k = 0; k < 2; ++k) dst[m][k] = *(const PG8_LAS bf16x8*)(lds + PG8_SA(b, h) + aoff + m * 2048 + k * 1024); } while (0)
; #define PG8_LDB(dst, b, h) do { _Pragma("unroll") for (int n = 0; n < 2; ++n) _Pragma("unroll") for (int k = 0; k < 2; ++k) dst[n][k] = *(const PG8_LAS bf16x8*)(lds + PG8_SB(b, h) + boff + n * 2048 + k * 1024); } while (0)
; #define PG8_MMA(ai, bj, At, Bt) do { __builtin_amdgcn_s_setprio(1); _Pragma("unroll") for (int m = 0; m < 4; ++m) _Pragma("unroll") for (int n = 0; n < 2; ++n) _Pragma("unroll") for (int k = 0; k < 2; ++k) \
;         acc[ai][bj][m][n] = __builtin_amdgcn_mfma_f32_16x16x32_bf16(Bt[n][k], At[m][k], acc[ai][bj][m][n], 0, 0, 0); __builtin_amdgcn_s_setprio(0); } while (0)
; #define PG8_BAR __builtin_amdgcn_s_barrier()
; template <class Epi, class Sched, bool ALIGN_EPI = false, bool SP2 = false>
; __device__ __forceinline__ void gemm_phase(PG8_LAS unsigned char* lds, const Gemm g, const Sched& S, const Epi& E, int wv) {
;     ...
;             PG8_LDB(B0, 0, 0); PG8_LDB(B1, 0, 1); PG8_SCHED; PG8_LDA(At, 0, 0); PG8_STAGE(PG8_SA(1, 1), a1 + hstepA, voffA);
;             PG8_WAIT_V(8); PG8_WAIT_L(0); PG8_BAR; PG8_MMA(0, 0, At, B0); PG8_MMA(0, 1, At, B1); PG8_BAR; PG8_SCHED;
;             PG8_LDA(At, 0, 1); PG8_STAGE(PG8_SB(0, 0), b2, voffB); PG8_STAGE(PG8_SB(0, 1), b2 + hstep, voffB); PG8_STAGE(PG8_SA(0, 0), a2, voffA);
;             PG8_WAIT_V(8); PG8_WAIT_L(0); PG8_BAR; PG8_MMA(1, 0, At, B0); PG8_MMA(1, 1, At, B1); PG8_BAR; PG8_SCHED;
;             PG8_LDB(B0, 1, 0); PG8_LDB(B1, 1, 1); PG8_SCHED; PG8_LDA(At, 1, 0); PG8_STAGE(PG8_SA(0, 1), a2 + hstepA, voffA);
;             PG8_WAIT_V(8); PG8_WAIT_L(0); PG8_BAR; PG8_MMA(0, 0, At, B0); PG8_MMA(0, 1, At, B1); PG8_BAR; PG8_SCHED;
;             PG8_LDA(At, 1, 1); PG8_STAGE(PG8_SB(1, 0), b3, voffB); PG8_STAGE(PG8_SB(1, 1), b3 + hstep, voffB); PG8_STAGE(PG8_SA(1, 0), a3, voffA);
;             PG8_WAIT_V(8); PG8_WAIT_L(0); PG8_BAR; PG8_MMA(1, 0, At, B0); PG8_MMA(1, 1, At, B1); PG8_BAR; PG8_SCHED;
	v_mfma_f32_16x16x32_bf16 v[62:65], v[130:133], v[174:177], v[62:65]
	v_mfma_f32_16x16x32_bf16 v[58:61], v[138:141], v[174:177], v[58:61]
	v_mfma_f32_16x16x32_bf16 v[46:49], v[130:133], v[182:185], v[46:49]
	v_mfma_f32_16x16x32_bf16 v[42:45], v[138:141], v[182:185], v[42:45]
	v_mfma_f32_16x16x32_bf16 v[30:33], v[130:133], v[200:203], v[30:33]
	v_mfma_f32_16x16x32_bf16 v[26:29], v[138:141], v[200:203], v[26:29]
	v_mfma_f32_16x16x32_bf16 v[14:17], v[130:133], v[208:211], v[14:17]
	v_mfma_f32_16x16x32_bf16 v[10:13], v[138:141], v[208:211], v[10:13]
	v_mfma_f32_16x16x32_bf16 v[62:65], v[134:137], v[178:181], v[62:65]
	v_mfma_f32_16x16x32_bf16 v[58:61], v[142:145], v[178:181], v[58:61]
	v_mfma_f32_16x16x32_bf16 v[46:49], v[134:137], v[196:199], v[46:49]
	v_mfma_f32_16x16x32_bf16 v[42:45], v[142:145], v[196:199], v[42:45]
	v_mfma_f32_16x16x32_bf16 v[30:33], v[134:137], v[204:207], v[30:33]
	v_mfma_f32_16x16x32_bf16 v[26:29], v[142:145], v[204:207], v[26:29]
	v_mfma_f32_16x16x32_bf16 v[14:17], v[134:137], v[222:225], v[14:17]
	v_mfma_f32_16x16x32_bf16 v[10:13], v[142:145], v[222:225], v[10:13]
	v_mfma_f32_16x16x32_bf16 v[54:57], v[146:149], v[174:177], v[54:57]
	v_mfma_f32_16x16x32_bf16 v[50:53], v[154:157], v[174:177], v[50:53]
	v_mfma_f32_16x16x32_bf16 v[38:41], v[146:149], v[182:185], v[38:41]
	v_mfma_f32_16x16x32_bf16 v[34:37], v[154:157], v[182:185], v[34:37]
	v_mfma_f32_16x16x32_bf16 v[22:25], v[146:149], v[200:203], v[22:25]
	v_mfma_f32_16x16x32_bf16 v[18:21], v[154:157], v[200:203], v[18:21]
	v_mfma_f32_16x16x32_bf16 v[6:9], v[146:149], v[208:211], v[6:9]
	v_mfma_f32_16x16x32_bf16 v[2:5], v[154:157], v[208:211], v[2:5]
	v_mfma_f32_16x16x32_bf16 v[54:57], v[150:153], v[178:181], v[54:57]
	v_mfma_f32_16x16x32_bf16 v[50:53], v[170:173], v[178:181], v[50:53]
	v_mfma_f32_16x16x32_bf16 v[38:41], v[150:153], v[196:199], v[38:41]
	v_mfma_f32_16x16x32_bf16 v[34:37], v[170:173], v[196:199], v[34:37]
	v_mfma_f32_16x16x32_bf16 v[22:25], v[150:153], v[204:207], v[22:25]
	v_mfma_f32_16x16x32_bf16 v[18:21], v[170:173], v[204:207], v[18:21]
	v_mfma_f32_16x16x32_bf16 v[6:9], v[150:153], v[222:225], v[6:9]
	v_mfma_f32_16x16x32_bf16 v[2:5], v[170:173], v[222:225], v[2:5]
	s_barrier
	s_setprio 0
	s_add_i32 s25, 0, 0x18000
	s_add_i32 s58, 0, 0x1c000
	v_add_u32_e32 v142, s25, v189
	v_add_u32_e32 v170, s58, v189
	ds_read_b128 v[130:133], v142
	ds_read_b128 v[134:137], v142 offset:1024
	ds_read_b128 v[138:141], v142 offset:2048
	ds_read_b128 v[142:145], v142 offset:3072
	ds_read_b128 v[146:149], v170
	ds_read_b128 v[150:153], v170 offset:1024
	ds_read_b128 v[154:157], v170 offset:2048
	ds_read_b128 v[170:173], v170 offset:3072
	s_add_u32 s44, s44, 0x40000
	s_addc_u32 s45, s45, 0
	s_mov_b32 m0, s48
	v_lshl_add_u64 v[228:229], s[44:45], 0, v[162:163]
	ds_read_b128 v[174:177], v191 offset:32768
	ds_read_b128 v[178:181], v191 offset:33792
	ds_read_b128 v[182:185], v191 offset:34816
	ds_read_b128 v[196:199], v191 offset:35840
	ds_read_b128 v[200:203], v191 offset:36864
	ds_read_b128 v[204:207], v191 offset:37888
	ds_read_b128 v[208:211], v191 offset:38912
	ds_read_b128 v[222:225], v191 offset:39936
	global_load_lds_dwordx4 v[228:229], off
	v_lshl_add_u64 v[228:229], s[44:45], 0, v[160:161]
	s_mov_b32 m0, s49
	s_nop 0
	global_load_lds_dwordx4 v[228:229], off
	s_waitcnt vmcnt(8)
	s_waitcnt lgkmcnt(0)
	s_setprio 1
	s_barrier
	v_mfma_f32_16x16x32_bf16 v[126:129], v[130:133], v[174:177], v[126:129]
	v_mfma_f32_16x16x32_bf16 v[122:125], v[138:141], v[174:177], v[122:125]
	v_mfma_f32_16x16x32_bf16 v[110:113], v[130:133], v[182:185], v[110:113]
	v_mfma_f32_16x16x32_bf16 v[106:109], v[138:141], v[182:185], v[106:109]
	v_mfma_f32_16x16x32_bf16 v[94:97], v[130:133], v[200:203], v[94:97]
	v_mfma_f32_16x16x32_bf16 v[90:93], v[138:141], v[200:203], v[90:93]
	v_mfma_f32_16x16x32_bf16 v[78:81], v[130:133], v[208:211], v[78:81]
	v_mfma_f32_16x16x32_bf16 v[74:77], v[138:141], v[208:211], v[74:77]
	v_mfma_f32_16x16x32_bf16 v[126:129], v[134:137], v[178:181], v[126:129]
	v_mfma_f32_16x16x32_bf16 v[122:125], v[142:145], v[178:181], v[122:125]
	v_mfma_f32_16x16x32_bf16 v[110:113], v[134:137], v[196:199], v[110:113]
	v_mfma_f32_16x16x32_bf16 v[106:109], v[142:145], v[196:199], v[106:109]
	v_mfma_f32_16x16x32_bf16 v[94:97], v[134:137], v[204:207], v[94:97]
	v_mfma_f32_16x16x32_bf16 v[90:93], v[142:145], v[204:207], v[90:93]
	v_mfma_f32_16x16x32_bf16 v[78:81], v[134:137], v[222:225], v[78:81]
	v_mfma_f32_16x16x32_bf16 v[74:77], v[142:145], v[222:225], v[74:77]
	v_mfma_f32_16x16x32_bf16 v[118:121], v[146:149], v[174:177], v[118:121]
	v_mfma_f32_16x16x32_bf16 v[114:117], v[154:157], v[174:177], v[114:117]
	v_mfma_f32_16x16x32_bf16 v[102:105], v[146:149], v[182:185], v[102:105]
	v_mfma_f32_16x16x32_bf16 v[98:101], v[154:157], v[182:185], v[98:101]
	v_mfma_f32_16x16x32_bf16 v[86:89], v[146:149], v[200:203], v[86:89]
	v_mfma_f32_16x16x32_bf16 v[82:85], v[154:157], v[200:203], v[82:85]
	v_mfma_f32_16x16x32_bf16 v[70:73], v[146:149], v[208:211], v[70:73]
	v_mfma_f32_16x16x32_bf16 v[66:69], v[154:157], v[208:211], v[66:69]
	v_mfma_f32_16x16x32_bf16 v[118:121], v[150:153], v[178:181], v[118:121]
	v_mfma_f32_16x16x32_bf16 v[114:117], v[170:173], v[178:181], v[114:117]
	v_mfma_f32_16x16x32_bf16 v[102:105], v[150:153], v[196:199], v[102:105]
	v_mfma_f32_16x16x32_bf16 v[98:101], v[170:173], v[196:199], v[98:101]
	v_mfma_f32_16x16x32_bf16 v[86:89], v[150:153], v[204:207], v[86:89]
	v_mfma_f32_16x16x32_bf16 v[82:85], v[170:173], v[204:207], v[82:85]
	v_mfma_f32_16x16x32_bf16 v[70:73], v[150:153], v[222:225], v[70:73]
	v_mfma_f32_16x16x32_bf16 v[66:69], v[170:173], v[222:225], v[66:69]
	s_barrier
; #define PG8_STAGE(bufoff, gbase, voff) do { _Pragma("unroll") for (int _i = 0; _i < 2; ++_i) \
;         __builtin_amdgcn_global_load_lds((const unsigned*)((const char*)(gbase) + (voff)[_i]), (PG8_LAS unsigned*)(lds + (bufoff) + ldsw + _i * 8192), 16, 0, 0); } while (0)
; #define PG8_LDA(dst, b, h) do { _Pragma("unroll") for (int m = 0; m < 4; ++m) _Pragma("unroll") for (int k = 0; k < 2; ++k) dst[m][k] = *(const PG8_LAS bf16x8*)(lds + PG8_SA(b, h) + aoff + m * 2048 + k * 1024); } while (0)
; #define PG8_MMA(ai, bj, At, Bt) do { __builtin_amdgcn_s_setprio(1); _Pragma("unroll") for (int m = 0; m < 4; ++m) _Pragma("unroll") for (int n = 0; n < 2; ++n) _Pragma("unroll") for (int k = 0; k < 2; ++k) \
;         acc[ai][bj][m][n] = __builtin_amdgcn_mfma_f32_16x16x32_bf16(Bt[n][k], At[m][k], acc[ai][bj][m][n], 0, 0, 0); __builtin_amdgcn_s_setprio(0); } while (0)
; #define PG8_WAIT_V(n) asm volatile("s_waitcnt vmcnt(" #n ")" ::: "memory")
; #define PG8_WAIT_L(n) asm volatile("s_waitcnt lgkmcnt(" #n ")" ::: "memory")
; #define PG8_BAR __builtin_amdgcn_s_barrier()
; #define PG8_SCHED __builtin_amdgcn_sched_barrier(0)
; template <class Epi, class Sched, bool ALIGN_EPI = false, bool SP2 = false>
; __device__ __forceinline__ void gemm_phase(PG8_LAS unsigned char* lds, const Gemm g, const Sched& S, const Epi& E, int wv) {
;     ...
;             PG8_LDA(At, 1, 1); PG8_STAGE(PG8_SB(1, 0), b3, voffB); PG8_STAGE(PG8_SB(1, 1), b3 + hstep, voffB); PG8_STAGE(PG8_SA(1, 0), a3, voffA);
;             PG8_WAIT_V(8); PG8_WAIT_L(0); PG8_BAR; PG8_MMA(1, 0, At, B0); PG8_MMA(1, 1, At, B1); PG8_BAR; PG8_SCHED;
;     ...
;         if constexpr (ALIGN_EPI) { if (wr == 0) PG8_BAR; }
	s_setprio 0
	s_add_i32 s25, s25, s26
	v_lshl_add_u64 v[186:187], v[186:187], 0, s[14:15]
	s_mov_b32 m0, s25
	ds_read_b128 v[174:177], v191 offset:49152
	ds_read_b128 v[178:181], v191 offset:50176
	ds_read_b128 v[182:185], v191 offset:51200
	ds_read_b128 v[196:199], v191 offset:52224
	ds_read_b128 v[200:203], v191 offset:53248
	ds_read_b128 v[204:207], v191 offset:54272
	ds_read_b128 v[208:211], v191 offset:55296
	ds_read_b128 v[222:225], v191 offset:56320
	global_load_lds_dwordx4 v[186:187], off
	s_add_i32 m0, s25, 0x2000
	s_add_u32 s30, s30, 0x40080
	v_lshl_add_u64 v[186:187], v[192:193], 0, s[14:15]
	s_addc_u32 s31, s31, 0
	s_add_i32 s25, s58, s26
	global_load_lds_dwordx4 v[186:187], off
	v_lshl_add_u64 v[186:187], s[30:31], 0, v[0:1]
	s_mov_b32 m0, s25
	s_nop 0
	global_load_lds_dwordx4 v[186:187], off
	v_lshl_add_u64 v[186:187], s[30:31], 0, v[158:159]
	s_add_i32 m0, s25, 0x2000
	s_nop 0
	global_load_lds_dwordx4 v[186:187], off
	v_lshl_add_u64 v[186:187], v[212:213], 0, s[14:15]
	s_mov_b32 m0, s51
	s_nop 0
	global_load_lds_dwordx4 v[186:187], off
	v_lshl_add_u64 v[186:187], v[226:227], 0, s[14:15]
	s_mov_b32 m0, s52
	s_nop 0
	global_load_lds_dwordx4 v[186:187], off
	s_waitcnt vmcnt(8)
	s_waitcnt lgkmcnt(0)
	s_setprio 1
	s_barrier
	v_mfma_f32_16x16x32_bf16 v[62:65], v[130:133], v[174:177], v[62:65]
	v_mfma_f32_16x16x32_bf16 v[58:61], v[138:141], v[174:177], v[58:61]
	v_mfma_f32_16x16x32_bf16 v[46:49], v[130:133], v[182:185], v[46:49]
	v_mfma_f32_16x16x32_bf16 v[42:45], v[138:141], v[182:185], v[42:45]
	v_mfma_f32_16x16x32_bf16 v[30:33], v[130:133], v[200:203], v[30:33]
	v_mfma_f32_16x16x32_bf16 v[26:29], v[138:141], v[200:203], v[26:29]
	v_mfma_f32_16x16x32_bf16 v[14:17], v[130:133], v[208:211], v[14:17]
	v_mfma_f32_16x16x32_bf16 v[10:13], v[138:141], v[208:211], v[10:13]
	v_mfma_f32_16x16x32_bf16 v[62:65], v[134:137], v[178:181], v[62:65]
	v_mfma_f32_16x16x32_bf16 v[58:61], v[142:145], v[178:181], v[58:61]
	v_mfma_f32_16x16x32_bf16 v[46:49], v[134:137], v[196:199], v[46:49]
	v_mfma_f32_16x16x32_bf16 v[42:45], v[142:145], v[196:199], v[42:45]
	v_mfma_f32_16x16x32_bf16 v[30:33], v[134:137], v[204:207], v[30:33]
	v_mfma_f32_16x16x32_bf16 v[26:29], v[142:145], v[204:207], v[26:29]
	v_mfma_f32_16x16x32_bf16 v[14:17], v[134:137], v[222:225], v[14:17]
	v_mfma_f32_16x16x32_bf16 v[10:13], v[142:145], v[222:225], v[10:13]
	v_mfma_f32_16x16x32_bf16 v[54:57], v[146:149], v[174:177], v[54:57]
	v_mfma_f32_16x16x32_bf16 v[50:53], v[154:157], v[174:177], v[50:53]
	v_mfma_f32_16x16x32_bf16 v[38:41], v[146:149], v[182:185], v[38:41]
	v_mfma_f32_16x16x32_bf16 v[34:37], v[154:157], v[182:185], v[34:37]
	v_mfma_f32_16x16x32_bf16 v[22:25], v[146:149], v[200:203], v[22:25]
	v_mfma_f32_16x16x32_bf16 v[18:21], v[154:157], v[200:203], v[18:21]
	v_mfma_f32_16x16x32_bf16 v[6:9], v[146:149], v[208:211], v[6:9]
	v_mfma_f32_16x16x32_bf16 v[2:5], v[154:157], v[208:211], v[2:5]
	v_mfma_f32_16x16x32_bf16 v[54:57], v[150:153], v[178:181], v[54:57]
	v_mfma_f32_16x16x32_bf16 v[50:53], v[170:173], v[178:181], v[50:53]
	v_mfma_f32_16x16x32_bf16 v[38:41], v[150:153], v[196:199], v[38:41]
	v_mfma_f32_16x16x32_bf16 v[34:37], v[170:173], v[196:199], v[34:37]
	v_mfma_f32_16x16x32_bf16 v[22:25], v[150:153], v[204:207], v[22:25]
	v_mfma_f32_16x16x32_bf16 v[18:21], v[170:173], v[204:207], v[18:21]
	v_mfma_f32_16x16x32_bf16 v[6:9], v[150:153], v[222:225], v[6:9]
	v_mfma_f32_16x16x32_bf16 v[2:5], v[170:173], v[222:225], v[2:5]
	s_barrier
	s_setprio 0
	s_add_i32 s57, s57, 2
	s_add_u32 s28, s28, 0x100
	s_addc_u32 s29, s29, 0
	s_add_u32 s55, s55, 0x100
	s_addc_u32 s56, s56, 0
	s_cmp_gt_u32 s57, 13
	s_cbranch_scc0 .LBB0_1147
	s_and_b64 vcc, exec, s[10:11]
	s_cbranch_vccz .LBB0_1150
	s_barrier

; #define PG8_STAGE(bufoff, gbase, voff) do { _Pragma("unroll") for (int _i = 0; _i < 2; ++_i) \
;         __builtin_amdgcn_global_load_lds((const unsigned*)((const char*)(gbase) + (voff)[_i]), (PG8_LAS unsigned*)(lds + (bufoff) + ldsw + _i * 8192), 16, 0, 0); } while (0)
; #define PG8_LDA(dst, b, h) do { _Pragma("unroll") for (int m = 0; m < 4; ++m) _Pragma("unroll") for (int k = 0; k < 2; ++k) dst[m][k] = *(const PG8_LAS bf16x8*)(lds + PG8_SA(b, h) + aoff + m * 2048 + k * 1024); } while (0)
; #define PG8_LDB(dst, b, h) do { _Pragma("unroll") for (int n = 0; n < 2; ++n) _Pragma("unroll") for (int k = 0; k < 2; ++k) dst[n][k] = *(const PG8_LAS bf16x8*)(lds + PG8_SB(b, h) + boff + n * 2048 + k * 1024); } while (0)
; #define PG8_MMA(ai, bj, At, Bt) do { __builtin_amdgcn_s_setprio(1); _Pragma("unroll") for (int m = 0; m < 4; ++m) _Pragma("unroll") for (int n = 0; n < 2; ++n) _Pragma("unroll") for (int k = 0; k < 2; ++k) \
;         acc[ai][bj][m][n] = __builtin_amdgcn_mfma_f32_16x16x32_bf16(Bt[n][k], At[m][k], acc[ai][bj][m][n], 0, 0, 0); __builtin_amdgcn_s_setprio(0); } while (0)
; #define PG8_WAIT_V(n) asm volatile("s_waitcnt vmcnt(" #n ")" ::: "memory")
; #define PG8_WAIT_L(n) asm volatile("s_waitcnt lgkmcnt(" #n ")" ::: "memory")
; #define PG8_BAR __builtin_amdgcn_s_barrier()
; #define PG8_SCHED __builtin_amdgcn_sched_barrier(0)
; template <class Epi, class Sched, bool ALIGN_EPI = false, bool SP2 = false>
; __device__ __forceinline__ void gemm_phase(PG8_LAS unsigned char* lds, const Gemm g, const Sched& S, const Epi& E, int wv) {
;     ...
;             const bool last = (t == nt - 2);
;             const char* a1 = cA + (size_t)(t + 1) * kstep;
;             const char* a2 = last ? nA : cA + (size_t)(t + 2) * kstep; const char* b2 = last ? nB : cB + (size_t)(t + 2) * kstep;
;             const char* a3 = a2 + kstep; const char* b3 = b2 + kstep;
;             if (last && has_next) S.a_ready(nxt);
;             if constexpr (SP2) {
;             PG8_LDB(B0, 0, 0); PG8_LDB(B1, 0, 1); PG8_SCHED; PG8_LDA(At, 0, 0); PG8_STAGE(PG8_SA(1, 1), a1 + hstepA, voffA);
;             PG8_WAIT_V(8); PG8_WAIT_L(0); PG8_BAR; PG8_MMA(0, 0, At, B0); PG8_MMA(0, 1, At, B1); PG8_BAR; PG8_SCHED;
;             PG8_LDA(At, 0, 1); PG8_STAGE(PG8_SB(0, 0), b2, voffB); PG8_STAGE(PG8_SB(0, 1), b2 + hstep, voffB); PG8_STAGE(PG8_SA(0, 0), a2, voffA);
.LBB0_1231:
	s_add_u32 s25, s36, 0xfffc0080
	s_addc_u32 s38, s37, -1
	s_add_i32 s53, 0, 0x10000
	s_cmp_eq_u32 s52, 12
	s_cselect_b32 s41, s16, s38
	s_cselect_b32 s40, s17, s25
	s_cselect_b32 s39, s11, s51
	s_cselect_b32 s38, s29, s50
	s_add_i32 s25, 0, 0x14000
	v_add_u32_e32 v154, s53, v171
	v_add_u32_e32 v166, s25, v171
	ds_read_b128 v[130:133], v154
	ds_read_b128 v[134:137], v154 offset:1024
	ds_read_b128 v[138:141], v154 offset:2048
	ds_read_b128 v[154:157], v154 offset:3072
	ds_read_b128 v[158:161], v166
	ds_read_b128 v[162:165], v166 offset:1024
	ds_read_b128 v[178:181], v166 offset:2048
	ds_read_b128 v[182:185], v166 offset:3072
	v_lshl_add_u64 v[168:169], s[36:37], 0, v[150:151]
	s_add_i32 m0, s26, 0xc000
	ds_read_b128 v[186:189], v177
	ds_read_b128 v[190:193], v177 offset:1024
	ds_read_b128 v[196:199], v177 offset:2048
	ds_read_b128 v[200:203], v177 offset:3072
	ds_read_b128 v[204:207], v177 offset:4096
	ds_read_b128 v[208:211], v177 offset:5120
	ds_read_b128 v[222:225], v177 offset:6144
	ds_read_b128 v[226:229], v177 offset:7168
	global_load_lds_dwordx4 v[168:169], off
	v_lshl_add_u64 v[168:169], s[36:37], 0, v[152:153]
	s_add_i32 m0, s26, 0xe000
	s_nop 0
	global_load_lds_dwordx4 v[168:169], off
	s_waitcnt vmcnt(8)
	s_waitcnt lgkmcnt(0)
	s_setprio 1
	s_barrier
	v_mfma_f32_16x16x32_bf16 v[126:129], v[130:133], v[186:189], v[126:129]
	v_mfma_f32_16x16x32_bf16 v[122:125], v[138:141], v[186:189], v[122:125]
	v_mfma_f32_16x16x32_bf16 v[110:113], v[130:133], v[196:199], v[110:113]
	v_mfma_f32_16x16x32_bf16 v[106:109], v[138:141], v[196:199], v[106:109]
	v_mfma_f32_16x16x32_bf16 v[94:97], v[130:133], v[204:207], v[94:97]
	v_mfma_f32_16x16x32_bf16 v[90:93], v[138:141], v[204:207], v[90:93]
	v_mfma_f32_16x16x32_bf16 v[78:81], v[130:133], v[222:225], v[78:81]
	v_mfma_f32_16x16x32_bf16 v[74:77], v[138:141], v[222:225], v[74:77]
	v_mfma_f32_16x16x32_bf16 v[126:129], v[134:137], v[190:193], v[126:129]
	v_mfma_f32_16x16x32_bf16 v[122:125], v[154:157], v[190:193], v[122:125]
	v_mfma_f32_16x16x32_bf16 v[110:113], v[134:137], v[200:203], v[110:113]
	v_mfma_f32_16x16x32_bf16 v[106:109], v[154:157], v[200:203], v[106:109]
	v_mfma_f32_16x16x32_bf16 v[94:97], v[134:137], v[208:211], v[94:97]
	v_mfma_f32_16x16x32_bf16 v[90:93], v[154:157], v[208:211], v[90:93]
	v_mfma_f32_16x16x32_bf16 v[78:81], v[134:137], v[226:229], v[78:81]
	v_mfma_f32_16x16x32_bf16 v[74:77], v[154:157], v[226:229], v[74:77]
	v_mfma_f32_16x16x32_bf16 v[118:121], v[158:161], v[186:189], v[118:121]
	v_mfma_f32_16x16x32_bf16 v[114:117], v[178:181], v[186:189], v[114:117]
	v_mfma_f32_16x16x32_bf16 v[102:105], v[158:161], v[196:199], v[102:105]
	v_mfma_f32_16x16x32_bf16 v[98:101], v[178:181], v[196:199], v[98:101]
	v_mfma_f32_16x16x32_bf16 v[86:89], v[158:161], v[204:207], v[86:89]
	v_mfma_f32_16x16x32_bf16 v[82:85], v[178:181], v[204:207], v[82:85]
	v_mfma_f32_16x16x32_bf16 v[70:73], v[158:161], v[222:225], v[70:73]
	v_mfma_f32_16x16x32_bf16 v[66:69], v[178:181], v[222:225], v[66:69]
	v_mfma_f32_16x16x32_bf16 v[118:121], v[162:165], v[190:193], v[118:121]
	v_mfma_f32_16x16x32_bf16 v[114:117], v[182:185], v[190:193], v[114:117]
	v_mfma_f32_16x16x32_bf16 v[102:105], v[162:165], v[200:203], v[102:105]
	v_mfma_f32_16x16x32_bf16 v[98:101], v[182:185], v[200:203], v[98:101]
	v_mfma_f32_16x16x32_bf16 v[86:89], v[162:165], v[208:211], v[86:89]
	v_mfma_f32_16x16x32_bf16 v[82:85], v[182:185], v[208:211], v[82:85]
	v_mfma_f32_16x16x32_bf16 v[70:73], v[162:165], v[226:229], v[70:73]
	v_mfma_f32_16x16x32_bf16 v[66:69], v[182:185], v[226:229], v[66:69]
	s_barrier
	s_setprio 0
	s_add_i32 s53, s53, s24
	v_lshl_add_u64 v[168:169], s[38:39], 0, v[0:1]
	s_mov_b32 m0, s53
	ds_read_b128 v[186:189], v177 offset:16384
	ds_read_b128 v[190:193], v177 offset:17408
	ds_read_b128 v[196:199], v177 offset:18432
	ds_read_b128 v[200:203], v177 offset:19456
	ds_read_b128 v[204:207], v177 offset:20480
	ds_read_b128 v[208:211], v177 offset:21504
	ds_read_b128 v[222:225], v177 offset:22528
	ds_read_b128 v[226:229], v177 offset:23552
	global_load_lds_dwordx4 v[168:169], off
	s_add_i32 m0, s53, 0x2000
	s_add_u32 s54, s38, 0x40000
	v_lshl_add_u64 v[174:175], s[38:39], 0, v[142:143]
	s_addc_u32 s55, s39, 0
	s_add_i32 s25, s25, s24
	global_load_lds_dwordx4 v[174:175], off
	v_lshl_add_u64 v[212:213], s[54:55], 0, v[0:1]
	s_mov_b32 m0, s25
	v_lshl_add_u64 v[230:231], s[40:41], 0, v[144:145]
	global_load_lds_dwordx4 v[212:213], off
	v_lshl_add_u64 v[212:213], s[54:55], 0, v[142:143]
	s_add_i32 m0, s25, 0x2000
	s_nop 0
	global_load_lds_dwordx4 v[212:213], off
	v_lshl_add_u64 v[212:213], s[40:41], 0, v[146:147]
	s_mov_b32 m0, s26
	s_nop 0
	global_load_lds_dwordx4 v[212:213], off
	s_mov_b32 m0, s42
	s_nop 0
	global_load_lds_dwordx4 v[230:231], off
	s_waitcnt vmcnt(8)
	s_waitcnt lgkmcnt(0)
	s_setprio 1
	s_barrier
; #define PG8_STAGE(bufoff, gbase, voff) do { _Pragma("unroll") for (int _i = 0; _i < 2; ++_i) \
;         __builtin_amdgcn_global_load_lds((const unsigned*)((const char*)(gbase) + (voff)[_i]), (PG8_LAS unsigned*)(lds + (bufoff) + ldsw + _i * 8192), 16, 0, 0); } while (0)
; #define PG8_LDA(dst, b, h) do { _Pragma("unroll") for (int m = 0; m < 4; ++m) _Pragma("unroll") for (int k = 0; k < 2; ++k) dst[m][k] = *(const PG8_LAS bf16x8*)(lds + PG8_SA(b, h) + aoff + m * 2048 + k * 1024); } while (0)
; #define PG8_LDB(dst, b, h) do { _Pragma("unroll") for (int n = 0; n < 2; ++n) _Pragma("unroll") for (int k = 0; k < 2; ++k) dst[n][k] = *(const PG8_LAS bf16x8*)(lds + PG8_SB(b, h) + boff + n * 2048 + k * 1024); } while (0)
; #define PG8_MMA(ai, bj, At, Bt) do { __builtin_amdgcn_s_setprio(1); _Pragma("unroll") for (int m = 0; m < 4; ++m) _Pragma("unroll") for (int n = 0; n < 2; ++n) _Pragma("unroll") for (int k = 0; k < 2; ++k) \
;         acc[ai][bj][m][n] = __builtin_amdgcn_mfma_f32_16x16x32_bf16(Bt[n][k], At[m][k], acc[ai][bj][m][n], 0, 0, 0); __builtin_amdgcn_s_setprio(0); } while (0)
; #define PG8_WAIT_V(n) asm volatile("s_waitcnt vmcnt(" #n ")" ::: "memory")
; #define PG8_WAIT_L(n) asm volatile("s_waitcnt lgkmcnt(" #n ")" ::: "memory")
; #define PG8_BAR __builtin_amdgcn_s_barrier()
; #define PG8_SCHED __builtin_amdgcn_sched_barrier(0)
; template <class Epi, class Sched, bool ALIGN_EPI = false, bool SP2 = false>
; __device__ __forceinline__ void gemm_phase(PG8_LAS unsigned char* lds, const Gemm g, const Sched& S, const Epi& E, int wv) {
;     ...
;             PG8_WAIT_V(8); PG8_WAIT_L(0); PG8_BAR; PG8_MMA(1, 0, At, B0); PG8_MMA(1, 1, At, B1); PG8_BAR; PG8_SCHED;
;             PG8_LDB(B0, 1, 0); PG8_LDB(B1, 1, 1); PG8_SCHED; PG8_LDA(At, 1, 0); PG8_STAGE(PG8_SA(0, 1), a2 + hstepA, voffA);
;             PG8_WAIT_V(8); PG8_WAIT_L(0); PG8_BAR; PG8_MMA(0, 0, At, B0); PG8_MMA(0, 1, At, B1); PG8_BAR; PG8_SCHED;
	v_mfma_f32_16x16x32_bf16 v[62:65], v[130:133], v[186:189], v[62:65]
	v_mfma_f32_16x16x32_bf16 v[58:61], v[138:141], v[186:189], v[58:61]
	v_mfma_f32_16x16x32_bf16 v[46:49], v[130:133], v[196:199], v[46:49]
	v_mfma_f32_16x16x32_bf16 v[42:45], v[138:141], v[196:199], v[42:45]
	v_mfma_f32_16x16x32_bf16 v[30:33], v[130:133], v[204:207], v[30:33]
	v_mfma_f32_16x16x32_bf16 v[26:29], v[138:141], v[204:207], v[26:29]
	v_mfma_f32_16x16x32_bf16 v[14:17], v[130:133], v[222:225], v[14:17]
	v_mfma_f32_16x16x32_bf16 v[10:13], v[138:141], v[222:225], v[10:13]
	v_mfma_f32_16x16x32_bf16 v[62:65], v[134:137], v[190:193], v[62:65]
	v_mfma_f32_16x16x32_bf16 v[58:61], v[154:157], v[190:193], v[58:61]
	v_mfma_f32_16x16x32_bf16 v[46:49], v[134:137], v[200:203], v[46:49]
	v_mfma_f32_16x16x32_bf16 v[42:45], v[154:157], v[200:203], v[42:45]
	v_mfma_f32_16x16x32_bf16 v[30:33], v[134:137], v[208:211], v[30:33]
	v_mfma_f32_16x16x32_bf16 v[26:29], v[154:157], v[208:211], v[26:29]
	v_mfma_f32_16x16x32_bf16 v[14:17], v[134:137], v[226:229], v[14:17]
	v_mfma_f32_16x16x32_bf16 v[10:13], v[154:157], v[226:229], v[10:13]
	v_mfma_f32_16x16x32_bf16 v[54:57], v[158:161], v[186:189], v[54:57]
	v_mfma_f32_16x16x32_bf16 v[50:53], v[178:181], v[186:189], v[50:53]
	v_mfma_f32_16x16x32_bf16 v[38:41], v[158:161], v[196:199], v[38:41]
	v_mfma_f32_16x16x32_bf16 v[34:37], v[178:181], v[196:199], v[34:37]
	v_mfma_f32_16x16x32_bf16 v[22:25], v[158:161], v[204:207], v[22:25]
	v_mfma_f32_16x16x32_bf16 v[18:21], v[178:181], v[204:207], v[18:21]
	v_mfma_f32_16x16x32_bf16 v[6:9], v[158:161], v[222:225], v[6:9]
	v_mfma_f32_16x16x32_bf16 v[2:5], v[178:181], v[222:225], v[2:5]
	v_mfma_f32_16x16x32_bf16 v[54:57], v[162:165], v[190:193], v[54:57]
	v_mfma_f32_16x16x32_bf16 v[50:53], v[182:185], v[190:193], v[50:53]
	v_mfma_f32_16x16x32_bf16 v[38:41], v[162:165], v[200:203], v[38:41]
	v_mfma_f32_16x16x32_bf16 v[34:37], v[182:185], v[200:203], v[34:37]
	v_mfma_f32_16x16x32_bf16 v[22:25], v[162:165], v[208:211], v[22:25]
	v_mfma_f32_16x16x32_bf16 v[18:21], v[182:185], v[208:211], v[18:21]
	v_mfma_f32_16x16x32_bf16 v[6:9], v[162:165], v[226:229], v[6:9]
	v_mfma_f32_16x16x32_bf16 v[2:5], v[182:185], v[226:229], v[2:5]
	s_barrier
	s_setprio 0
	s_add_i32 s25, 0, 0x18000
	s_add_i32 s53, 0, 0x1c000
	v_add_u32_e32 v154, s25, v171
	v_add_u32_e32 v166, s53, v171
	ds_read_b128 v[130:133], v154
	ds_read_b128 v[134:137], v154 offset:1024
	ds_read_b128 v[138:141], v154 offset:2048
	ds_read_b128 v[154:157], v154 offset:3072
	ds_read_b128 v[158:161], v166
	ds_read_b128 v[162:165], v166 offset:1024
	ds_read_b128 v[178:181], v166 offset:2048
	ds_read_b128 v[182:185], v166 offset:3072
	s_add_u32 s40, s40, 0x40000
	s_addc_u32 s41, s41, 0
	s_mov_b32 m0, s43
	v_lshl_add_u64 v[232:233], s[40:41], 0, v[146:147]
	ds_read_b128 v[186:189], v177 offset:32768
	ds_read_b128 v[190:193], v177 offset:33792
	ds_read_b128 v[196:199], v177 offset:34816
	ds_read_b128 v[200:203], v177 offset:35840
	ds_read_b128 v[204:207], v177 offset:36864
	ds_read_b128 v[208:211], v177 offset:37888
	ds_read_b128 v[222:225], v177 offset:38912
	ds_read_b128 v[226:229], v177 offset:39936
	global_load_lds_dwordx4 v[232:233], off
	v_lshl_add_u64 v[232:233], s[40:41], 0, v[144:145]
	s_mov_b32 m0, s44
	s_nop 0
	global_load_lds_dwordx4 v[232:233], off
	s_waitcnt vmcnt(8)
	s_waitcnt lgkmcnt(0)
	s_setprio 1
	s_barrier
	v_mfma_f32_16x16x32_bf16 v[126:129], v[130:133], v[186:189], v[126:129]
	v_mfma_f32_16x16x32_bf16 v[122:125], v[138:141], v[186:189], v[122:125]
	v_mfma_f32_16x16x32_bf16 v[110:113], v[130:133], v[196:199], v[110:113]
	v_mfma_f32_16x16x32_bf16 v[106:109], v[138:141], v[196:199], v[106:109]
	v_mfma_f32_16x16x32_bf16 v[94:97], v[130:133], v[204:207], v[94:97]
	v_mfma_f32_16x16x32_bf16 v[90:93], v[138:141], v[204:207], v[90:93]
	v_mfma_f32_16x16x32_bf16 v[78:81], v[130:133], v[222:225], v[78:81]
	v_mfma_f32_16x16x32_bf16 v[74:77], v[138:141], v[222:225], v[74:77]
	v_mfma_f32_16x16x32_bf16 v[126:129], v[134:137], v[190:193], v[126:129]
	v_mfma_f32_16x16x32_bf16 v[122:125], v[154:157], v[190:193], v[122:125]
	v_mfma_f32_16x16x32_bf16 v[110:113], v[134:137], v[200:203], v[110:113]
	v_mfma_f32_16x16x32_bf16 v[106:109], v[154:157], v[200:203], v[106:109]
	v_mfma_f32_16x16x32_bf16 v[94:97], v[134:137], v[208:211], v[94:97]
	v_mfma_f32_16x16x32_bf16 v[90:93], v[154:157], v[208:211], v[90:93]
	v_mfma_f32_16x16x32_bf16 v[78:81], v[134:137], v[226:229], v[78:81]
	v_mfma_f32_16x16x32_bf16 v[74:77], v[154:157], v[226:229], v[74:77]
	v_mfma_f32_16x16x32_bf16 v[118:121], v[158:161], v[186:189], v[118:121]
	v_mfma_f32_16x16x32_bf16 v[114:117], v[178:181], v[186:189], v[114:117]
	v_mfma_f32_16x16x32_bf16 v[102:105], v[158:161], v[196:199], v[102:105]
	v_mfma_f32_16x16x32_bf16 v[98:101], v[178:181], v[196:199], v[98:101]
	v_mfma_f32_16x16x32_bf16 v[86:89], v[158:161], v[204:207], v[86:89]
	v_mfma_f32_16x16x32_bf16 v[82:85], v[178:181], v[204:207], v[82:85]
	v_mfma_f32_16x16x32_bf16 v[70:73], v[158:161], v[222:225], v[70:73]
	v_mfma_f32_16x16x32_bf16 v[66:69], v[178:181], v[222:225], v[66:69]
	v_mfma_f32_16x16x32_bf16 v[118:121], v[162:165], v[190:193], v[118:121]
	v_mfma_f32_16x16x32_bf16 v[114:117], v[182:185], v[190:193], v[114:117]
	v_mfma_f32_16x16x32_bf16 v[102:105], v[162:165], v[200:203], v[102:105]
	v_mfma_f32_16x16x32_bf16 v[98:101], v[182:185], v[200:203], v[98:101]
	v_mfma_f32_16x16x32_bf16 v[86:89], v[162:165], v[208:211], v[86:89]
	v_mfma_f32_16x16x32_bf16 v[82:85], v[182:185], v[208:211], v[82:85]
	v_mfma_f32_16x16x32_bf16 v[70:73], v[162:165], v[226:229], v[70:73]
	v_mfma_f32_16x16x32_bf16 v[66:69], v[182:185], v[226:229], v[66:69]
	s_barrier
; #define PG8_STAGE(bufoff, gbase, voff) do { _Pragma("unroll") for (int _i = 0; _i < 2; ++_i) \
;         __builtin_amdgcn_global_load_lds((const unsigned*)((const char*)(gbase) + (voff)[_i]), (PG8_LAS unsigned*)(lds + (bufoff) + ldsw + _i * 8192), 16, 0, 0); } while (0)
; #define PG8_LDA(dst, b, h) do { _Pragma("unroll") for (int m = 0; m < 4; ++m) _Pragma("unroll") for (int k = 0; k < 2; ++k) dst[m][k] = *(const PG8_LAS bf16x8*)(lds + PG8_SA(b, h) + aoff + m * 2048 + k * 1024); } while (0)
; #define PG8_MMA(ai, bj, At, Bt) do { __builtin_amdgcn_s_setprio(1); _Pragma("unroll") for (int m = 0; m < 4; ++m) _Pragma("unroll") for (int n = 0; n < 2; ++n) _Pragma("unroll") for (int k = 0; k < 2; ++k) \
;         acc[ai][bj][m][n] = __builtin_amdgcn_mfma_f32_16x16x32_bf16(Bt[n][k], At[m][k], acc[ai][bj][m][n], 0, 0, 0); __builtin_amdgcn_s_setprio(0); } while (0)
; #define PG8_WAIT_V(n) asm volatile("s_waitcnt vmcnt(" #n ")" ::: "memory")
; #define PG8_WAIT_L(n) asm volatile("s_waitcnt lgkmcnt(" #n ")" ::: "memory")
; #define PG8_BAR __builtin_amdgcn_s_barrier()
; #define PG8_SCHED __builtin_amdgcn_sched_barrier(0)
; template <class Epi, class Sched, bool ALIGN_EPI = false, bool SP2 = false>
; __device__ __forceinline__ void gemm_phase(PG8_LAS unsigned char* lds, const Gemm g, const Sched& S, const Epi& E, int wv) {
;     ...
;             PG8_LDA(At, 1, 1); PG8_STAGE(PG8_SB(1, 0), b3, voffB); PG8_STAGE(PG8_SB(1, 1), b3 + hstep, voffB); PG8_STAGE(PG8_SA(1, 0), a3, voffA);
;             PG8_WAIT_V(8); PG8_WAIT_L(0); PG8_BAR; PG8_MMA(1, 0, At, B0); PG8_MMA(1, 1, At, B1); PG8_BAR; PG8_SCHED;
;     ...
;         if constexpr (ALIGN_EPI) { if (wr == 0) PG8_BAR; }
	s_setprio 0
	s_add_i32 s25, s25, s24
	v_lshl_add_u64 v[168:169], v[168:169], 0, s[14:15]
	s_mov_b32 m0, s25
	ds_read_b128 v[186:189], v177 offset:49152
	ds_read_b128 v[190:193], v177 offset:50176
	ds_read_b128 v[196:199], v177 offset:51200
	ds_read_b128 v[200:203], v177 offset:52224
	ds_read_b128 v[204:207], v177 offset:53248
	ds_read_b128 v[208:211], v177 offset:54272
	ds_read_b128 v[222:225], v177 offset:55296
	ds_read_b128 v[226:229], v177 offset:56320
	global_load_lds_dwordx4 v[168:169], off
	s_add_i32 m0, s25, 0x2000
	s_add_u32 s38, s38, 0x40080
	v_lshl_add_u64 v[168:169], v[174:175], 0, s[14:15]
	s_addc_u32 s39, s39, 0
	s_add_i32 s25, s53, s24
	global_load_lds_dwordx4 v[168:169], off
	v_lshl_add_u64 v[168:169], s[38:39], 0, v[0:1]
	s_mov_b32 m0, s25
	s_nop 0
	global_load_lds_dwordx4 v[168:169], off
	v_lshl_add_u64 v[168:169], s[38:39], 0, v[142:143]
	s_add_i32 m0, s25, 0x2000
	s_nop 0
	global_load_lds_dwordx4 v[168:169], off
	v_lshl_add_u64 v[168:169], v[212:213], 0, s[14:15]
	s_mov_b32 m0, s45
	s_nop 0
	global_load_lds_dwordx4 v[168:169], off
	v_lshl_add_u64 v[168:169], v[230:231], 0, s[14:15]
	s_mov_b32 m0, s46
	s_nop 0
	global_load_lds_dwordx4 v[168:169], off
	s_waitcnt vmcnt(8)
	s_waitcnt lgkmcnt(0)
	s_setprio 1
	s_barrier
	v_mfma_f32_16x16x32_bf16 v[62:65], v[130:133], v[186:189], v[62:65]
	v_mfma_f32_16x16x32_bf16 v[58:61], v[138:141], v[186:189], v[58:61]
	v_mfma_f32_16x16x32_bf16 v[46:49], v[130:133], v[196:199], v[46:49]
	v_mfma_f32_16x16x32_bf16 v[42:45], v[138:141], v[196:199], v[42:45]
	v_mfma_f32_16x16x32_bf16 v[30:33], v[130:133], v[204:207], v[30:33]
	v_mfma_f32_16x16x32_bf16 v[26:29], v[138:141], v[204:207], v[26:29]
	v_mfma_f32_16x16x32_bf16 v[14:17], v[130:133], v[222:225], v[14:17]
	v_mfma_f32_16x16x32_bf16 v[10:13], v[138:141], v[222:225], v[10:13]
	v_mfma_f32_16x16x32_bf16 v[62:65], v[134:137], v[190:193], v[62:65]
	v_mfma_f32_16x16x32_bf16 v[58:61], v[154:157], v[190:193], v[58:61]
	v_mfma_f32_16x16x32_bf16 v[46:49], v[134:137], v[200:203], v[46:49]
	v_mfma_f32_16x16x32_bf16 v[42:45], v[154:157], v[200:203], v[42:45]
	v_mfma_f32_16x16x32_bf16 v[30:33], v[134:137], v[208:211], v[30:33]
	v_mfma_f32_16x16x32_bf16 v[26:29], v[154:157], v[208:211], v[26:29]
	v_mfma_f32_16x16x32_bf16 v[14:17], v[134:137], v[226:229], v[14:17]
	v_mfma_f32_16x16x32_bf16 v[10:13], v[154:157], v[226:229], v[10:13]
	v_mfma_f32_16x16x32_bf16 v[54:57], v[158:161], v[186:189], v[54:57]
	v_mfma_f32_16x16x32_bf16 v[50:53], v[178:181], v[186:189], v[50:53]
	v_mfma_f32_16x16x32_bf16 v[38:41], v[158:161], v[196:199], v[38:41]
	v_mfma_f32_16x16x32_bf16 v[34:37], v[178:181], v[196:199], v[34:37]
	v_mfma_f32_16x16x32_bf16 v[22:25], v[158:161], v[204:207], v[22:25]
	v_mfma_f32_16x16x32_bf16 v[18:21], v[178:181], v[204:207], v[18:21]
	v_mfma_f32_16x16x32_bf16 v[6:9], v[158:161], v[222:225], v[6:9]
	v_mfma_f32_16x16x32_bf16 v[2:5], v[178:181], v[222:225], v[2:5]
	v_mfma_f32_16x16x32_bf16 v[54:57], v[162:165], v[190:193], v[54:57]
	v_mfma_f32_16x16x32_bf16 v[50:53], v[182:185], v[190:193], v[50:53]
	v_mfma_f32_16x16x32_bf16 v[38:41], v[162:165], v[200:203], v[38:41]
	v_mfma_f32_16x16x32_bf16 v[34:37], v[182:185], v[200:203], v[34:37]
	v_mfma_f32_16x16x32_bf16 v[22:25], v[162:165], v[208:211], v[22:25]
	v_mfma_f32_16x16x32_bf16 v[18:21], v[182:185], v[208:211], v[18:21]
	v_mfma_f32_16x16x32_bf16 v[6:9], v[162:165], v[226:229], v[6:9]
	v_mfma_f32_16x16x32_bf16 v[2:5], v[182:185], v[226:229], v[2:5]
	s_barrier
	s_setprio 0
	s_add_i32 s52, s52, 2
	s_add_u32 s36, s36, 0x100
	s_addc_u32 s37, s37, 0
	s_add_u32 s50, s50, 0x100
	s_addc_u32 s51, s51, 0
	s_cmp_gt_u32 s52, 13
	s_cbranch_scc0 .LBB0_1231
	s_and_b64 vcc, exec, s[8:9]
	s_cbranch_vccz .LBB0_1234
	s_barrier

; #define PG8_STAGE(bufoff, gbase, voff) do { _Pragma("unroll") for (int _i = 0; _i < 2; ++_i) \
;         __builtin_amdgcn_global_load_lds((const unsigned*)((const char*)(gbase) + (voff)[_i]), (PG8_LAS unsigned*)(lds + (bufoff) + ldsw + _i * 8192), 16, 0, 0); } while (0)
; #define PG8_LDA(dst, b, h) do { _Pragma("unroll") for (int m = 0; m < 4; ++m) _Pragma("unroll") for (int k = 0; k < 2; ++k) dst[m][k] = *(const PG8_LAS bf16x8*)(lds + PG8_SA(b, h) + aoff + m * 2048 + k * 1024); } while (0)
; #define PG8_LDB(dst, b, h) do { _Pragma("unroll") for (int n = 0; n < 2; ++n) _Pragma("unroll") for (int k = 0; k < 2; ++k) dst[n][k] = *(const PG8_LAS bf16x8*)(lds + PG8_SB(b, h) + boff + n * 2048 + k * 1024); } while (0)
; #define PG8_MMA(ai, bj, At, Bt) do { __builtin_amdgcn_s_setprio(1); _Pragma("unroll") for (int m = 0; m < 4; ++m) _Pragma("unroll") for (int n = 0; n < 2; ++n) _Pragma("unroll") for (int k = 0; k < 2; ++k) \
;         acc[ai][bj][m][n] = __builtin_amdgcn_mfma_f32_16x16x32_bf16(Bt[n][k], At[m][k], acc[ai][bj][m][n], 0, 0, 0); __builtin_amdgcn_s_setprio(0); } while (0)
; #define PG8_WAIT_V(n) asm volatile("s_waitcnt vmcnt(" #n ")" ::: "memory")
; #define PG8_WAIT_L(n) asm volatile("s_waitcnt lgkmcnt(" #n ")" ::: "memory")
; #define PG8_BAR __builtin_amdgcn_s_barrier()
; #define PG8_SCHED __builtin_amdgcn_sched_barrier(0)
; template <class Epi, class Sched, bool ALIGN_EPI = false, bool SP2 = false>
; __device__ __forceinline__ void gemm_phase(PG8_LAS unsigned char* lds, const Gemm g, const Sched& S, const Epi& E, int wv) {
;     ...
;             const bool last = (t == nt - 2);
;             const char* a1 = cA + (size_t)(t + 1) * kstep;
;             const char* a2 = last ? nA : cA + (size_t)(t + 2) * kstep; const char* b2 = last ? nB : cB + (size_t)(t + 2) * kstep;
;             const char* a3 = a2 + kstep; const char* b3 = b2 + kstep;
;             if (last && has_next) S.a_ready(nxt);
;             if constexpr (SP2) {
;             PG8_LDB(B0, 0, 0); PG8_LDB(B1, 0, 1); PG8_SCHED; PG8_LDA(At, 0, 0); PG8_STAGE(PG8_SA(1, 1), a1 + hstepA, voffA);
;             PG8_WAIT_V(8); PG8_WAIT_L(0); PG8_BAR; PG8_MMA(0, 0, At, B0); PG8_MMA(0, 1, At, B1); PG8_BAR; PG8_SCHED;
;             PG8_LDA(At, 0, 1); PG8_STAGE(PG8_SB(0, 0), b2, voffB); PG8_STAGE(PG8_SB(0, 1), b2 + hstep, voffB); PG8_STAGE(PG8_SA(0, 0), a2, voffA);
.LBB0_1299:
	s_add_u32 s25, s28, 0xfff00080
	s_addc_u32 s30, s29, -1
	s_add_i32 s58, 0, 0x10000
	s_cmp_eq_u32 s57, 60
	s_cselect_b32 s45, s16, s30
	s_cselect_b32 s44, s17, s25
	s_cselect_b32 s31, s37, s56
	s_cselect_b32 s30, s39, s55
	s_add_i32 s25, 0, 0x14000
	v_add_u32_e32 v142, s58, v189
	v_add_u32_e32 v170, s25, v189
	ds_read_b128 v[130:133], v142
	ds_read_b128 v[134:137], v142 offset:1024
	ds_read_b128 v[138:141], v142 offset:2048
	ds_read_b128 v[142:145], v142 offset:3072
	ds_read_b128 v[146:149], v170
	ds_read_b128 v[150:153], v170 offset:1024
	ds_read_b128 v[154:157], v170 offset:2048
	ds_read_b128 v[170:173], v170 offset:3072
	v_lshl_add_u64 v[186:187], s[28:29], 0, v[166:167]
	s_add_i32 m0, s46, 0xc000
	ds_read_b128 v[174:177], v191
	ds_read_b128 v[178:181], v191 offset:1024
	ds_read_b128 v[182:185], v191 offset:2048
	ds_read_b128 v[196:199], v191 offset:3072
	ds_read_b128 v[200:203], v191 offset:4096
	ds_read_b128 v[204:207], v191 offset:5120
	ds_read_b128 v[208:211], v191 offset:6144
	ds_read_b128 v[222:225], v191 offset:7168
	global_load_lds_dwordx4 v[186:187], off
	v_lshl_add_u64 v[186:187], s[28:29], 0, v[168:169]
	s_add_i32 m0, s46, 0xe000
	s_nop 0
	global_load_lds_dwordx4 v[186:187], off
	s_waitcnt vmcnt(8)
	s_waitcnt lgkmcnt(0)
	s_setprio 1
	s_barrier
	v_mfma_f32_16x16x32_bf16 v[126:129], v[130:133], v[174:177], v[126:129]
	v_mfma_f32_16x16x32_bf16 v[122:125], v[138:141], v[174:177], v[122:125]
	v_mfma_f32_16x16x32_bf16 v[110:113], v[130:133], v[182:185], v[110:113]
	v_mfma_f32_16x16x32_bf16 v[106:109], v[138:141], v[182:185], v[106:109]
	v_mfma_f32_16x16x32_bf16 v[94:97], v[130:133], v[200:203], v[94:97]
	v_mfma_f32_16x16x32_bf16 v[90:93], v[138:141], v[200:203], v[90:93]
	v_mfma_f32_16x16x32_bf16 v[78:81], v[130:133], v[208:211], v[78:81]
	v_mfma_f32_16x16x32_bf16 v[74:77], v[138:141], v[208:211], v[74:77]
	v_mfma_f32_16x16x32_bf16 v[126:129], v[134:137], v[178:181], v[126:129]
	v_mfma_f32_16x16x32_bf16 v[122:125], v[142:145], v[178:181], v[122:125]
	v_mfma_f32_16x16x32_bf16 v[110:113], v[134:137], v[196:199], v[110:113]
	v_mfma_f32_16x16x32_bf16 v[106:109], v[142:145], v[196:199], v[106:109]
	v_mfma_f32_16x16x32_bf16 v[94:97], v[134:137], v[204:207], v[94:97]
	v_mfma_f32_16x16x32_bf16 v[90:93], v[142:145], v[204:207], v[90:93]
	v_mfma_f32_16x16x32_bf16 v[78:81], v[134:137], v[222:225], v[78:81]
	v_mfma_f32_16x16x32_bf16 v[74:77], v[142:145], v[222:225], v[74:77]
	v_mfma_f32_16x16x32_bf16 v[118:121], v[146:149], v[174:177], v[118:121]
	v_mfma_f32_16x16x32_bf16 v[114:117], v[154:157], v[174:177], v[114:117]
	v_mfma_f32_16x16x32_bf16 v[102:105], v[146:149], v[182:185], v[102:105]
	v_mfma_f32_16x16x32_bf16 v[98:101], v[154:157], v[182:185], v[98:101]
	v_mfma_f32_16x16x32_bf16 v[86:89], v[146:149], v[200:203], v[86:89]
	v_mfma_f32_16x16x32_bf16 v[82:85], v[154:157], v[200:203], v[82:85]
	v_mfma_f32_16x16x32_bf16 v[70:73], v[146:149], v[208:211], v[70:73]
	v_mfma_f32_16x16x32_bf16 v[66:69], v[154:157], v[208:211], v[66:69]
	v_mfma_f32_16x16x32_bf16 v[118:121], v[150:153], v[178:181], v[118:121]
	v_mfma_f32_16x16x32_bf16 v[114:117], v[170:173], v[178:181], v[114:117]
	v_mfma_f32_16x16x32_bf16 v[102:105], v[150:153], v[196:199], v[102:105]
	v_mfma_f32_16x16x32_bf16 v[98:101], v[170:173], v[196:199], v[98:101]
	v_mfma_f32_16x16x32_bf16 v[86:89], v[150:153], v[204:207], v[86:89]
	v_mfma_f32_16x16x32_bf16 v[82:85], v[170:173], v[204:207], v[82:85]
	v_mfma_f32_16x16x32_bf16 v[70:73], v[150:153], v[222:225], v[70:73]
	v_mfma_f32_16x16x32_bf16 v[66:69], v[170:173], v[222:225], v[66:69]
	s_barrier
	s_setprio 0
	s_add_i32 s58, s58, s26
	v_lshl_add_u64 v[186:187], s[30:31], 0, v[0:1]
	s_mov_b32 m0, s58
	ds_read_b128 v[174:177], v191 offset:16384
	ds_read_b128 v[178:181], v191 offset:17408
	ds_read_b128 v[182:185], v191 offset:18432
	ds_read_b128 v[196:199], v191 offset:19456
	ds_read_b128 v[200:203], v191 offset:20480
	ds_read_b128 v[204:207], v191 offset:21504
	ds_read_b128 v[208:211], v191 offset:22528
	ds_read_b128 v[222:225], v191 offset:23552
	global_load_lds_dwordx4 v[186:187], off
	s_add_i32 m0, s58, 0x2000
	s_add_u32 s58, s30, 0x100000
	v_lshl_add_u64 v[192:193], s[30:31], 0, v[158:159]
	s_addc_u32 s59, s31, 0
	s_add_i32 s25, s25, s26
	global_load_lds_dwordx4 v[192:193], off
	v_lshl_add_u64 v[212:213], s[58:59], 0, v[0:1]
	s_mov_b32 m0, s25
	v_lshl_add_u64 v[226:227], s[44:45], 0, v[160:161]
	global_load_lds_dwordx4 v[212:213], off
	v_lshl_add_u64 v[212:213], s[58:59], 0, v[158:159]
	s_add_i32 m0, s25, 0x2000
	s_nop 0
	global_load_lds_dwordx4 v[212:213], off
	v_lshl_add_u64 v[212:213], s[44:45], 0, v[162:163]
	s_mov_b32 m0, s46
	s_nop 0
	global_load_lds_dwordx4 v[212:213], off
	s_mov_b32 m0, s47
	s_nop 0
	global_load_lds_dwordx4 v[226:227], off
	s_waitcnt vmcnt(8)
	s_waitcnt lgkmcnt(0)
	s_setprio 1
	s_barrier
; #define PG8_STAGE(bufoff, gbase, voff) do { _Pragma("unroll") for (int _i = 0; _i < 2; ++_i) \
;         __builtin_amdgcn_global_load_lds((const unsigned*)((const char*)(gbase) + (voff)[_i]), (PG8_LAS unsigned*)(lds + (bufoff) + ldsw + _i * 8192), 16, 0, 0); } while (0)
; #define PG8_LDA(dst, b, h) do { _Pragma("unroll") for (int m = 0; m < 4; ++m) _Pragma("unroll") for (int k = 0; k < 2; ++k) dst[m][k] = *(const PG8_LAS bf16x8*)(lds + PG8_SA(b, h) + aoff + m * 2048 + k * 1024); } while (0)
; #define PG8_LDB(dst, b, h) do { _Pragma("unroll") for (int n = 0; n < 2; ++n) _Pragma("unroll") for (int k = 0; k < 2; ++k) dst[n][k] = *(const PG8_LAS bf16x8*)(lds + PG8_SB(b, h) + boff + n * 2048 + k * 1024); } while (0)
; #define PG8_MMA(ai, bj, At, Bt) do { __builtin_amdgcn_s_setprio(1); _Pragma("unroll") for (int m = 0; m < 4; ++m) _Pragma("unroll") for (int n = 0; n < 2; ++n) _Pragma("unroll") for (int k = 0; k < 2; ++k) \
;         acc[ai][bj][m][n] = __builtin_amdgcn_mfma_f32_16x16x32_bf16(Bt[n][k], At[m][k], acc[ai][bj][m][n], 0, 0, 0); __builtin_amdgcn_s_setprio(0); } while (0)
; #define PG8_WAIT_V(n) asm volatile("s_waitcnt vmcnt(" #n ")" ::: "memory")
; #define PG8_WAIT_L(n) asm volatile("s_waitcnt lgkmcnt(" #n ")" ::: "memory")
; #define PG8_BAR __builtin_amdgcn_s_barrier()
; #define PG8_SCHED __builtin_amdgcn_sched_barrier(0)
; template <class Epi, class Sched, bool ALIGN_EPI = false, bool SP2 = false>
; __device__ __forceinline__ void gemm_phase(PG8_LAS unsigned char* lds, const Gemm g, const Sched& S, const Epi& E, int wv) {
;     ...
;             PG8_WAIT_V(8); PG8_WAIT_L(0); PG8_BAR; PG8_MMA(1, 0, At, B0); PG8_MMA(1, 1, At, B1); PG8_BAR; PG8_SCHED;
;             PG8_LDB(B0, 1, 0); PG8_LDB(B1, 1, 1); PG8_SCHED; PG8_LDA(At, 1, 0); PG8_STAGE(PG8_SA(0, 1), a2 + hstepA, voffA);
;             PG8_WAIT_V(8); PG8_WAIT_L(0); PG8_BAR; PG8_MMA(0, 0, At, B0); PG8_MMA(0, 1, At, B1); PG8_BAR; PG8_SCHED;
	v_mfma_f32_16x16x32_bf16 v[62:65], v[130:133], v[174:177], v[62:65]
	v_mfma_f32_16x16x32_bf16 v[58:61], v[138:141], v[174:177], v[58:61]
	v_mfma_f32_16x16x32_bf16 v[46:49], v[130:133], v[182:185], v[46:49]
	v_mfma_f32_16x16x32_bf16 v[42:45], v[138:141], v[182:185], v[42:45]
	v_mfma_f32_16x16x32_bf16 v[30:33], v[130:133], v[200:203], v[30:33]
	v_mfma_f32_16x16x32_bf16 v[26:29], v[138:141], v[200:203], v[26:29]
	v_mfma_f32_16x16x32_bf16 v[14:17], v[130:133], v[208:211], v[14:17]
	v_mfma_f32_16x16x32_bf16 v[10:13], v[138:141], v[208:211], v[10:13]
	v_mfma_f32_16x16x32_bf16 v[62:65], v[134:137], v[178:181], v[62:65]
	v_mfma_f32_16x16x32_bf16 v[58:61], v[142:145], v[178:181], v[58:61]
	v_mfma_f32_16x16x32_bf16 v[46:49], v[134:137], v[196:199], v[46:49]
	v_mfma_f32_16x16x32_bf16 v[42:45], v[142:145], v[196:199], v[42:45]
	v_mfma_f32_16x16x32_bf16 v[30:33], v[134:137], v[204:207], v[30:33]
	v_mfma_f32_16x16x32_bf16 v[26:29], v[142:145], v[204:207], v[26:29]
	v_mfma_f32_16x16x32_bf16 v[14:17], v[134:137], v[222:225], v[14:17]
	v_mfma_f32_16x16x32_bf16 v[10:13], v[142:145], v[222:225], v[10:13]
	v_mfma_f32_16x16x32_bf16 v[54:57], v[146:149], v[174:177], v[54:57]
	v_mfma_f32_16x16x32_bf16 v[50:53], v[154:157], v[174:177], v[50:53]
	v_mfma_f32_16x16x32_bf16 v[38:41], v[146:149], v[182:185], v[38:41]
	v_mfma_f32_16x16x32_bf16 v[34:37], v[154:157], v[182:185], v[34:37]
	v_mfma_f32_16x16x32_bf16 v[22:25], v[146:149], v[200:203], v[22:25]
	v_mfma_f32_16x16x32_bf16 v[18:21], v[154:157], v[200:203], v[18:21]
	v_mfma_f32_16x16x32_bf16 v[6:9], v[146:149], v[208:211], v[6:9]
	v_mfma_f32_16x16x32_bf16 v[2:5], v[154:157], v[208:211], v[2:5]
	v_mfma_f32_16x16x32_bf16 v[54:57], v[150:153], v[178:181], v[54:57]
	v_mfma_f32_16x16x32_bf16 v[50:53], v[170:173], v[178:181], v[50:53]
	v_mfma_f32_16x16x32_bf16 v[38:41], v[150:153], v[196:199], v[38:41]
	v_mfma_f32_16x16x32_bf16 v[34:37], v[170:173], v[196:199], v[34:37]
	v_mfma_f32_16x16x32_bf16 v[22:25], v[150:153], v[204:207], v[22:25]
	v_mfma_f32_16x16x32_bf16 v[18:21], v[170:173], v[204:207], v[18:21]
	v_mfma_f32_16x16x32_bf16 v[6:9], v[150:153], v[222:225], v[6:9]
	v_mfma_f32_16x16x32_bf16 v[2:5], v[170:173], v[222:225], v[2:5]
	s_barrier
	s_setprio 0
	s_add_i32 s25, 0, 0x18000
	s_add_i32 s58, 0, 0x1c000
	v_add_u32_e32 v142, s25, v189
	v_add_u32_e32 v170, s58, v189
	ds_read_b128 v[130:133], v142
	ds_read_b128 v[134:137], v142 offset:1024
	ds_read_b128 v[138:141], v142 offset:2048
	ds_read_b128 v[142:145], v142 offset:3072
	ds_read_b128 v[146:149], v170
	ds_read_b128 v[150:153], v170 offset:1024
	ds_read_b128 v[154:157], v170 offset:2048
	ds_read_b128 v[170:173], v170 offset:3072
	s_add_u32 s44, s44, 0x100000
	s_addc_u32 s45, s45, 0
	s_mov_b32 m0, s48
	v_lshl_add_u64 v[228:229], s[44:45], 0, v[162:163]
	ds_read_b128 v[174:177], v191 offset:32768
	ds_read_b128 v[178:181], v191 offset:33792
	ds_read_b128 v[182:185], v191 offset:34816
	ds_read_b128 v[196:199], v191 offset:35840
	ds_read_b128 v[200:203], v191 offset:36864
	ds_read_b128 v[204:207], v191 offset:37888
	ds_read_b128 v[208:211], v191 offset:38912
	ds_read_b128 v[222:225], v191 offset:39936
	global_load_lds_dwordx4 v[228:229], off
	v_lshl_add_u64 v[228:229], s[44:45], 0, v[160:161]
	s_mov_b32 m0, s49
	s_nop 0
	global_load_lds_dwordx4 v[228:229], off
	s_waitcnt vmcnt(8)
	s_waitcnt lgkmcnt(0)
	s_setprio 1
	s_barrier
	v_mfma_f32_16x16x32_bf16 v[126:129], v[130:133], v[174:177], v[126:129]
	v_mfma_f32_16x16x32_bf16 v[122:125], v[138:141], v[174:177], v[122:125]
	v_mfma_f32_16x16x32_bf16 v[110:113], v[130:133], v[182:185], v[110:113]
	v_mfma_f32_16x16x32_bf16 v[106:109], v[138:141], v[182:185], v[106:109]
	v_mfma_f32_16x16x32_bf16 v[94:97], v[130:133], v[200:203], v[94:97]
	v_mfma_f32_16x16x32_bf16 v[90:93], v[138:141], v[200:203], v[90:93]
	v_mfma_f32_16x16x32_bf16 v[78:81], v[130:133], v[208:211], v[78:81]
	v_mfma_f32_16x16x32_bf16 v[74:77], v[138:141], v[208:211], v[74:77]
	v_mfma_f32_16x16x32_bf16 v[126:129], v[134:137], v[178:181], v[126:129]
	v_mfma_f32_16x16x32_bf16 v[122:125], v[142:145], v[178:181], v[122:125]
	v_mfma_f32_16x16x32_bf16 v[110:113], v[134:137], v[196:199], v[110:113]
	v_mfma_f32_16x16x32_bf16 v[106:109], v[142:145], v[196:199], v[106:109]
	v_mfma_f32_16x16x32_bf16 v[94:97], v[134:137], v[204:207], v[94:97]
	v_mfma_f32_16x16x32_bf16 v[90:93], v[142:145], v[204:207], v[90:93]
	v_mfma_f32_16x16x32_bf16 v[78:81], v[134:137], v[222:225], v[78:81]
	v_mfma_f32_16x16x32_bf16 v[74:77], v[142:145], v[222:225], v[74:77]
	v_mfma_f32_16x16x32_bf16 v[118:121], v[146:149], v[174:177], v[118:121]
	v_mfma_f32_16x16x32_bf16 v[114:117], v[154:157], v[174:177], v[114:117]
	v_mfma_f32_16x16x32_bf16 v[102:105], v[146:149], v[182:185], v[102:105]
	v_mfma_f32_16x16x32_bf16 v[98:101], v[154:157], v[182:185], v[98:101]
	v_mfma_f32_16x16x32_bf16 v[86:89], v[146:149], v[200:203], v[86:89]
	v_mfma_f32_16x16x32_bf16 v[82:85], v[154:157], v[200:203], v[82:85]
	v_mfma_f32_16x16x32_bf16 v[70:73], v[146:149], v[208:211], v[70:73]
	v_mfma_f32_16x16x32_bf16 v[66:69], v[154:157], v[208:211], v[66:69]
	v_mfma_f32_16x16x32_bf16 v[118:121], v[150:153], v[178:181], v[118:121]
	v_mfma_f32_16x16x32_bf16 v[114:117], v[170:173], v[178:181], v[114:117]
	v_mfma_f32_16x16x32_bf16 v[102:105], v[150:153], v[196:199], v[102:105]
	v_mfma_f32_16x16x32_bf16 v[98:101], v[170:173], v[196:199], v[98:101]
	v_mfma_f32_16x16x32_bf16 v[86:89], v[150:153], v[204:207], v[86:89]
	v_mfma_f32_16x16x32_bf16 v[82:85], v[170:173], v[204:207], v[82:85]
	v_mfma_f32_16x16x32_bf16 v[70:73], v[150:153], v[222:225], v[70:73]
	v_mfma_f32_16x16x32_bf16 v[66:69], v[170:173], v[222:225], v[66:69]
	s_barrier
; #define PG8_STAGE(bufoff, gbase, voff) do { _Pragma("unroll") for (int _i = 0; _i < 2; ++_i) \
;         __builtin_amdgcn_global_load_lds((const unsigned*)((const char*)(gbase) + (voff)[_i]), (PG8_LAS unsigned*)(lds + (bufoff) + ldsw + _i * 8192), 16, 0, 0); } while (0)
; #define PG8_LDA(dst, b, h) do { _Pragma("unroll") for (int m = 0; m < 4; ++m) _Pragma("unroll") for (int k = 0; k < 2; ++k) dst[m][k] = *(const PG8_LAS bf16x8*)(lds + PG8_SA(b, h) + aoff + m * 2048 + k * 1024); } while (0)
; #define PG8_MMA(ai, bj, At, Bt) do { __builtin_amdgcn_s_setprio(1); _Pragma("unroll") for (int m = 0; m < 4; ++m) _Pragma("unroll") for (int n = 0; n < 2; ++n) _Pragma("unroll") for (int k = 0; k < 2; ++k) \
;         acc[ai][bj][m][n] = __builtin_amdgcn_mfma_f32_16x16x32_bf16(Bt[n][k], At[m][k], acc[ai][bj][m][n], 0, 0, 0); __builtin_amdgcn_s_setprio(0); } while (0)
; #define PG8_WAIT_V(n) asm volatile("s_waitcnt vmcnt(" #n ")" ::: "memory")
; #define PG8_WAIT_L(n) asm volatile("s_waitcnt lgkmcnt(" #n ")" ::: "memory")
; #define PG8_BAR __builtin_amdgcn_s_barrier()
; #define PG8_SCHED __builtin_amdgcn_sched_barrier(0)
; template <class Epi, class Sched, bool ALIGN_EPI = false, bool SP2 = false>
; __device__ __forceinline__ void gemm_phase(PG8_LAS unsigned char* lds, const Gemm g, const Sched& S, const Epi& E, int wv) {
;     ...
;             PG8_LDA(At, 1, 1); PG8_STAGE(PG8_SB(1, 0), b3, voffB); PG8_STAGE(PG8_SB(1, 1), b3 + hstep, voffB); PG8_STAGE(PG8_SA(1, 0), a3, voffA);
;             PG8_WAIT_V(8); PG8_WAIT_L(0); PG8_BAR; PG8_MMA(1, 0, At, B0); PG8_MMA(1, 1, At, B1); PG8_BAR; PG8_SCHED;
;     ...
;         if constexpr (ALIGN_EPI) { if (wr == 0) PG8_BAR; }
	s_setprio 0
	s_add_i32 s25, s25, s26
	v_lshl_add_u64 v[186:187], v[186:187], 0, s[14:15]
	s_mov_b32 m0, s25
	ds_read_b128 v[174:177], v191 offset:49152
	ds_read_b128 v[178:181], v191 offset:50176
	ds_read_b128 v[182:185], v191 offset:51200
	ds_read_b128 v[196:199], v191 offset:52224
	ds_read_b128 v[200:203], v191 offset:53248
	ds_read_b128 v[204:207], v191 offset:54272
	ds_read_b128 v[208:211], v191 offset:55296
	ds_read_b128 v[222:225], v191 offset:56320
	global_load_lds_dwordx4 v[186:187], off
	s_add_i32 m0, s25, 0x2000
	s_add_u32 s30, s30, 0x100080
	v_lshl_add_u64 v[186:187], v[192:193], 0, s[14:15]
	s_addc_u32 s31, s31, 0
	s_add_i32 s25, s58, s26
	global_load_lds_dwordx4 v[186:187], off
	v_lshl_add_u64 v[186:187], s[30:31], 0, v[0:1]
	s_mov_b32 m0, s25
	s_nop 0
	global_load_lds_dwordx4 v[186:187], off
	v_lshl_add_u64 v[186:187], s[30:31], 0, v[158:159]
	s_add_i32 m0, s25, 0x2000
	s_nop 0
	global_load_lds_dwordx4 v[186:187], off
	v_lshl_add_u64 v[186:187], v[212:213], 0, s[14:15]
	s_mov_b32 m0, s51
	s_nop 0
	global_load_lds_dwordx4 v[186:187], off
	v_lshl_add_u64 v[186:187], v[226:227], 0, s[14:15]
	s_mov_b32 m0, s52
	s_nop 0
	global_load_lds_dwordx4 v[186:187], off
	s_waitcnt vmcnt(8)
	s_waitcnt lgkmcnt(0)
	s_setprio 1
	s_barrier
	v_mfma_f32_16x16x32_bf16 v[62:65], v[130:133], v[174:177], v[62:65]
	v_mfma_f32_16x16x32_bf16 v[58:61], v[138:141], v[174:177], v[58:61]
	v_mfma_f32_16x16x32_bf16 v[46:49], v[130:133], v[182:185], v[46:49]
	v_mfma_f32_16x16x32_bf16 v[42:45], v[138:141], v[182:185], v[42:45]
	v_mfma_f32_16x16x32_bf16 v[30:33], v[130:133], v[200:203], v[30:33]
	v_mfma_f32_16x16x32_bf16 v[26:29], v[138:141], v[200:203], v[26:29]
	v_mfma_f32_16x16x32_bf16 v[14:17], v[130:133], v[208:211], v[14:17]
	v_mfma_f32_16x16x32_bf16 v[10:13], v[138:141], v[208:211], v[10:13]
	v_mfma_f32_16x16x32_bf16 v[62:65], v[134:137], v[178:181], v[62:65]
	v_mfma_f32_16x16x32_bf16 v[58:61], v[142:145], v[178:181], v[58:61]
	v_mfma_f32_16x16x32_bf16 v[46:49], v[134:137], v[196:199], v[46:49]
	v_mfma_f32_16x16x32_bf16 v[42:45], v[142:145], v[196:199], v[42:45]
	v_mfma_f32_16x16x32_bf16 v[30:33], v[134:137], v[204:207], v[30:33]
	v_mfma_f32_16x16x32_bf16 v[26:29], v[142:145], v[204:207], v[26:29]
	v_mfma_f32_16x16x32_bf16 v[14:17], v[134:137], v[222:225], v[14:17]
	v_mfma_f32_16x16x32_bf16 v[10:13], v[142:145], v[222:225], v[10:13]
	v_mfma_f32_16x16x32_bf16 v[54:57], v[146:149], v[174:177], v[54:57]
	v_mfma_f32_16x16x32_bf16 v[50:53], v[154:157], v[174:177], v[50:53]
	v_mfma_f32_16x16x32_bf16 v[38:41], v[146:149], v[182:185], v[38:41]
	v_mfma_f32_16x16x32_bf16 v[34:37], v[154:157], v[182:185], v[34:37]
	v_mfma_f32_16x16x32_bf16 v[22:25], v[146:149], v[200:203], v[22:25]
	v_mfma_f32_16x16x32_bf16 v[18:21], v[154:157], v[200:203], v[18:21]
	v_mfma_f32_16x16x32_bf16 v[6:9], v[146:149], v[208:211], v[6:9]
	v_mfma_f32_16x16x32_bf16 v[2:5], v[154:157], v[208:211], v[2:5]
	v_mfma_f32_16x16x32_bf16 v[54:57], v[150:153], v[178:181], v[54:57]
	v_mfma_f32_16x16x32_bf16 v[50:53], v[170:173], v[178:181], v[50:53]
	v_mfma_f32_16x16x32_bf16 v[38:41], v[150:153], v[196:199], v[38:41]
	v_mfma_f32_16x16x32_bf16 v[34:37], v[170:173], v[196:199], v[34:37]
	v_mfma_f32_16x16x32_bf16 v[22:25], v[150:153], v[204:207], v[22:25]
	v_mfma_f32_16x16x32_bf16 v[18:21], v[170:173], v[204:207], v[18:21]
	v_mfma_f32_16x16x32_bf16 v[6:9], v[150:153], v[222:225], v[6:9]
	v_mfma_f32_16x16x32_bf16 v[2:5], v[170:173], v[222:225], v[2:5]
	s_barrier
	s_setprio 0
	s_add_i32 s57, s57, 2
	s_add_u32 s28, s28, 0x100
	s_addc_u32 s29, s29, 0
	s_add_u32 s55, s55, 0x100
	s_addc_u32 s56, s56, 0
	s_cmp_gt_u32 s57, 61
	s_cbranch_scc0 .LBB0_1299
	s_and_b64 vcc, exec, s[10:11]
	s_cbranch_vccz .LBB0_1302
	s_barrier
